# v25 plus 64-byte alignment of the five K-loop heads and removal of the s_setprio 0/1 pair between the two 16-MFMA groups of each block
# speedup vs baseline: 1.0042x; 1.0042x over previous
; #define PG8_STAGE(bufoff, gbase, voff) do { _Pragma("unroll") for (int _i = 0; _i < 2; ++_i) \
;         __builtin_amdgcn_global_load_lds((const unsigned*)((const char*)(gbase) + (voff)[_i]), (PG8_LAS unsigned*)(lds + (bufoff) + ldsw + _i * 8192), 16, 0, 0); } while (0)
; #define PG8_LDA(dst, b, h) do { _Pragma("unroll") for (int m = 0; m < 4; ++m) _Pragma("unroll") for (int k = 0; k < 2; ++k) dst[m][k] = *(const PG8_LAS bf16x8*)(lds + PG8_SA(b, h) + aoff + m * 2048 + k * 1024); } while (0)
; #define PG8_LDB(dst, b, h) do { _Pragma("unroll") for (int n = 0; n < 2; ++n) _Pragma("unroll") for (int k = 0; k < 2; ++k) dst[n][k] = *(const PG8_LAS bf16x8*)(lds + PG8_SB(b, h) + boff + n * 2048 + k * 1024); } while (0)
; #define PG8_WAIT_V(n) asm volatile("s_waitcnt vmcnt(" #n ")" ::: "memory")
; #define PG8_WAIT_L(n) asm volatile("s_waitcnt lgkmcnt(" #n ")" ::: "memory")
; #define PG8_BAR __builtin_amdgcn_s_barrier()
; #define PG8_SCHED __builtin_amdgcn_sched_barrier(0)
; template <class Epi, class Sched, bool ALIGN_EPI = false, bool SP2 = false>
; __device__ __forceinline__ void gemm_phase(PG8_LAS unsigned char* lds, const Gemm g, const Sched& S, const Epi& E) {
;     ...
;         const bool has_next = S.next(ui + 1, nxt);
;         const char* nA = has_next ? (const char*)g.A + (size_t)nxt.pm * tstep : cA; const char* nB = has_next ? (const char*)g.Bt + (size_t)nxt.pn * tstep : cB;
;         for (int t = 0; t < nt; t += 2) {
;             const bool last = (t == nt - 2);
;             const char* a1 = cA + (size_t)(t + 1) * kstep;
;             const char* a2 = last ? nA : cA + (size_t)(t + 2) * kstep; const char* b2 = last ? nB : cB + (size_t)(t + 2) * kstep;
;             const char* a3 = a2 + kstep; const char* b3 = b2 + kstep;
;             if (last && has_next) S.a_ready(nxt);
;             if constexpr (SP2) {
;             PG8_LDB(B0, 0, 0); PG8_LDB(B1, 0, 1); PG8_SCHED; PG8_LDA(At, 0, 0); PG8_STAGE(PG8_SA(1, 1), a1 + hstep, voffA);
;             PG8_WAIT_V(8); PG8_WAIT_L(0); PG8_BAR; PG8_MMA(0, 0, At, B0); PG8_MMA(0, 1, At, B1); PG8_BAR; PG8_SCHED;
;             PG8_LDA(At, 0, 1); PG8_STAGE(PG8_SB(0, 0), b2, voffB); PG8_STAGE(PG8_SB(0, 1), b2 + hstep, voffB); PG8_STAGE(PG8_SA(0, 0), a2, voffA);
;             PG8_WAIT_V(8); PG8_WAIT_L(0); PG8_BAR; PG8_MMA(1, 0, At, B0); PG8_MMA(1, 1, At, B1); PG8_BAR; PG8_SCHED;
.LBB0_127:
	s_ashr_i32 s47, s46, 31
	s_lshl_b64 s[50:51], s[46:47], 19
	s_add_u32 s50, s36, s50
	s_addc_u32 s51, s37, s51
	s_and_b64 s[54:55], s[2:3], exec
	s_cselect_b32 s47, s51, s59
	s_cselect_b32 s89, s50, s58
	s_ashr_i32 s41, s40, 31
	s_lshl_b64 s[54:55], s[40:41], 19
	s_add_u32 s54, s82, s54
	s_addc_u32 s55, s83, s55
	s_and_b64 s[62:63], s[2:3], exec
	s_cselect_b32 s41, s55, s61
	s_cselect_b32 s90, s54, s60
	s_add_u32 s58, s58, 0x40080
	s_addc_u32 s59, s59, 0
	s_add_u32 s91, s60, 0x100
	s_addc_u32 s92, s61, 0
	s_mov_b32 s93, -2
	ds_read_b128 v[160:163], v157
	ds_read_b128 v[164:167], v157 offset:1024
	ds_read_b128 v[168:171], v157 offset:2048
	ds_read_b128 v[172:175], v157 offset:3072
	ds_read_b128 v[176:179], v158
	ds_read_b128 v[180:183], v158 offset:1024
	ds_read_b128 v[184:187], v158 offset:2048
	ds_read_b128 v[188:191], v158 offset:3072
	s_add_u32 s19, s58, 0xfffc0080
	s_addc_u32 s60, s59, -1
	s_cmp_eq_u32 s93, 12
	s_cselect_b32 s63, s47, s60
	s_cselect_b32 s62, s89, s19
	s_cselect_b32 s61, s41, s92
	s_cselect_b32 s60, s90, s91
	v_lshl_add_u64 v[144:145], s[58:59], 0, v[136:137]
	s_add_i32 m0, s18, 0xc000
	ds_read_b128 v[192:195], v159
	ds_read_b128 v[196:199], v159 offset:1024
	ds_read_b128 v[200:203], v159 offset:2048
	ds_read_b128 v[208:211], v159 offset:3072
	ds_read_b128 v[212:215], v159 offset:4096
	ds_read_b128 v[216:219], v159 offset:5120
	ds_read_b128 v[220:223], v159 offset:6144
	ds_read_b128 v[224:227], v159 offset:7168
	global_load_lds_dwordx4 v[144:145], off
	v_lshl_add_u64 v[144:145], s[58:59], 0, v[138:139]
	s_add_i32 m0, s18, 0xe000
	s_nop 0
	global_load_lds_dwordx4 v[144:145], off
	s_waitcnt vmcnt(8)
	s_waitcnt lgkmcnt(0)
	s_barrier
	s_setprio 1
	s_waitcnt lgkmcnt(0)
	v_mfma_f32_16x16x32_bf16 v[124:127], v[160:163], v[192:195], 0
	v_mfma_f32_16x16x32_bf16 v[120:123], v[168:171], v[192:195], 0
	v_mfma_f32_16x16x32_bf16 v[112:115], v[160:163], v[200:203], 0
	v_mfma_f32_16x16x32_bf16 v[104:107], v[168:171], v[200:203], 0
	v_mfma_f32_16x16x32_bf16 v[96:99], v[160:163], v[212:215], 0
	v_mfma_f32_16x16x32_bf16 v[88:91], v[168:171], v[212:215], 0
	v_mfma_f32_16x16x32_bf16 v[80:83], v[160:163], v[220:223], 0
	v_mfma_f32_16x16x32_bf16 v[72:75], v[168:171], v[220:223], 0
	v_mfma_f32_16x16x32_bf16 v[124:127], v[164:167], v[196:199], v[124:127]
	v_mfma_f32_16x16x32_bf16 v[120:123], v[172:175], v[196:199], v[120:123]
	v_mfma_f32_16x16x32_bf16 v[112:115], v[164:167], v[208:211], v[112:115]
	v_mfma_f32_16x16x32_bf16 v[104:107], v[172:175], v[208:211], v[104:107]
	v_mfma_f32_16x16x32_bf16 v[96:99], v[164:167], v[216:219], v[96:99]
	v_mfma_f32_16x16x32_bf16 v[88:91], v[172:175], v[216:219], v[88:91]
	v_mfma_f32_16x16x32_bf16 v[80:83], v[164:167], v[224:227], v[80:83]
	v_mfma_f32_16x16x32_bf16 v[72:75], v[172:175], v[224:227], v[72:75]
	v_mfma_f32_16x16x32_bf16 v[116:119], v[176:179], v[192:195], 0
	v_mfma_f32_16x16x32_bf16 v[108:111], v[184:187], v[192:195], 0
	v_mfma_f32_16x16x32_bf16 v[100:103], v[176:179], v[200:203], 0
	v_mfma_f32_16x16x32_bf16 v[92:95], v[184:187], v[200:203], 0
	v_mfma_f32_16x16x32_bf16 v[84:87], v[176:179], v[212:215], 0
	v_mfma_f32_16x16x32_bf16 v[76:79], v[184:187], v[212:215], 0
	v_mfma_f32_16x16x32_bf16 v[68:71], v[176:179], v[220:223], 0
	v_mfma_f32_16x16x32_bf16 v[64:67], v[184:187], v[220:223], 0
	v_mfma_f32_16x16x32_bf16 v[116:119], v[180:183], v[196:199], v[116:119]
	v_mfma_f32_16x16x32_bf16 v[108:111], v[188:191], v[196:199], v[108:111]
	v_mfma_f32_16x16x32_bf16 v[100:103], v[180:183], v[208:211], v[100:103]
	v_mfma_f32_16x16x32_bf16 v[92:95], v[188:191], v[208:211], v[92:95]
	v_mfma_f32_16x16x32_bf16 v[84:87], v[180:183], v[216:219], v[84:87]
	v_mfma_f32_16x16x32_bf16 v[76:79], v[188:191], v[216:219], v[76:79]
	v_mfma_f32_16x16x32_bf16 v[68:71], v[180:183], v[224:227], v[68:71]
	v_mfma_f32_16x16x32_bf16 v[64:67], v[188:191], v[224:227], v[64:67]
	s_setprio 0
	s_barrier
	s_add_i32 s19, s75, s15
	v_lshl_add_u64 v[144:145], s[60:61], 0, v[130:131]
	s_mov_b32 m0, s19
	ds_read_b128 v[192:195], v159 offset:16384
	ds_read_b128 v[196:199], v159 offset:17408
	ds_read_b128 v[200:203], v159 offset:18432
	ds_read_b128 v[208:211], v159 offset:19456
	ds_read_b128 v[212:215], v159 offset:20480
	ds_read_b128 v[216:219], v159 offset:21504
	ds_read_b128 v[220:223], v159 offset:22528
	ds_read_b128 v[224:227], v159 offset:23552
	global_load_lds_dwordx4 v[144:145], off
	s_add_i32 m0, s19, 0x2000
	s_add_u32 s70, s60, 0x40000
	v_lshl_add_u64 v[204:205], s[60:61], 0, v[134:135]
	s_addc_u32 s71, s61, 0
	s_add_i32 s19, s84, s15
	global_load_lds_dwordx4 v[204:205], off
	v_lshl_add_u64 v[228:229], s[70:71], 0, v[130:131]
	s_mov_b32 m0, s19
	v_lshl_add_u64 v[230:231], s[62:63], 0, v[132:133]
	global_load_lds_dwordx4 v[228:229], off
	v_lshl_add_u64 v[228:229], s[70:71], 0, v[134:135]
	s_add_i32 m0, s19, 0x2000
	s_nop 0
	global_load_lds_dwordx4 v[228:229], off
	v_lshl_add_u64 v[228:229], s[62:63], 0, v[128:129]
	s_mov_b32 m0, s18
	s_nop 0
	global_load_lds_dwordx4 v[228:229], off
	s_mov_b32 m0, s23
	s_nop 0
	global_load_lds_dwordx4 v[230:231], off
	s_waitcnt vmcnt(8)
	s_waitcnt lgkmcnt(0)
	s_barrier
; #define PG8_STAGE(bufoff, gbase, voff) do { _Pragma("unroll") for (int _i = 0; _i < 2; ++_i) \
;         __builtin_amdgcn_global_load_lds((const unsigned*)((const char*)(gbase) + (voff)[_i]), (PG8_LAS unsigned*)(lds + (bufoff) + ldsw + _i * 8192), 16, 0, 0); } while (0)
; #define PG8_LDA(dst, b, h) do { _Pragma("unroll") for (int m = 0; m < 4; ++m) _Pragma("unroll") for (int k = 0; k < 2; ++k) dst[m][k] = *(const PG8_LAS bf16x8*)(lds + PG8_SA(b, h) + aoff + m * 2048 + k * 1024); } while (0)
; #define PG8_LDB(dst, b, h) do { _Pragma("unroll") for (int n = 0; n < 2; ++n) _Pragma("unroll") for (int k = 0; k < 2; ++k) dst[n][k] = *(const PG8_LAS bf16x8*)(lds + PG8_SB(b, h) + boff + n * 2048 + k * 1024); } while (0)
; #define PG8_MMA(ai, bj, At, Bt) do { __builtin_amdgcn_s_setprio(1); _Pragma("unroll") for (int m = 0; m < 4; ++m) _Pragma("unroll") for (int n = 0; n < 2; ++n) _Pragma("unroll") for (int k = 0; k < 2; ++k) \
;         acc[ai][bj][m][n] = __builtin_amdgcn_mfma_f32_16x16x32_bf16(Bt[n][k], At[m][k], acc[ai][bj][m][n], 0, 0, 0); __builtin_amdgcn_s_setprio(0); } while (0)
; #define PG8_WAIT_V(n) asm volatile("s_waitcnt vmcnt(" #n ")" ::: "memory")
; #define PG8_WAIT_L(n) asm volatile("s_waitcnt lgkmcnt(" #n ")" ::: "memory")
; #define PG8_BAR __builtin_amdgcn_s_barrier()
; #define PG8_SCHED __builtin_amdgcn_sched_barrier(0)
; template <class Epi, class Sched, bool ALIGN_EPI = false, bool SP2 = false>
; __device__ __forceinline__ void gemm_phase(PG8_LAS unsigned char* lds, const Gemm g, const Sched& S, const Epi& E) {
;     ...
;             PG8_WAIT_V(8); PG8_WAIT_L(0); PG8_BAR; PG8_MMA(1, 0, At, B0); PG8_MMA(1, 1, At, B1); PG8_BAR; PG8_SCHED;
;             PG8_LDB(B0, 1, 0); PG8_LDB(B1, 1, 1); PG8_SCHED; PG8_LDA(At, 1, 0); PG8_STAGE(PG8_SA(0, 1), a2 + hstep, voffA);
;             PG8_WAIT_V(8); PG8_WAIT_L(0); PG8_BAR; PG8_MMA(0, 0, At, B0); PG8_MMA(0, 1, At, B1); PG8_BAR; PG8_SCHED;
	s_setprio 1
	s_waitcnt lgkmcnt(0)
	v_mfma_f32_16x16x32_bf16 v[60:63], v[160:163], v[192:195], 0
	v_mfma_f32_16x16x32_bf16 v[56:59], v[168:171], v[192:195], 0
	v_mfma_f32_16x16x32_bf16 v[48:51], v[160:163], v[200:203], 0
	v_mfma_f32_16x16x32_bf16 v[40:43], v[168:171], v[200:203], 0
	v_mfma_f32_16x16x32_bf16 v[32:35], v[160:163], v[212:215], 0
	v_mfma_f32_16x16x32_bf16 v[24:27], v[168:171], v[212:215], 0
	v_mfma_f32_16x16x32_bf16 v[16:19], v[160:163], v[220:223], 0
	v_mfma_f32_16x16x32_bf16 v[8:11], v[168:171], v[220:223], 0
	v_mfma_f32_16x16x32_bf16 v[60:63], v[164:167], v[196:199], v[60:63]
	v_mfma_f32_16x16x32_bf16 v[56:59], v[172:175], v[196:199], v[56:59]
	v_mfma_f32_16x16x32_bf16 v[48:51], v[164:167], v[208:211], v[48:51]
	v_mfma_f32_16x16x32_bf16 v[40:43], v[172:175], v[208:211], v[40:43]
	v_mfma_f32_16x16x32_bf16 v[32:35], v[164:167], v[216:219], v[32:35]
	v_mfma_f32_16x16x32_bf16 v[24:27], v[172:175], v[216:219], v[24:27]
	v_mfma_f32_16x16x32_bf16 v[16:19], v[164:167], v[224:227], v[16:19]
	v_mfma_f32_16x16x32_bf16 v[8:11], v[172:175], v[224:227], v[8:11]
	v_mfma_f32_16x16x32_bf16 v[52:55], v[176:179], v[192:195], 0
	v_mfma_f32_16x16x32_bf16 v[44:47], v[184:187], v[192:195], 0
	v_mfma_f32_16x16x32_bf16 v[36:39], v[176:179], v[200:203], 0
	v_mfma_f32_16x16x32_bf16 v[28:31], v[184:187], v[200:203], 0
	v_mfma_f32_16x16x32_bf16 v[20:23], v[176:179], v[212:215], 0
	v_mfma_f32_16x16x32_bf16 v[12:15], v[184:187], v[212:215], 0
	v_mfma_f32_16x16x32_bf16 v[4:7], v[176:179], v[220:223], 0
	v_mfma_f32_16x16x32_bf16 v[0:3], v[184:187], v[220:223], 0
	v_mfma_f32_16x16x32_bf16 v[52:55], v[180:183], v[196:199], v[52:55]
	v_mfma_f32_16x16x32_bf16 v[44:47], v[188:191], v[196:199], v[44:47]
	v_mfma_f32_16x16x32_bf16 v[36:39], v[180:183], v[208:211], v[36:39]
	v_mfma_f32_16x16x32_bf16 v[28:31], v[188:191], v[208:211], v[28:31]
	v_mfma_f32_16x16x32_bf16 v[20:23], v[180:183], v[216:219], v[20:23]
	v_mfma_f32_16x16x32_bf16 v[12:15], v[188:191], v[216:219], v[12:15]
	v_mfma_f32_16x16x32_bf16 v[4:7], v[180:183], v[224:227], v[4:7]
	v_mfma_f32_16x16x32_bf16 v[0:3], v[188:191], v[224:227], v[0:3]
	s_setprio 0
	s_barrier
	s_add_i32 s19, 0, 0x18000
	s_add_i32 s70, 0, 0x1c000
	v_add_u32_e32 v172, s19, v155
	v_add_u32_e32 v188, s70, v155
	ds_read_b128 v[160:163], v172
	ds_read_b128 v[164:167], v172 offset:1024
	ds_read_b128 v[168:171], v172 offset:2048
	ds_read_b128 v[172:175], v172 offset:3072
	ds_read_b128 v[176:179], v188
	ds_read_b128 v[180:183], v188 offset:1024
	ds_read_b128 v[184:187], v188 offset:2048
	ds_read_b128 v[188:191], v188 offset:3072
	s_add_u32 s62, s62, 0x40000
	s_addc_u32 s63, s63, 0
	s_mov_b32 m0, s33
	v_lshl_add_u64 v[232:233], s[62:63], 0, v[128:129]
	ds_read_b128 v[192:195], v159 offset:32768
	ds_read_b128 v[196:199], v159 offset:33792
	ds_read_b128 v[200:203], v159 offset:34816
	ds_read_b128 v[208:211], v159 offset:35840
	ds_read_b128 v[212:215], v159 offset:36864
	ds_read_b128 v[216:219], v159 offset:37888
	ds_read_b128 v[220:223], v159 offset:38912
	ds_read_b128 v[224:227], v159 offset:39936
	global_load_lds_dwordx4 v[232:233], off
	v_lshl_add_u64 v[232:233], s[62:63], 0, v[132:133]
	s_mov_b32 m0, s35
	s_nop 0
	global_load_lds_dwordx4 v[232:233], off
	s_waitcnt vmcnt(8)
	s_waitcnt lgkmcnt(0)
	s_barrier
	s_setprio 1
	s_waitcnt lgkmcnt(0)
	v_mfma_f32_16x16x32_bf16 v[124:127], v[160:163], v[192:195], v[124:127]
	v_mfma_f32_16x16x32_bf16 v[120:123], v[168:171], v[192:195], v[120:123]
	v_mfma_f32_16x16x32_bf16 v[112:115], v[160:163], v[200:203], v[112:115]
	v_mfma_f32_16x16x32_bf16 v[104:107], v[168:171], v[200:203], v[104:107]
	v_mfma_f32_16x16x32_bf16 v[96:99], v[160:163], v[212:215], v[96:99]
	v_mfma_f32_16x16x32_bf16 v[88:91], v[168:171], v[212:215], v[88:91]
	v_mfma_f32_16x16x32_bf16 v[80:83], v[160:163], v[220:223], v[80:83]
	v_mfma_f32_16x16x32_bf16 v[72:75], v[168:171], v[220:223], v[72:75]
	v_mfma_f32_16x16x32_bf16 v[124:127], v[164:167], v[196:199], v[124:127]
	v_mfma_f32_16x16x32_bf16 v[120:123], v[172:175], v[196:199], v[120:123]
	v_mfma_f32_16x16x32_bf16 v[112:115], v[164:167], v[208:211], v[112:115]
	v_mfma_f32_16x16x32_bf16 v[104:107], v[172:175], v[208:211], v[104:107]
	v_mfma_f32_16x16x32_bf16 v[96:99], v[164:167], v[216:219], v[96:99]
	v_mfma_f32_16x16x32_bf16 v[88:91], v[172:175], v[216:219], v[88:91]
	v_mfma_f32_16x16x32_bf16 v[80:83], v[164:167], v[224:227], v[80:83]
	v_mfma_f32_16x16x32_bf16 v[72:75], v[172:175], v[224:227], v[72:75]
	v_mfma_f32_16x16x32_bf16 v[116:119], v[176:179], v[192:195], v[116:119]
	v_mfma_f32_16x16x32_bf16 v[108:111], v[184:187], v[192:195], v[108:111]
	v_mfma_f32_16x16x32_bf16 v[100:103], v[176:179], v[200:203], v[100:103]
	v_mfma_f32_16x16x32_bf16 v[92:95], v[184:187], v[200:203], v[92:95]
	v_mfma_f32_16x16x32_bf16 v[84:87], v[176:179], v[212:215], v[84:87]
	v_mfma_f32_16x16x32_bf16 v[76:79], v[184:187], v[212:215], v[76:79]
	v_mfma_f32_16x16x32_bf16 v[68:71], v[176:179], v[220:223], v[68:71]
	v_mfma_f32_16x16x32_bf16 v[64:67], v[184:187], v[220:223], v[64:67]
	v_mfma_f32_16x16x32_bf16 v[116:119], v[180:183], v[196:199], v[116:119]
	v_mfma_f32_16x16x32_bf16 v[108:111], v[188:191], v[196:199], v[108:111]
	v_mfma_f32_16x16x32_bf16 v[100:103], v[180:183], v[208:211], v[100:103]
	v_mfma_f32_16x16x32_bf16 v[92:95], v[188:191], v[208:211], v[92:95]
	v_mfma_f32_16x16x32_bf16 v[84:87], v[180:183], v[216:219], v[84:87]
	v_mfma_f32_16x16x32_bf16 v[76:79], v[188:191], v[216:219], v[76:79]
	v_mfma_f32_16x16x32_bf16 v[68:71], v[180:183], v[224:227], v[68:71]
	v_mfma_f32_16x16x32_bf16 v[64:67], v[188:191], v[224:227], v[64:67]
	s_setprio 0
	s_barrier
; #define PG8_STAGE(bufoff, gbase, voff) do { _Pragma("unroll") for (int _i = 0; _i < 2; ++_i) \
;         __builtin_amdgcn_global_load_lds((const unsigned*)((const char*)(gbase) + (voff)[_i]), (PG8_LAS unsigned*)(lds + (bufoff) + ldsw + _i * 8192), 16, 0, 0); } while (0)
; #define PG8_LDA(dst, b, h) do { _Pragma("unroll") for (int m = 0; m < 4; ++m) _Pragma("unroll") for (int k = 0; k < 2; ++k) dst[m][k] = *(const PG8_LAS bf16x8*)(lds + PG8_SA(b, h) + aoff + m * 2048 + k * 1024); } while (0)
; #define PG8_LDB(dst, b, h) do { _Pragma("unroll") for (int n = 0; n < 2; ++n) _Pragma("unroll") for (int k = 0; k < 2; ++k) dst[n][k] = *(const PG8_LAS bf16x8*)(lds + PG8_SB(b, h) + boff + n * 2048 + k * 1024); } while (0)
; #define PG8_MMA(ai, bj, At, Bt) do { __builtin_amdgcn_s_setprio(1); _Pragma("unroll") for (int m = 0; m < 4; ++m) _Pragma("unroll") for (int n = 0; n < 2; ++n) _Pragma("unroll") for (int k = 0; k < 2; ++k) \
;         acc[ai][bj][m][n] = __builtin_amdgcn_mfma_f32_16x16x32_bf16(Bt[n][k], At[m][k], acc[ai][bj][m][n], 0, 0, 0); __builtin_amdgcn_s_setprio(0); } while (0)
; #define PG8_WAIT_V(n) asm volatile("s_waitcnt vmcnt(" #n ")" ::: "memory")
; #define PG8_BAR __builtin_amdgcn_s_barrier()
; template <class Epi, class Sched, bool ALIGN_EPI = false, bool SP2 = false>
; __device__ __forceinline__ void gemm_phase(PG8_LAS unsigned char* lds, const Gemm g, const Sched& S, const Epi& E) {
;     ...
;         for (int t = 0; t < nt; t += 2) {
;             const bool last = (t == nt - 2);
;             const char* a1 = cA + (size_t)(t + 1) * kstep;
;             const char* a2 = last ? nA : cA + (size_t)(t + 2) * kstep; const char* b2 = last ? nB : cB + (size_t)(t + 2) * kstep;
;             const char* a3 = a2 + kstep; const char* b3 = b2 + kstep;
;             if (last && has_next) S.a_ready(nxt);
;             if constexpr (SP2) {
;             PG8_LDB(B0, 0, 0); PG8_LDB(B1, 0, 1); PG8_SCHED; PG8_LDA(At, 0, 0); PG8_STAGE(PG8_SA(1, 1), a1 + hstep, voffA);
;             PG8_WAIT_V(8); PG8_WAIT_L(0); PG8_BAR; PG8_MMA(0, 0, At, B0); PG8_MMA(0, 1, At, B1); PG8_BAR; PG8_SCHED;
;     ...
;             PG8_LDA(At, 1, 1); PG8_STAGE(PG8_SB(1, 0), b3, voffB); PG8_STAGE(PG8_SB(1, 1), b3 + hstep, voffB); PG8_STAGE(PG8_SA(1, 0), a3, voffA);
;             PG8_WAIT_V(8); PG8_WAIT_L(0); PG8_BAR; PG8_MMA(1, 0, At, B0); PG8_MMA(1, 1, At, B1); PG8_BAR; PG8_SCHED;
	s_add_i32 s19, s19, s15
	v_lshl_add_u64 v[144:145], v[144:145], 0, s[8:9]
	s_mov_b32 m0, s19
	ds_read_b128 v[192:195], v159 offset:49152
	ds_read_b128 v[196:199], v159 offset:50176
	ds_read_b128 v[200:203], v159 offset:51200
	ds_read_b128 v[208:211], v159 offset:52224
	ds_read_b128 v[212:215], v159 offset:53248
	ds_read_b128 v[216:219], v159 offset:54272
	ds_read_b128 v[220:223], v159 offset:55296
	ds_read_b128 v[224:227], v159 offset:56320
	global_load_lds_dwordx4 v[144:145], off
	s_add_i32 m0, s19, 0x2000
	s_add_u32 s60, s60, 0x40080
	v_lshl_add_u64 v[144:145], v[204:205], 0, s[8:9]
	s_addc_u32 s61, s61, 0
	s_add_i32 s19, s70, s15
	global_load_lds_dwordx4 v[144:145], off
	v_lshl_add_u64 v[144:145], s[60:61], 0, v[130:131]
	s_mov_b32 m0, s19
	s_nop 0
	global_load_lds_dwordx4 v[144:145], off
	v_lshl_add_u64 v[144:145], s[60:61], 0, v[134:135]
	s_add_i32 m0, s19, 0x2000
	s_nop 0
	global_load_lds_dwordx4 v[144:145], off
	v_lshl_add_u64 v[144:145], v[228:229], 0, s[8:9]
	s_mov_b32 m0, s64
	s_nop 0
	global_load_lds_dwordx4 v[144:145], off
	v_lshl_add_u64 v[144:145], v[230:231], 0, s[8:9]
	s_mov_b32 m0, s65
	s_nop 0
	global_load_lds_dwordx4 v[144:145], off
	s_waitcnt vmcnt(8)
	s_waitcnt lgkmcnt(0)
	s_barrier
	s_setprio 1
	s_waitcnt lgkmcnt(0)
	v_mfma_f32_16x16x32_bf16 v[60:63], v[160:163], v[192:195], v[60:63]
	v_mfma_f32_16x16x32_bf16 v[56:59], v[168:171], v[192:195], v[56:59]
	v_mfma_f32_16x16x32_bf16 v[48:51], v[160:163], v[200:203], v[48:51]
	v_mfma_f32_16x16x32_bf16 v[40:43], v[168:171], v[200:203], v[40:43]
	v_mfma_f32_16x16x32_bf16 v[32:35], v[160:163], v[212:215], v[32:35]
	v_mfma_f32_16x16x32_bf16 v[24:27], v[168:171], v[212:215], v[24:27]
	v_mfma_f32_16x16x32_bf16 v[16:19], v[160:163], v[220:223], v[16:19]
	v_mfma_f32_16x16x32_bf16 v[8:11], v[168:171], v[220:223], v[8:11]
	v_mfma_f32_16x16x32_bf16 v[60:63], v[164:167], v[196:199], v[60:63]
	v_mfma_f32_16x16x32_bf16 v[56:59], v[172:175], v[196:199], v[56:59]
	v_mfma_f32_16x16x32_bf16 v[48:51], v[164:167], v[208:211], v[48:51]
	v_mfma_f32_16x16x32_bf16 v[40:43], v[172:175], v[208:211], v[40:43]
	v_mfma_f32_16x16x32_bf16 v[32:35], v[164:167], v[216:219], v[32:35]
	v_mfma_f32_16x16x32_bf16 v[24:27], v[172:175], v[216:219], v[24:27]
	v_mfma_f32_16x16x32_bf16 v[16:19], v[164:167], v[224:227], v[16:19]
	v_mfma_f32_16x16x32_bf16 v[8:11], v[172:175], v[224:227], v[8:11]
	v_mfma_f32_16x16x32_bf16 v[52:55], v[176:179], v[192:195], v[52:55]
	v_mfma_f32_16x16x32_bf16 v[44:47], v[184:187], v[192:195], v[44:47]
	v_mfma_f32_16x16x32_bf16 v[36:39], v[176:179], v[200:203], v[36:39]
	v_mfma_f32_16x16x32_bf16 v[28:31], v[184:187], v[200:203], v[28:31]
	v_mfma_f32_16x16x32_bf16 v[20:23], v[176:179], v[212:215], v[20:23]
	v_mfma_f32_16x16x32_bf16 v[12:15], v[184:187], v[212:215], v[12:15]
	v_mfma_f32_16x16x32_bf16 v[4:7], v[176:179], v[220:223], v[4:7]
	v_mfma_f32_16x16x32_bf16 v[0:3], v[184:187], v[220:223], v[0:3]
	v_mfma_f32_16x16x32_bf16 v[52:55], v[180:183], v[196:199], v[52:55]
	v_mfma_f32_16x16x32_bf16 v[44:47], v[188:191], v[196:199], v[44:47]
	v_mfma_f32_16x16x32_bf16 v[36:39], v[180:183], v[208:211], v[36:39]
	v_mfma_f32_16x16x32_bf16 v[28:31], v[188:191], v[208:211], v[28:31]
	v_mfma_f32_16x16x32_bf16 v[20:23], v[180:183], v[216:219], v[20:23]
	v_mfma_f32_16x16x32_bf16 v[12:15], v[188:191], v[216:219], v[12:15]
	v_mfma_f32_16x16x32_bf16 v[4:7], v[180:183], v[224:227], v[4:7]
	v_mfma_f32_16x16x32_bf16 v[0:3], v[188:191], v[224:227], v[0:3]
	s_setprio 0
	s_barrier
	s_add_i32 s93, s93, 2
	s_add_u32 s58, s58, 0x100
	s_addc_u32 s59, s59, 0
	s_add_u32 s91, s91, 0x100
	s_addc_u32 s92, s92, 0
	s_cmp_gt_u32 s93, 13
	s_cbranch_scc1 .Lpeel_exit_0
	.p2align	6
.LBB0_128:
	ds_read_b128 v[160:163], v157
	ds_read_b128 v[164:167], v157 offset:1024
	ds_read_b128 v[168:171], v157 offset:2048
	ds_read_b128 v[172:175], v157 offset:3072
	ds_read_b128 v[176:179], v158
	ds_read_b128 v[180:183], v158 offset:1024
	ds_read_b128 v[184:187], v158 offset:2048
	ds_read_b128 v[188:191], v158 offset:3072
	s_add_u32 s19, s58, 0xfffc0080
	s_addc_u32 s60, s59, -1
	s_cmp_eq_u32 s93, 12
	s_cselect_b32 s63, s47, s60
	s_cselect_b32 s62, s89, s19
	s_cselect_b32 s61, s41, s92
	s_cselect_b32 s60, s90, s91
	v_lshl_add_u64 v[144:145], s[58:59], 0, v[136:137]
	s_add_i32 m0, s18, 0xc000
	ds_read_b128 v[192:195], v159
	ds_read_b128 v[196:199], v159 offset:1024
	ds_read_b128 v[200:203], v159 offset:2048
	ds_read_b128 v[208:211], v159 offset:3072
	ds_read_b128 v[212:215], v159 offset:4096
	ds_read_b128 v[216:219], v159 offset:5120
	ds_read_b128 v[220:223], v159 offset:6144
	ds_read_b128 v[224:227], v159 offset:7168
	global_load_lds_dwordx4 v[144:145], off
	v_lshl_add_u64 v[144:145], s[58:59], 0, v[138:139]
	s_add_i32 m0, s18, 0xe000
	s_nop 0
	global_load_lds_dwordx4 v[144:145], off
	s_waitcnt vmcnt(8)
	s_waitcnt lgkmcnt(0)
	s_barrier
; #define PG8_STAGE(bufoff, gbase, voff) do { _Pragma("unroll") for (int _i = 0; _i < 2; ++_i) \
;         __builtin_amdgcn_global_load_lds((const unsigned*)((const char*)(gbase) + (voff)[_i]), (PG8_LAS unsigned*)(lds + (bufoff) + ldsw + _i * 8192), 16, 0, 0); } while (0)
; #define PG8_LDA(dst, b, h) do { _Pragma("unroll") for (int m = 0; m < 4; ++m) _Pragma("unroll") for (int k = 0; k < 2; ++k) dst[m][k] = *(const PG8_LAS bf16x8*)(lds + PG8_SA(b, h) + aoff + m * 2048 + k * 1024); } while (0)
; #define PG8_MMA(ai, bj, At, Bt) do { __builtin_amdgcn_s_setprio(1); _Pragma("unroll") for (int m = 0; m < 4; ++m) _Pragma("unroll") for (int n = 0; n < 2; ++n) _Pragma("unroll") for (int k = 0; k < 2; ++k) \
;         acc[ai][bj][m][n] = __builtin_amdgcn_mfma_f32_16x16x32_bf16(Bt[n][k], At[m][k], acc[ai][bj][m][n], 0, 0, 0); __builtin_amdgcn_s_setprio(0); } while (0)
; #define PG8_WAIT_V(n) asm volatile("s_waitcnt vmcnt(" #n ")" ::: "memory")
; #define PG8_WAIT_L(n) asm volatile("s_waitcnt lgkmcnt(" #n ")" ::: "memory")
; #define PG8_BAR __builtin_amdgcn_s_barrier()
; #define PG8_SCHED __builtin_amdgcn_sched_barrier(0)
; template <class Epi, class Sched, bool ALIGN_EPI = false, bool SP2 = false>
; __device__ __forceinline__ void gemm_phase(PG8_LAS unsigned char* lds, const Gemm g, const Sched& S, const Epi& E) {
;     ...
;             PG8_WAIT_V(8); PG8_WAIT_L(0); PG8_BAR; PG8_MMA(0, 0, At, B0); PG8_MMA(0, 1, At, B1); PG8_BAR; PG8_SCHED;
;             PG8_LDA(At, 0, 1); PG8_STAGE(PG8_SB(0, 0), b2, voffB); PG8_STAGE(PG8_SB(0, 1), b2 + hstep, voffB); PG8_STAGE(PG8_SA(0, 0), a2, voffA);
;             PG8_WAIT_V(8); PG8_WAIT_L(0); PG8_BAR; PG8_MMA(1, 0, At, B0); PG8_MMA(1, 1, At, B1); PG8_BAR; PG8_SCHED;
	s_setprio 1
	s_waitcnt lgkmcnt(0)
	v_mfma_f32_16x16x32_bf16 v[124:127], v[160:163], v[192:195], v[124:127]
	v_mfma_f32_16x16x32_bf16 v[120:123], v[168:171], v[192:195], v[120:123]
	v_mfma_f32_16x16x32_bf16 v[112:115], v[160:163], v[200:203], v[112:115]
	v_mfma_f32_16x16x32_bf16 v[104:107], v[168:171], v[200:203], v[104:107]
	v_mfma_f32_16x16x32_bf16 v[96:99], v[160:163], v[212:215], v[96:99]
	v_mfma_f32_16x16x32_bf16 v[88:91], v[168:171], v[212:215], v[88:91]
	v_mfma_f32_16x16x32_bf16 v[80:83], v[160:163], v[220:223], v[80:83]
	v_mfma_f32_16x16x32_bf16 v[72:75], v[168:171], v[220:223], v[72:75]
	v_mfma_f32_16x16x32_bf16 v[124:127], v[164:167], v[196:199], v[124:127]
	v_mfma_f32_16x16x32_bf16 v[120:123], v[172:175], v[196:199], v[120:123]
	v_mfma_f32_16x16x32_bf16 v[112:115], v[164:167], v[208:211], v[112:115]
	v_mfma_f32_16x16x32_bf16 v[104:107], v[172:175], v[208:211], v[104:107]
	v_mfma_f32_16x16x32_bf16 v[96:99], v[164:167], v[216:219], v[96:99]
	v_mfma_f32_16x16x32_bf16 v[88:91], v[172:175], v[216:219], v[88:91]
	v_mfma_f32_16x16x32_bf16 v[80:83], v[164:167], v[224:227], v[80:83]
	v_mfma_f32_16x16x32_bf16 v[72:75], v[172:175], v[224:227], v[72:75]
	v_mfma_f32_16x16x32_bf16 v[116:119], v[176:179], v[192:195], v[116:119]
	v_mfma_f32_16x16x32_bf16 v[108:111], v[184:187], v[192:195], v[108:111]
	v_mfma_f32_16x16x32_bf16 v[100:103], v[176:179], v[200:203], v[100:103]
	v_mfma_f32_16x16x32_bf16 v[92:95], v[184:187], v[200:203], v[92:95]
	v_mfma_f32_16x16x32_bf16 v[84:87], v[176:179], v[212:215], v[84:87]
	v_mfma_f32_16x16x32_bf16 v[76:79], v[184:187], v[212:215], v[76:79]
	v_mfma_f32_16x16x32_bf16 v[68:71], v[176:179], v[220:223], v[68:71]
	v_mfma_f32_16x16x32_bf16 v[64:67], v[184:187], v[220:223], v[64:67]
	v_mfma_f32_16x16x32_bf16 v[116:119], v[180:183], v[196:199], v[116:119]
	v_mfma_f32_16x16x32_bf16 v[108:111], v[188:191], v[196:199], v[108:111]
	v_mfma_f32_16x16x32_bf16 v[100:103], v[180:183], v[208:211], v[100:103]
	v_mfma_f32_16x16x32_bf16 v[92:95], v[188:191], v[208:211], v[92:95]
	v_mfma_f32_16x16x32_bf16 v[84:87], v[180:183], v[216:219], v[84:87]
	v_mfma_f32_16x16x32_bf16 v[76:79], v[188:191], v[216:219], v[76:79]
	v_mfma_f32_16x16x32_bf16 v[68:71], v[180:183], v[224:227], v[68:71]
	v_mfma_f32_16x16x32_bf16 v[64:67], v[188:191], v[224:227], v[64:67]
	s_setprio 0
	s_barrier
	s_add_i32 s19, s75, s15
	v_lshl_add_u64 v[144:145], s[60:61], 0, v[130:131]
	s_mov_b32 m0, s19
	ds_read_b128 v[192:195], v159 offset:16384
	ds_read_b128 v[196:199], v159 offset:17408
	ds_read_b128 v[200:203], v159 offset:18432
	ds_read_b128 v[208:211], v159 offset:19456
	ds_read_b128 v[212:215], v159 offset:20480
	ds_read_b128 v[216:219], v159 offset:21504
	ds_read_b128 v[220:223], v159 offset:22528
	ds_read_b128 v[224:227], v159 offset:23552
	global_load_lds_dwordx4 v[144:145], off
	s_add_i32 m0, s19, 0x2000
	s_add_u32 s70, s60, 0x40000
	v_lshl_add_u64 v[204:205], s[60:61], 0, v[134:135]
	s_addc_u32 s71, s61, 0
	s_add_i32 s19, s84, s15
	global_load_lds_dwordx4 v[204:205], off
	v_lshl_add_u64 v[228:229], s[70:71], 0, v[130:131]
	s_mov_b32 m0, s19
	v_lshl_add_u64 v[230:231], s[62:63], 0, v[132:133]
	global_load_lds_dwordx4 v[228:229], off
	v_lshl_add_u64 v[228:229], s[70:71], 0, v[134:135]
	s_add_i32 m0, s19, 0x2000
	s_nop 0
	global_load_lds_dwordx4 v[228:229], off
	v_lshl_add_u64 v[228:229], s[62:63], 0, v[128:129]
	s_mov_b32 m0, s18
	s_nop 0
	global_load_lds_dwordx4 v[228:229], off
	s_mov_b32 m0, s23
	s_nop 0
	global_load_lds_dwordx4 v[230:231], off
	s_waitcnt vmcnt(8)
	s_waitcnt lgkmcnt(0)
	s_barrier
	s_setprio 1
	s_waitcnt lgkmcnt(0)
	v_mfma_f32_16x16x32_bf16 v[60:63], v[160:163], v[192:195], v[60:63]
	v_mfma_f32_16x16x32_bf16 v[56:59], v[168:171], v[192:195], v[56:59]
	v_mfma_f32_16x16x32_bf16 v[48:51], v[160:163], v[200:203], v[48:51]
	v_mfma_f32_16x16x32_bf16 v[40:43], v[168:171], v[200:203], v[40:43]
	v_mfma_f32_16x16x32_bf16 v[32:35], v[160:163], v[212:215], v[32:35]
	v_mfma_f32_16x16x32_bf16 v[24:27], v[168:171], v[212:215], v[24:27]
	v_mfma_f32_16x16x32_bf16 v[16:19], v[160:163], v[220:223], v[16:19]
	v_mfma_f32_16x16x32_bf16 v[8:11], v[168:171], v[220:223], v[8:11]
	v_mfma_f32_16x16x32_bf16 v[60:63], v[164:167], v[196:199], v[60:63]
	v_mfma_f32_16x16x32_bf16 v[56:59], v[172:175], v[196:199], v[56:59]
	v_mfma_f32_16x16x32_bf16 v[48:51], v[164:167], v[208:211], v[48:51]
	v_mfma_f32_16x16x32_bf16 v[40:43], v[172:175], v[208:211], v[40:43]
	v_mfma_f32_16x16x32_bf16 v[32:35], v[164:167], v[216:219], v[32:35]
	v_mfma_f32_16x16x32_bf16 v[24:27], v[172:175], v[216:219], v[24:27]
	v_mfma_f32_16x16x32_bf16 v[16:19], v[164:167], v[224:227], v[16:19]
	v_mfma_f32_16x16x32_bf16 v[8:11], v[172:175], v[224:227], v[8:11]
	v_mfma_f32_16x16x32_bf16 v[52:55], v[176:179], v[192:195], v[52:55]
	v_mfma_f32_16x16x32_bf16 v[44:47], v[184:187], v[192:195], v[44:47]
	v_mfma_f32_16x16x32_bf16 v[36:39], v[176:179], v[200:203], v[36:39]
	v_mfma_f32_16x16x32_bf16 v[28:31], v[184:187], v[200:203], v[28:31]
	v_mfma_f32_16x16x32_bf16 v[20:23], v[176:179], v[212:215], v[20:23]
	v_mfma_f32_16x16x32_bf16 v[12:15], v[184:187], v[212:215], v[12:15]
	v_mfma_f32_16x16x32_bf16 v[4:7], v[176:179], v[220:223], v[4:7]
	v_mfma_f32_16x16x32_bf16 v[0:3], v[184:187], v[220:223], v[0:3]
	v_mfma_f32_16x16x32_bf16 v[52:55], v[180:183], v[196:199], v[52:55]
	v_mfma_f32_16x16x32_bf16 v[44:47], v[188:191], v[196:199], v[44:47]
	v_mfma_f32_16x16x32_bf16 v[36:39], v[180:183], v[208:211], v[36:39]
	v_mfma_f32_16x16x32_bf16 v[28:31], v[188:191], v[208:211], v[28:31]
	v_mfma_f32_16x16x32_bf16 v[20:23], v[180:183], v[216:219], v[20:23]
	v_mfma_f32_16x16x32_bf16 v[12:15], v[188:191], v[216:219], v[12:15]
	v_mfma_f32_16x16x32_bf16 v[4:7], v[180:183], v[224:227], v[4:7]
	v_mfma_f32_16x16x32_bf16 v[0:3], v[188:191], v[224:227], v[0:3]
	s_setprio 0
	s_barrier
; #define PG8_STAGE(bufoff, gbase, voff) do { _Pragma("unroll") for (int _i = 0; _i < 2; ++_i) \
;         __builtin_amdgcn_global_load_lds((const unsigned*)((const char*)(gbase) + (voff)[_i]), (PG8_LAS unsigned*)(lds + (bufoff) + ldsw + _i * 8192), 16, 0, 0); } while (0)
; #define PG8_LDA(dst, b, h) do { _Pragma("unroll") for (int m = 0; m < 4; ++m) _Pragma("unroll") for (int k = 0; k < 2; ++k) dst[m][k] = *(const PG8_LAS bf16x8*)(lds + PG8_SA(b, h) + aoff + m * 2048 + k * 1024); } while (0)
; #define PG8_LDB(dst, b, h) do { _Pragma("unroll") for (int n = 0; n < 2; ++n) _Pragma("unroll") for (int k = 0; k < 2; ++k) dst[n][k] = *(const PG8_LAS bf16x8*)(lds + PG8_SB(b, h) + boff + n * 2048 + k * 1024); } while (0)
; #define PG8_MMA(ai, bj, At, Bt) do { __builtin_amdgcn_s_setprio(1); _Pragma("unroll") for (int m = 0; m < 4; ++m) _Pragma("unroll") for (int n = 0; n < 2; ++n) _Pragma("unroll") for (int k = 0; k < 2; ++k) \
;         acc[ai][bj][m][n] = __builtin_amdgcn_mfma_f32_16x16x32_bf16(Bt[n][k], At[m][k], acc[ai][bj][m][n], 0, 0, 0); __builtin_amdgcn_s_setprio(0); } while (0)
; #define PG8_WAIT_V(n) asm volatile("s_waitcnt vmcnt(" #n ")" ::: "memory")
; #define PG8_WAIT_L(n) asm volatile("s_waitcnt lgkmcnt(" #n ")" ::: "memory")
; #define PG8_BAR __builtin_amdgcn_s_barrier()
; #define PG8_SCHED __builtin_amdgcn_sched_barrier(0)
; template <class Epi, class Sched, bool ALIGN_EPI = false, bool SP2 = false>
; __device__ __forceinline__ void gemm_phase(PG8_LAS unsigned char* lds, const Gemm g, const Sched& S, const Epi& E) {
;     ...
;             PG8_LDB(B0, 1, 0); PG8_LDB(B1, 1, 1); PG8_SCHED; PG8_LDA(At, 1, 0); PG8_STAGE(PG8_SA(0, 1), a2 + hstep, voffA);
;             PG8_WAIT_V(8); PG8_WAIT_L(0); PG8_BAR; PG8_MMA(0, 0, At, B0); PG8_MMA(0, 1, At, B1); PG8_BAR; PG8_SCHED;
	s_add_i32 s19, 0, 0x18000
	s_add_i32 s70, 0, 0x1c000
	v_add_u32_e32 v172, s19, v155
	v_add_u32_e32 v188, s70, v155
	ds_read_b128 v[160:163], v172
	ds_read_b128 v[164:167], v172 offset:1024
	ds_read_b128 v[168:171], v172 offset:2048
	ds_read_b128 v[172:175], v172 offset:3072
	ds_read_b128 v[176:179], v188
	ds_read_b128 v[180:183], v188 offset:1024
	ds_read_b128 v[184:187], v188 offset:2048
	ds_read_b128 v[188:191], v188 offset:3072
	s_add_u32 s62, s62, 0x40000
	s_addc_u32 s63, s63, 0
	s_mov_b32 m0, s33
	v_lshl_add_u64 v[232:233], s[62:63], 0, v[128:129]
	ds_read_b128 v[192:195], v159 offset:32768
	ds_read_b128 v[196:199], v159 offset:33792
	ds_read_b128 v[200:203], v159 offset:34816
	ds_read_b128 v[208:211], v159 offset:35840
	ds_read_b128 v[212:215], v159 offset:36864
	ds_read_b128 v[216:219], v159 offset:37888
	ds_read_b128 v[220:223], v159 offset:38912
	ds_read_b128 v[224:227], v159 offset:39936
	global_load_lds_dwordx4 v[232:233], off
	v_lshl_add_u64 v[232:233], s[62:63], 0, v[132:133]
	s_mov_b32 m0, s35
	s_nop 0
	global_load_lds_dwordx4 v[232:233], off
	s_waitcnt vmcnt(8)
	s_waitcnt lgkmcnt(0)
	s_barrier
	s_setprio 1
	s_waitcnt lgkmcnt(0)
	v_mfma_f32_16x16x32_bf16 v[124:127], v[160:163], v[192:195], v[124:127]
	v_mfma_f32_16x16x32_bf16 v[120:123], v[168:171], v[192:195], v[120:123]
	v_mfma_f32_16x16x32_bf16 v[112:115], v[160:163], v[200:203], v[112:115]
	v_mfma_f32_16x16x32_bf16 v[104:107], v[168:171], v[200:203], v[104:107]
	v_mfma_f32_16x16x32_bf16 v[96:99], v[160:163], v[212:215], v[96:99]
	v_mfma_f32_16x16x32_bf16 v[88:91], v[168:171], v[212:215], v[88:91]
	v_mfma_f32_16x16x32_bf16 v[80:83], v[160:163], v[220:223], v[80:83]
	v_mfma_f32_16x16x32_bf16 v[72:75], v[168:171], v[220:223], v[72:75]
	v_mfma_f32_16x16x32_bf16 v[124:127], v[164:167], v[196:199], v[124:127]
	v_mfma_f32_16x16x32_bf16 v[120:123], v[172:175], v[196:199], v[120:123]
	v_mfma_f32_16x16x32_bf16 v[112:115], v[164:167], v[208:211], v[112:115]
	v_mfma_f32_16x16x32_bf16 v[104:107], v[172:175], v[208:211], v[104:107]
	v_mfma_f32_16x16x32_bf16 v[96:99], v[164:167], v[216:219], v[96:99]
	v_mfma_f32_16x16x32_bf16 v[88:91], v[172:175], v[216:219], v[88:91]
	v_mfma_f32_16x16x32_bf16 v[80:83], v[164:167], v[224:227], v[80:83]
	v_mfma_f32_16x16x32_bf16 v[72:75], v[172:175], v[224:227], v[72:75]
	v_mfma_f32_16x16x32_bf16 v[116:119], v[176:179], v[192:195], v[116:119]
	v_mfma_f32_16x16x32_bf16 v[108:111], v[184:187], v[192:195], v[108:111]
	v_mfma_f32_16x16x32_bf16 v[100:103], v[176:179], v[200:203], v[100:103]
	v_mfma_f32_16x16x32_bf16 v[92:95], v[184:187], v[200:203], v[92:95]
	v_mfma_f32_16x16x32_bf16 v[84:87], v[176:179], v[212:215], v[84:87]
	v_mfma_f32_16x16x32_bf16 v[76:79], v[184:187], v[212:215], v[76:79]
	v_mfma_f32_16x16x32_bf16 v[68:71], v[176:179], v[220:223], v[68:71]
	v_mfma_f32_16x16x32_bf16 v[64:67], v[184:187], v[220:223], v[64:67]
	v_mfma_f32_16x16x32_bf16 v[116:119], v[180:183], v[196:199], v[116:119]
	v_mfma_f32_16x16x32_bf16 v[108:111], v[188:191], v[196:199], v[108:111]
	v_mfma_f32_16x16x32_bf16 v[100:103], v[180:183], v[208:211], v[100:103]
	v_mfma_f32_16x16x32_bf16 v[92:95], v[188:191], v[208:211], v[92:95]
	v_mfma_f32_16x16x32_bf16 v[84:87], v[180:183], v[216:219], v[84:87]
	v_mfma_f32_16x16x32_bf16 v[76:79], v[188:191], v[216:219], v[76:79]
	v_mfma_f32_16x16x32_bf16 v[68:71], v[180:183], v[224:227], v[68:71]
	v_mfma_f32_16x16x32_bf16 v[64:67], v[188:191], v[224:227], v[64:67]
	s_setprio 0
	s_barrier
; #define PG8_STAGE(bufoff, gbase, voff) do { _Pragma("unroll") for (int _i = 0; _i < 2; ++_i) \
;         __builtin_amdgcn_global_load_lds((const unsigned*)((const char*)(gbase) + (voff)[_i]), (PG8_LAS unsigned*)(lds + (bufoff) + ldsw + _i * 8192), 16, 0, 0); } while (0)
; #define PG8_LDA(dst, b, h) do { _Pragma("unroll") for (int m = 0; m < 4; ++m) _Pragma("unroll") for (int k = 0; k < 2; ++k) dst[m][k] = *(const PG8_LAS bf16x8*)(lds + PG8_SA(b, h) + aoff + m * 2048 + k * 1024); } while (0)
; #define PG8_MMA(ai, bj, At, Bt) do { __builtin_amdgcn_s_setprio(1); _Pragma("unroll") for (int m = 0; m < 4; ++m) _Pragma("unroll") for (int n = 0; n < 2; ++n) _Pragma("unroll") for (int k = 0; k < 2; ++k) \
;         acc[ai][bj][m][n] = __builtin_amdgcn_mfma_f32_16x16x32_bf16(Bt[n][k], At[m][k], acc[ai][bj][m][n], 0, 0, 0); __builtin_amdgcn_s_setprio(0); } while (0)
; #define PG8_WAIT_V(n) asm volatile("s_waitcnt vmcnt(" #n ")" ::: "memory")
; #define PG8_WAIT_L(n) asm volatile("s_waitcnt lgkmcnt(" #n ")" ::: "memory")
; #define PG8_BAR __builtin_amdgcn_s_barrier()
; #define PG8_SCHED __builtin_amdgcn_sched_barrier(0)
; template <class Epi, class Sched, bool ALIGN_EPI = false, bool SP2 = false>
; __device__ __forceinline__ void gemm_phase(PG8_LAS unsigned char* lds, const Gemm g, const Sched& S, const Epi& E) {
;     ...
;         for (int t = 0; t < nt; t += 2) {
;     ...
;             PG8_LDA(At, 1, 1); PG8_STAGE(PG8_SB(1, 0), b3, voffB); PG8_STAGE(PG8_SB(1, 1), b3 + hstep, voffB); PG8_STAGE(PG8_SA(1, 0), a3, voffA);
;             PG8_WAIT_V(8); PG8_WAIT_L(0); PG8_BAR; PG8_MMA(1, 0, At, B0); PG8_MMA(1, 1, At, B1); PG8_BAR; PG8_SCHED;
	s_add_i32 s19, s19, s15
	v_lshl_add_u64 v[144:145], v[144:145], 0, s[8:9]
	s_mov_b32 m0, s19
	ds_read_b128 v[192:195], v159 offset:49152
	ds_read_b128 v[196:199], v159 offset:50176
	ds_read_b128 v[200:203], v159 offset:51200
	ds_read_b128 v[208:211], v159 offset:52224
	ds_read_b128 v[212:215], v159 offset:53248
	ds_read_b128 v[216:219], v159 offset:54272
	ds_read_b128 v[220:223], v159 offset:55296
	ds_read_b128 v[224:227], v159 offset:56320
	global_load_lds_dwordx4 v[144:145], off
	s_add_i32 m0, s19, 0x2000
	s_add_u32 s60, s60, 0x40080
	v_lshl_add_u64 v[144:145], v[204:205], 0, s[8:9]
	s_addc_u32 s61, s61, 0
	s_add_i32 s19, s70, s15
	global_load_lds_dwordx4 v[144:145], off
	v_lshl_add_u64 v[144:145], s[60:61], 0, v[130:131]
	s_mov_b32 m0, s19
	s_nop 0
	global_load_lds_dwordx4 v[144:145], off
	v_lshl_add_u64 v[144:145], s[60:61], 0, v[134:135]
	s_add_i32 m0, s19, 0x2000
	s_nop 0
	global_load_lds_dwordx4 v[144:145], off
	v_lshl_add_u64 v[144:145], v[228:229], 0, s[8:9]
	s_mov_b32 m0, s64
	s_nop 0
	global_load_lds_dwordx4 v[144:145], off
	v_lshl_add_u64 v[144:145], v[230:231], 0, s[8:9]
	s_mov_b32 m0, s65
	s_nop 0
	global_load_lds_dwordx4 v[144:145], off
	s_waitcnt vmcnt(8)
	s_waitcnt lgkmcnt(0)
	s_barrier
	s_setprio 1
	s_waitcnt lgkmcnt(0)
	v_mfma_f32_16x16x32_bf16 v[60:63], v[160:163], v[192:195], v[60:63]
	v_mfma_f32_16x16x32_bf16 v[56:59], v[168:171], v[192:195], v[56:59]
	v_mfma_f32_16x16x32_bf16 v[48:51], v[160:163], v[200:203], v[48:51]
	v_mfma_f32_16x16x32_bf16 v[40:43], v[168:171], v[200:203], v[40:43]
	v_mfma_f32_16x16x32_bf16 v[32:35], v[160:163], v[212:215], v[32:35]
	v_mfma_f32_16x16x32_bf16 v[24:27], v[168:171], v[212:215], v[24:27]
	v_mfma_f32_16x16x32_bf16 v[16:19], v[160:163], v[220:223], v[16:19]
	v_mfma_f32_16x16x32_bf16 v[8:11], v[168:171], v[220:223], v[8:11]
	v_mfma_f32_16x16x32_bf16 v[60:63], v[164:167], v[196:199], v[60:63]
	v_mfma_f32_16x16x32_bf16 v[56:59], v[172:175], v[196:199], v[56:59]
	v_mfma_f32_16x16x32_bf16 v[48:51], v[164:167], v[208:211], v[48:51]
	v_mfma_f32_16x16x32_bf16 v[40:43], v[172:175], v[208:211], v[40:43]
	v_mfma_f32_16x16x32_bf16 v[32:35], v[164:167], v[216:219], v[32:35]
	v_mfma_f32_16x16x32_bf16 v[24:27], v[172:175], v[216:219], v[24:27]
	v_mfma_f32_16x16x32_bf16 v[16:19], v[164:167], v[224:227], v[16:19]
	v_mfma_f32_16x16x32_bf16 v[8:11], v[172:175], v[224:227], v[8:11]
	v_mfma_f32_16x16x32_bf16 v[52:55], v[176:179], v[192:195], v[52:55]
	v_mfma_f32_16x16x32_bf16 v[44:47], v[184:187], v[192:195], v[44:47]
	v_mfma_f32_16x16x32_bf16 v[36:39], v[176:179], v[200:203], v[36:39]
	v_mfma_f32_16x16x32_bf16 v[28:31], v[184:187], v[200:203], v[28:31]
	v_mfma_f32_16x16x32_bf16 v[20:23], v[176:179], v[212:215], v[20:23]
	v_mfma_f32_16x16x32_bf16 v[12:15], v[184:187], v[212:215], v[12:15]
	v_mfma_f32_16x16x32_bf16 v[4:7], v[176:179], v[220:223], v[4:7]
	v_mfma_f32_16x16x32_bf16 v[0:3], v[184:187], v[220:223], v[0:3]
	v_mfma_f32_16x16x32_bf16 v[52:55], v[180:183], v[196:199], v[52:55]
	v_mfma_f32_16x16x32_bf16 v[44:47], v[188:191], v[196:199], v[44:47]
	v_mfma_f32_16x16x32_bf16 v[36:39], v[180:183], v[208:211], v[36:39]
	v_mfma_f32_16x16x32_bf16 v[28:31], v[188:191], v[208:211], v[28:31]
	v_mfma_f32_16x16x32_bf16 v[20:23], v[180:183], v[216:219], v[20:23]
	v_mfma_f32_16x16x32_bf16 v[12:15], v[188:191], v[216:219], v[12:15]
	v_mfma_f32_16x16x32_bf16 v[4:7], v[180:183], v[224:227], v[4:7]
	v_mfma_f32_16x16x32_bf16 v[0:3], v[188:191], v[224:227], v[0:3]
	s_setprio 0
	s_barrier
	s_add_i32 s93, s93, 2
	s_add_u32 s58, s58, 0x100
	s_addc_u32 s59, s59, 0
	s_add_u32 s91, s91, 0x100
	s_addc_u32 s92, s92, 0
	s_cmp_gt_u32 s93, 13
	s_cbranch_scc0 .LBB0_128

; #define PG8_STAGE(bufoff, gbase, voff) do { _Pragma("unroll") for (int _i = 0; _i < 2; ++_i) \
;         __builtin_amdgcn_global_load_lds((const unsigned*)((const char*)(gbase) + (voff)[_i]), (PG8_LAS unsigned*)(lds + (bufoff) + ldsw + _i * 8192), 16, 0, 0); } while (0)
; #define PG8_LDA(dst, b, h) do { _Pragma("unroll") for (int m = 0; m < 4; ++m) _Pragma("unroll") for (int k = 0; k < 2; ++k) dst[m][k] = *(const PG8_LAS bf16x8*)(lds + PG8_SA(b, h) + aoff + m * 2048 + k * 1024); } while (0)
; #define PG8_LDB(dst, b, h) do { _Pragma("unroll") for (int n = 0; n < 2; ++n) _Pragma("unroll") for (int k = 0; k < 2; ++k) dst[n][k] = *(const PG8_LAS bf16x8*)(lds + PG8_SB(b, h) + boff + n * 2048 + k * 1024); } while (0)
; #define PG8_WAIT_V(n) asm volatile("s_waitcnt vmcnt(" #n ")" ::: "memory")
; #define PG8_WAIT_L(n) asm volatile("s_waitcnt lgkmcnt(" #n ")" ::: "memory")
; #define PG8_BAR __builtin_amdgcn_s_barrier()
; #define PG8_SCHED __builtin_amdgcn_sched_barrier(0)
; template <class Epi, class Sched, bool ALIGN_EPI = false, bool SP2 = false>
; __device__ __forceinline__ void gemm_phase(PG8_LAS unsigned char* lds, const Gemm g, const Sched& S, const Epi& E) {
;     ...
;         const bool has_next = S.next(ui + 1, nxt);
;         const char* nA = has_next ? (const char*)g.A + (size_t)nxt.pm * tstep : cA; const char* nB = has_next ? (const char*)g.Bt + (size_t)nxt.pn * tstep : cB;
;         for (int t = 0; t < nt; t += 2) {
;             const bool last = (t == nt - 2);
;             const char* a1 = cA + (size_t)(t + 1) * kstep;
;             const char* a2 = last ? nA : cA + (size_t)(t + 2) * kstep; const char* b2 = last ? nB : cB + (size_t)(t + 2) * kstep;
;             const char* a3 = a2 + kstep; const char* b3 = b2 + kstep;
;             if (last && has_next) S.a_ready(nxt);
;             if constexpr (SP2) {
;             PG8_LDB(B0, 0, 0); PG8_LDB(B1, 0, 1); PG8_SCHED; PG8_LDA(At, 0, 0); PG8_STAGE(PG8_SA(1, 1), a1 + hstep, voffA);
;             PG8_WAIT_V(8); PG8_WAIT_L(0); PG8_BAR; PG8_MMA(0, 0, At, B0); PG8_MMA(0, 1, At, B1); PG8_BAR; PG8_SCHED;
;             PG8_LDA(At, 0, 1); PG8_STAGE(PG8_SB(0, 0), b2, voffB); PG8_STAGE(PG8_SB(0, 1), b2 + hstep, voffB); PG8_STAGE(PG8_SA(0, 0), a2, voffA);
;             PG8_WAIT_V(8); PG8_WAIT_L(0); PG8_BAR; PG8_MMA(1, 0, At, B0); PG8_MMA(1, 1, At, B1); PG8_BAR; PG8_SCHED;
.LBB0_151:
	s_ashr_i32 s47, s46, 31
	s_lshl_b64 s[50:51], s[46:47], 19
	s_add_u32 s50, s15, s50
	s_addc_u32 s51, s18, s51
	s_and_b64 s[54:55], s[2:3], exec
	s_cselect_b32 s47, s51, s59
	s_cselect_b32 s89, s50, s58
	s_ashr_i32 s41, s40, 31
	s_lshl_b64 s[54:55], s[40:41], 19
	s_add_u32 s54, s36, s54
	s_addc_u32 s55, s37, s55
	s_and_b64 s[62:63], s[2:3], exec
	s_cselect_b32 s41, s55, s61
	s_cselect_b32 s90, s54, s60
	s_add_u32 s58, s58, 0x40080
	s_addc_u32 s59, s59, 0
	s_add_u32 s91, s60, 0x100
	s_addc_u32 s92, s61, 0
	s_mov_b32 s93, -2
	ds_read_b128 v[156:159], v146
	ds_read_b128 v[160:163], v146 offset:1024
	ds_read_b128 v[164:167], v146 offset:2048
	ds_read_b128 v[168:171], v146 offset:3072
	ds_read_b128 v[172:175], v147
	ds_read_b128 v[176:179], v147 offset:1024
	ds_read_b128 v[180:183], v147 offset:2048
	ds_read_b128 v[184:187], v147 offset:3072
	s_add_u32 s19, s58, 0xfffc0080
	s_addc_u32 s60, s59, -1
	s_cmp_eq_u32 s93, 12
	s_cselect_b32 s63, s47, s60
	s_cselect_b32 s62, s89, s19
	s_cselect_b32 s61, s41, s92
	s_cselect_b32 s60, s90, s91
	v_lshl_add_u64 v[144:145], s[58:59], 0, v[136:137]
	s_add_i32 m0, s33, 0xc000
	ds_read_b128 v[188:191], v148
	ds_read_b128 v[192:195], v148 offset:1024
	ds_read_b128 v[196:199], v148 offset:2048
	ds_read_b128 v[200:203], v148 offset:3072
	ds_read_b128 v[208:211], v148 offset:4096
	ds_read_b128 v[212:215], v148 offset:5120
	ds_read_b128 v[216:219], v148 offset:6144
	ds_read_b128 v[220:223], v148 offset:7168
	global_load_lds_dwordx4 v[144:145], off
	v_lshl_add_u64 v[144:145], s[58:59], 0, v[138:139]
	s_add_i32 m0, s33, 0xe000
	s_nop 0
	global_load_lds_dwordx4 v[144:145], off
	s_waitcnt vmcnt(8)
	s_waitcnt lgkmcnt(0)
	s_barrier
	s_setprio 1
	s_waitcnt lgkmcnt(0)
	v_mfma_f32_16x16x32_bf16 v[124:127], v[156:159], v[188:191], 0
	v_mfma_f32_16x16x32_bf16 v[120:123], v[164:167], v[188:191], 0
	v_mfma_f32_16x16x32_bf16 v[112:115], v[156:159], v[196:199], 0
	v_mfma_f32_16x16x32_bf16 v[104:107], v[164:167], v[196:199], 0
	v_mfma_f32_16x16x32_bf16 v[96:99], v[156:159], v[208:211], 0
	v_mfma_f32_16x16x32_bf16 v[88:91], v[164:167], v[208:211], 0
	v_mfma_f32_16x16x32_bf16 v[80:83], v[156:159], v[216:219], 0
	v_mfma_f32_16x16x32_bf16 v[72:75], v[164:167], v[216:219], 0
	v_mfma_f32_16x16x32_bf16 v[124:127], v[160:163], v[192:195], v[124:127]
	v_mfma_f32_16x16x32_bf16 v[120:123], v[168:171], v[192:195], v[120:123]
	v_mfma_f32_16x16x32_bf16 v[112:115], v[160:163], v[200:203], v[112:115]
	v_mfma_f32_16x16x32_bf16 v[104:107], v[168:171], v[200:203], v[104:107]
	v_mfma_f32_16x16x32_bf16 v[96:99], v[160:163], v[212:215], v[96:99]
	v_mfma_f32_16x16x32_bf16 v[88:91], v[168:171], v[212:215], v[88:91]
	v_mfma_f32_16x16x32_bf16 v[80:83], v[160:163], v[220:223], v[80:83]
	v_mfma_f32_16x16x32_bf16 v[72:75], v[168:171], v[220:223], v[72:75]
	v_mfma_f32_16x16x32_bf16 v[116:119], v[172:175], v[188:191], 0
	v_mfma_f32_16x16x32_bf16 v[108:111], v[180:183], v[188:191], 0
	v_mfma_f32_16x16x32_bf16 v[100:103], v[172:175], v[196:199], 0
	v_mfma_f32_16x16x32_bf16 v[92:95], v[180:183], v[196:199], 0
	v_mfma_f32_16x16x32_bf16 v[84:87], v[172:175], v[208:211], 0
	v_mfma_f32_16x16x32_bf16 v[76:79], v[180:183], v[208:211], 0
	v_mfma_f32_16x16x32_bf16 v[68:71], v[172:175], v[216:219], 0
	v_mfma_f32_16x16x32_bf16 v[64:67], v[180:183], v[216:219], 0
	v_mfma_f32_16x16x32_bf16 v[116:119], v[176:179], v[192:195], v[116:119]
	v_mfma_f32_16x16x32_bf16 v[108:111], v[184:187], v[192:195], v[108:111]
	v_mfma_f32_16x16x32_bf16 v[100:103], v[176:179], v[200:203], v[100:103]
	v_mfma_f32_16x16x32_bf16 v[92:95], v[184:187], v[200:203], v[92:95]
	v_mfma_f32_16x16x32_bf16 v[84:87], v[176:179], v[212:215], v[84:87]
	v_mfma_f32_16x16x32_bf16 v[76:79], v[184:187], v[212:215], v[76:79]
	v_mfma_f32_16x16x32_bf16 v[68:71], v[176:179], v[220:223], v[68:71]
	v_mfma_f32_16x16x32_bf16 v[64:67], v[184:187], v[220:223], v[64:67]
	s_setprio 0
	s_barrier
	s_add_i32 s19, s83, s23
	v_lshl_add_u64 v[144:145], s[60:61], 0, v[130:131]
	s_mov_b32 m0, s19
	ds_read_b128 v[188:191], v148 offset:16384
	ds_read_b128 v[192:195], v148 offset:17408
	ds_read_b128 v[196:199], v148 offset:18432
	ds_read_b128 v[200:203], v148 offset:19456
	ds_read_b128 v[208:211], v148 offset:20480
	ds_read_b128 v[212:215], v148 offset:21504
	ds_read_b128 v[216:219], v148 offset:22528
	ds_read_b128 v[220:223], v148 offset:23552
	global_load_lds_dwordx4 v[144:145], off
	s_add_i32 m0, s19, 0x2000
	s_add_u32 s70, s60, 0x40000
	v_lshl_add_u64 v[152:153], s[60:61], 0, v[134:135]
	s_addc_u32 s71, s61, 0
	s_add_i32 s19, s84, s23
	global_load_lds_dwordx4 v[152:153], off
	v_lshl_add_u64 v[204:205], s[70:71], 0, v[130:131]
	s_mov_b32 m0, s19
	v_lshl_add_u64 v[224:225], s[62:63], 0, v[132:133]
	global_load_lds_dwordx4 v[204:205], off
	v_lshl_add_u64 v[204:205], s[70:71], 0, v[134:135]
	s_add_i32 m0, s19, 0x2000
	s_nop 0
	global_load_lds_dwordx4 v[204:205], off
	v_lshl_add_u64 v[204:205], s[62:63], 0, v[128:129]
	s_mov_b32 m0, s33
	s_nop 0
	global_load_lds_dwordx4 v[204:205], off
	s_mov_b32 m0, s35
	s_nop 0
	global_load_lds_dwordx4 v[224:225], off
	s_waitcnt vmcnt(8)
	s_waitcnt lgkmcnt(0)
	s_barrier
; #define PG8_STAGE(bufoff, gbase, voff) do { _Pragma("unroll") for (int _i = 0; _i < 2; ++_i) \
;         __builtin_amdgcn_global_load_lds((const unsigned*)((const char*)(gbase) + (voff)[_i]), (PG8_LAS unsigned*)(lds + (bufoff) + ldsw + _i * 8192), 16, 0, 0); } while (0)
; #define PG8_LDA(dst, b, h) do { _Pragma("unroll") for (int m = 0; m < 4; ++m) _Pragma("unroll") for (int k = 0; k < 2; ++k) dst[m][k] = *(const PG8_LAS bf16x8*)(lds + PG8_SA(b, h) + aoff + m * 2048 + k * 1024); } while (0)
; #define PG8_LDB(dst, b, h) do { _Pragma("unroll") for (int n = 0; n < 2; ++n) _Pragma("unroll") for (int k = 0; k < 2; ++k) dst[n][k] = *(const PG8_LAS bf16x8*)(lds + PG8_SB(b, h) + boff + n * 2048 + k * 1024); } while (0)
; #define PG8_MMA(ai, bj, At, Bt) do { __builtin_amdgcn_s_setprio(1); _Pragma("unroll") for (int m = 0; m < 4; ++m) _Pragma("unroll") for (int n = 0; n < 2; ++n) _Pragma("unroll") for (int k = 0; k < 2; ++k) \
;         acc[ai][bj][m][n] = __builtin_amdgcn_mfma_f32_16x16x32_bf16(Bt[n][k], At[m][k], acc[ai][bj][m][n], 0, 0, 0); __builtin_amdgcn_s_setprio(0); } while (0)
; #define PG8_WAIT_V(n) asm volatile("s_waitcnt vmcnt(" #n ")" ::: "memory")
; #define PG8_WAIT_L(n) asm volatile("s_waitcnt lgkmcnt(" #n ")" ::: "memory")
; #define PG8_BAR __builtin_amdgcn_s_barrier()
; #define PG8_SCHED __builtin_amdgcn_sched_barrier(0)
; template <class Epi, class Sched, bool ALIGN_EPI = false, bool SP2 = false>
; __device__ __forceinline__ void gemm_phase(PG8_LAS unsigned char* lds, const Gemm g, const Sched& S, const Epi& E) {
;     ...
;             PG8_WAIT_V(8); PG8_WAIT_L(0); PG8_BAR; PG8_MMA(1, 0, At, B0); PG8_MMA(1, 1, At, B1); PG8_BAR; PG8_SCHED;
;             PG8_LDB(B0, 1, 0); PG8_LDB(B1, 1, 1); PG8_SCHED; PG8_LDA(At, 1, 0); PG8_STAGE(PG8_SA(0, 1), a2 + hstep, voffA);
;             PG8_WAIT_V(8); PG8_WAIT_L(0); PG8_BAR; PG8_MMA(0, 0, At, B0); PG8_MMA(0, 1, At, B1); PG8_BAR; PG8_SCHED;
	s_setprio 1
	s_waitcnt lgkmcnt(0)
	v_mfma_f32_16x16x32_bf16 v[60:63], v[156:159], v[188:191], 0
	v_mfma_f32_16x16x32_bf16 v[56:59], v[164:167], v[188:191], 0
	v_mfma_f32_16x16x32_bf16 v[48:51], v[156:159], v[196:199], 0
	v_mfma_f32_16x16x32_bf16 v[40:43], v[164:167], v[196:199], 0
	v_mfma_f32_16x16x32_bf16 v[32:35], v[156:159], v[208:211], 0
	v_mfma_f32_16x16x32_bf16 v[24:27], v[164:167], v[208:211], 0
	v_mfma_f32_16x16x32_bf16 v[16:19], v[156:159], v[216:219], 0
	v_mfma_f32_16x16x32_bf16 v[8:11], v[164:167], v[216:219], 0
	v_mfma_f32_16x16x32_bf16 v[60:63], v[160:163], v[192:195], v[60:63]
	v_mfma_f32_16x16x32_bf16 v[56:59], v[168:171], v[192:195], v[56:59]
	v_mfma_f32_16x16x32_bf16 v[48:51], v[160:163], v[200:203], v[48:51]
	v_mfma_f32_16x16x32_bf16 v[40:43], v[168:171], v[200:203], v[40:43]
	v_mfma_f32_16x16x32_bf16 v[32:35], v[160:163], v[212:215], v[32:35]
	v_mfma_f32_16x16x32_bf16 v[24:27], v[168:171], v[212:215], v[24:27]
	v_mfma_f32_16x16x32_bf16 v[16:19], v[160:163], v[220:223], v[16:19]
	v_mfma_f32_16x16x32_bf16 v[8:11], v[168:171], v[220:223], v[8:11]
	v_mfma_f32_16x16x32_bf16 v[52:55], v[172:175], v[188:191], 0
	v_mfma_f32_16x16x32_bf16 v[44:47], v[180:183], v[188:191], 0
	v_mfma_f32_16x16x32_bf16 v[36:39], v[172:175], v[196:199], 0
	v_mfma_f32_16x16x32_bf16 v[28:31], v[180:183], v[196:199], 0
	v_mfma_f32_16x16x32_bf16 v[20:23], v[172:175], v[208:211], 0
	v_mfma_f32_16x16x32_bf16 v[12:15], v[180:183], v[208:211], 0
	v_mfma_f32_16x16x32_bf16 v[4:7], v[172:175], v[216:219], 0
	v_mfma_f32_16x16x32_bf16 v[0:3], v[180:183], v[216:219], 0
	v_mfma_f32_16x16x32_bf16 v[52:55], v[176:179], v[192:195], v[52:55]
	v_mfma_f32_16x16x32_bf16 v[44:47], v[184:187], v[192:195], v[44:47]
	v_mfma_f32_16x16x32_bf16 v[36:39], v[176:179], v[200:203], v[36:39]
	v_mfma_f32_16x16x32_bf16 v[28:31], v[184:187], v[200:203], v[28:31]
	v_mfma_f32_16x16x32_bf16 v[20:23], v[176:179], v[212:215], v[20:23]
	v_mfma_f32_16x16x32_bf16 v[12:15], v[184:187], v[212:215], v[12:15]
	v_mfma_f32_16x16x32_bf16 v[4:7], v[176:179], v[220:223], v[4:7]
	v_mfma_f32_16x16x32_bf16 v[0:3], v[184:187], v[220:223], v[0:3]
	s_setprio 0
	s_barrier
	s_add_i32 s19, 0, 0x18000
	v_add_u32_e32 v150, s19, v151
	s_add_i32 s70, 0, 0x1c000
	ds_read_b128 v[156:159], v150
	ds_read_b128 v[160:163], v150 offset:1024
	ds_read_b128 v[164:167], v150 offset:2048
	ds_read_b128 v[168:171], v150 offset:3072
	v_add_u32_e32 v150, s70, v151
	ds_read_b128 v[172:175], v150
	ds_read_b128 v[176:179], v150 offset:1024
	ds_read_b128 v[180:183], v150 offset:2048
	ds_read_b128 v[184:187], v150 offset:3072
	s_add_u32 s62, s62, 0x40000
	s_addc_u32 s63, s63, 0
	s_mov_b32 m0, s57
	v_lshl_add_u64 v[226:227], s[62:63], 0, v[128:129]
	ds_read_b128 v[188:191], v148 offset:32768
	ds_read_b128 v[192:195], v148 offset:33792
	ds_read_b128 v[196:199], v148 offset:34816
	ds_read_b128 v[200:203], v148 offset:35840
	ds_read_b128 v[208:211], v148 offset:36864
	ds_read_b128 v[212:215], v148 offset:37888
	ds_read_b128 v[216:219], v148 offset:38912
	ds_read_b128 v[220:223], v148 offset:39936
	global_load_lds_dwordx4 v[226:227], off
	v_lshl_add_u64 v[226:227], s[62:63], 0, v[132:133]
	s_mov_b32 m0, s64
	s_nop 0
	global_load_lds_dwordx4 v[226:227], off
	s_waitcnt vmcnt(8)
	s_waitcnt lgkmcnt(0)
	s_barrier
	s_setprio 1
	s_waitcnt lgkmcnt(0)
	v_mfma_f32_16x16x32_bf16 v[124:127], v[156:159], v[188:191], v[124:127]
	v_mfma_f32_16x16x32_bf16 v[120:123], v[164:167], v[188:191], v[120:123]
	v_mfma_f32_16x16x32_bf16 v[112:115], v[156:159], v[196:199], v[112:115]
	v_mfma_f32_16x16x32_bf16 v[104:107], v[164:167], v[196:199], v[104:107]
	v_mfma_f32_16x16x32_bf16 v[96:99], v[156:159], v[208:211], v[96:99]
	v_mfma_f32_16x16x32_bf16 v[88:91], v[164:167], v[208:211], v[88:91]
	v_mfma_f32_16x16x32_bf16 v[80:83], v[156:159], v[216:219], v[80:83]
	v_mfma_f32_16x16x32_bf16 v[72:75], v[164:167], v[216:219], v[72:75]
	v_mfma_f32_16x16x32_bf16 v[124:127], v[160:163], v[192:195], v[124:127]
	v_mfma_f32_16x16x32_bf16 v[120:123], v[168:171], v[192:195], v[120:123]
	v_mfma_f32_16x16x32_bf16 v[112:115], v[160:163], v[200:203], v[112:115]
	v_mfma_f32_16x16x32_bf16 v[104:107], v[168:171], v[200:203], v[104:107]
	v_mfma_f32_16x16x32_bf16 v[96:99], v[160:163], v[212:215], v[96:99]
	v_mfma_f32_16x16x32_bf16 v[88:91], v[168:171], v[212:215], v[88:91]
	v_mfma_f32_16x16x32_bf16 v[80:83], v[160:163], v[220:223], v[80:83]
	v_mfma_f32_16x16x32_bf16 v[72:75], v[168:171], v[220:223], v[72:75]
	v_mfma_f32_16x16x32_bf16 v[116:119], v[172:175], v[188:191], v[116:119]
	v_mfma_f32_16x16x32_bf16 v[108:111], v[180:183], v[188:191], v[108:111]
	v_mfma_f32_16x16x32_bf16 v[100:103], v[172:175], v[196:199], v[100:103]
	v_mfma_f32_16x16x32_bf16 v[92:95], v[180:183], v[196:199], v[92:95]
	v_mfma_f32_16x16x32_bf16 v[84:87], v[172:175], v[208:211], v[84:87]
	v_mfma_f32_16x16x32_bf16 v[76:79], v[180:183], v[208:211], v[76:79]
	v_mfma_f32_16x16x32_bf16 v[68:71], v[172:175], v[216:219], v[68:71]
	v_mfma_f32_16x16x32_bf16 v[64:67], v[180:183], v[216:219], v[64:67]
	v_mfma_f32_16x16x32_bf16 v[116:119], v[176:179], v[192:195], v[116:119]
	v_mfma_f32_16x16x32_bf16 v[108:111], v[184:187], v[192:195], v[108:111]
	v_mfma_f32_16x16x32_bf16 v[100:103], v[176:179], v[200:203], v[100:103]
	v_mfma_f32_16x16x32_bf16 v[92:95], v[184:187], v[200:203], v[92:95]
	v_mfma_f32_16x16x32_bf16 v[84:87], v[176:179], v[212:215], v[84:87]
	v_mfma_f32_16x16x32_bf16 v[76:79], v[184:187], v[212:215], v[76:79]
	v_mfma_f32_16x16x32_bf16 v[68:71], v[176:179], v[220:223], v[68:71]
	v_mfma_f32_16x16x32_bf16 v[64:67], v[184:187], v[220:223], v[64:67]
	s_setprio 0
	s_barrier
; #define PG8_STAGE(bufoff, gbase, voff) do { _Pragma("unroll") for (int _i = 0; _i < 2; ++_i) \
;         __builtin_amdgcn_global_load_lds((const unsigned*)((const char*)(gbase) + (voff)[_i]), (PG8_LAS unsigned*)(lds + (bufoff) + ldsw + _i * 8192), 16, 0, 0); } while (0)
; #define PG8_LDA(dst, b, h) do { _Pragma("unroll") for (int m = 0; m < 4; ++m) _Pragma("unroll") for (int k = 0; k < 2; ++k) dst[m][k] = *(const PG8_LAS bf16x8*)(lds + PG8_SA(b, h) + aoff + m * 2048 + k * 1024); } while (0)
; #define PG8_LDB(dst, b, h) do { _Pragma("unroll") for (int n = 0; n < 2; ++n) _Pragma("unroll") for (int k = 0; k < 2; ++k) dst[n][k] = *(const PG8_LAS bf16x8*)(lds + PG8_SB(b, h) + boff + n * 2048 + k * 1024); } while (0)
; #define PG8_MMA(ai, bj, At, Bt) do { __builtin_amdgcn_s_setprio(1); _Pragma("unroll") for (int m = 0; m < 4; ++m) _Pragma("unroll") for (int n = 0; n < 2; ++n) _Pragma("unroll") for (int k = 0; k < 2; ++k) \
;         acc[ai][bj][m][n] = __builtin_amdgcn_mfma_f32_16x16x32_bf16(Bt[n][k], At[m][k], acc[ai][bj][m][n], 0, 0, 0); __builtin_amdgcn_s_setprio(0); } while (0)
; #define PG8_WAIT_V(n) asm volatile("s_waitcnt vmcnt(" #n ")" ::: "memory")
; #define PG8_BAR __builtin_amdgcn_s_barrier()
; template <class Epi, class Sched, bool ALIGN_EPI = false, bool SP2 = false>
; __device__ __forceinline__ void gemm_phase(PG8_LAS unsigned char* lds, const Gemm g, const Sched& S, const Epi& E) {
;     ...
;         for (int t = 0; t < nt; t += 2) {
;             const bool last = (t == nt - 2);
;             const char* a1 = cA + (size_t)(t + 1) * kstep;
;             const char* a2 = last ? nA : cA + (size_t)(t + 2) * kstep; const char* b2 = last ? nB : cB + (size_t)(t + 2) * kstep;
;             const char* a3 = a2 + kstep; const char* b3 = b2 + kstep;
;             if (last && has_next) S.a_ready(nxt);
;             if constexpr (SP2) {
;             PG8_LDB(B0, 0, 0); PG8_LDB(B1, 0, 1); PG8_SCHED; PG8_LDA(At, 0, 0); PG8_STAGE(PG8_SA(1, 1), a1 + hstep, voffA);
;             PG8_WAIT_V(8); PG8_WAIT_L(0); PG8_BAR; PG8_MMA(0, 0, At, B0); PG8_MMA(0, 1, At, B1); PG8_BAR; PG8_SCHED;
;     ...
;             PG8_LDA(At, 1, 1); PG8_STAGE(PG8_SB(1, 0), b3, voffB); PG8_STAGE(PG8_SB(1, 1), b3 + hstep, voffB); PG8_STAGE(PG8_SA(1, 0), a3, voffA);
;             PG8_WAIT_V(8); PG8_WAIT_L(0); PG8_BAR; PG8_MMA(1, 0, At, B0); PG8_MMA(1, 1, At, B1); PG8_BAR; PG8_SCHED;
	s_add_i32 s19, s19, s23
	v_lshl_add_u64 v[144:145], v[144:145], 0, s[8:9]
	s_mov_b32 m0, s19
	ds_read_b128 v[188:191], v148 offset:49152
	ds_read_b128 v[192:195], v148 offset:50176
	ds_read_b128 v[196:199], v148 offset:51200
	ds_read_b128 v[200:203], v148 offset:52224
	ds_read_b128 v[208:211], v148 offset:53248
	ds_read_b128 v[212:215], v148 offset:54272
	ds_read_b128 v[216:219], v148 offset:55296
	ds_read_b128 v[220:223], v148 offset:56320
	global_load_lds_dwordx4 v[144:145], off
	s_add_i32 m0, s19, 0x2000
	s_add_u32 s60, s60, 0x40080
	v_lshl_add_u64 v[144:145], v[152:153], 0, s[8:9]
	s_addc_u32 s61, s61, 0
	s_add_i32 s19, s70, s23
	global_load_lds_dwordx4 v[144:145], off
	v_lshl_add_u64 v[144:145], s[60:61], 0, v[130:131]
	s_mov_b32 m0, s19
	s_nop 0
	global_load_lds_dwordx4 v[144:145], off
	v_lshl_add_u64 v[144:145], s[60:61], 0, v[134:135]
	s_add_i32 m0, s19, 0x2000
	s_nop 0
	global_load_lds_dwordx4 v[144:145], off
	v_lshl_add_u64 v[144:145], v[204:205], 0, s[8:9]
	s_mov_b32 m0, s66
	s_nop 0
	global_load_lds_dwordx4 v[144:145], off
	v_lshl_add_u64 v[144:145], v[224:225], 0, s[8:9]
	s_mov_b32 m0, s67
	s_nop 0
	global_load_lds_dwordx4 v[144:145], off
	s_waitcnt vmcnt(8)
	s_waitcnt lgkmcnt(0)
	s_barrier
	s_setprio 1
	s_waitcnt lgkmcnt(0)
	v_mfma_f32_16x16x32_bf16 v[60:63], v[156:159], v[188:191], v[60:63]
	v_mfma_f32_16x16x32_bf16 v[56:59], v[164:167], v[188:191], v[56:59]
	v_mfma_f32_16x16x32_bf16 v[48:51], v[156:159], v[196:199], v[48:51]
	v_mfma_f32_16x16x32_bf16 v[40:43], v[164:167], v[196:199], v[40:43]
	v_mfma_f32_16x16x32_bf16 v[32:35], v[156:159], v[208:211], v[32:35]
	v_mfma_f32_16x16x32_bf16 v[24:27], v[164:167], v[208:211], v[24:27]
	v_mfma_f32_16x16x32_bf16 v[16:19], v[156:159], v[216:219], v[16:19]
	v_mfma_f32_16x16x32_bf16 v[8:11], v[164:167], v[216:219], v[8:11]
	v_mfma_f32_16x16x32_bf16 v[60:63], v[160:163], v[192:195], v[60:63]
	v_mfma_f32_16x16x32_bf16 v[56:59], v[168:171], v[192:195], v[56:59]
	v_mfma_f32_16x16x32_bf16 v[48:51], v[160:163], v[200:203], v[48:51]
	v_mfma_f32_16x16x32_bf16 v[40:43], v[168:171], v[200:203], v[40:43]
	v_mfma_f32_16x16x32_bf16 v[32:35], v[160:163], v[212:215], v[32:35]
	v_mfma_f32_16x16x32_bf16 v[24:27], v[168:171], v[212:215], v[24:27]
	v_mfma_f32_16x16x32_bf16 v[16:19], v[160:163], v[220:223], v[16:19]
	v_mfma_f32_16x16x32_bf16 v[8:11], v[168:171], v[220:223], v[8:11]
	v_mfma_f32_16x16x32_bf16 v[52:55], v[172:175], v[188:191], v[52:55]
	v_mfma_f32_16x16x32_bf16 v[44:47], v[180:183], v[188:191], v[44:47]
	v_mfma_f32_16x16x32_bf16 v[36:39], v[172:175], v[196:199], v[36:39]
	v_mfma_f32_16x16x32_bf16 v[28:31], v[180:183], v[196:199], v[28:31]
	v_mfma_f32_16x16x32_bf16 v[20:23], v[172:175], v[208:211], v[20:23]
	v_mfma_f32_16x16x32_bf16 v[12:15], v[180:183], v[208:211], v[12:15]
	v_mfma_f32_16x16x32_bf16 v[4:7], v[172:175], v[216:219], v[4:7]
	v_mfma_f32_16x16x32_bf16 v[0:3], v[180:183], v[216:219], v[0:3]
	v_mfma_f32_16x16x32_bf16 v[52:55], v[176:179], v[192:195], v[52:55]
	v_mfma_f32_16x16x32_bf16 v[44:47], v[184:187], v[192:195], v[44:47]
	v_mfma_f32_16x16x32_bf16 v[36:39], v[176:179], v[200:203], v[36:39]
	v_mfma_f32_16x16x32_bf16 v[28:31], v[184:187], v[200:203], v[28:31]
	v_mfma_f32_16x16x32_bf16 v[20:23], v[176:179], v[212:215], v[20:23]
	v_mfma_f32_16x16x32_bf16 v[12:15], v[184:187], v[212:215], v[12:15]
	v_mfma_f32_16x16x32_bf16 v[4:7], v[176:179], v[220:223], v[4:7]
	v_mfma_f32_16x16x32_bf16 v[0:3], v[184:187], v[220:223], v[0:3]
	s_setprio 0
	s_barrier
	s_add_i32 s93, s93, 2
	s_add_u32 s58, s58, 0x100
	s_addc_u32 s59, s59, 0
	s_add_u32 s91, s91, 0x100
	s_addc_u32 s92, s92, 0
	s_cmp_gt_u32 s93, 13
	s_cbranch_scc1 .Lpeel_exit_1
	.p2align	6
.LBB0_152:
	ds_read_b128 v[156:159], v146
	ds_read_b128 v[160:163], v146 offset:1024
	ds_read_b128 v[164:167], v146 offset:2048
	ds_read_b128 v[168:171], v146 offset:3072
	ds_read_b128 v[172:175], v147
	ds_read_b128 v[176:179], v147 offset:1024
	ds_read_b128 v[180:183], v147 offset:2048
	ds_read_b128 v[184:187], v147 offset:3072
	s_add_u32 s19, s58, 0xfffc0080
	s_addc_u32 s60, s59, -1
	s_cmp_eq_u32 s93, 12
	s_cselect_b32 s63, s47, s60
	s_cselect_b32 s62, s89, s19
	s_cselect_b32 s61, s41, s92
	s_cselect_b32 s60, s90, s91
	v_lshl_add_u64 v[144:145], s[58:59], 0, v[136:137]
	s_add_i32 m0, s33, 0xc000
	ds_read_b128 v[188:191], v148
	ds_read_b128 v[192:195], v148 offset:1024
	ds_read_b128 v[196:199], v148 offset:2048
	ds_read_b128 v[200:203], v148 offset:3072
	ds_read_b128 v[208:211], v148 offset:4096
	ds_read_b128 v[212:215], v148 offset:5120
	ds_read_b128 v[216:219], v148 offset:6144
	ds_read_b128 v[220:223], v148 offset:7168
	global_load_lds_dwordx4 v[144:145], off
	v_lshl_add_u64 v[144:145], s[58:59], 0, v[138:139]
	s_add_i32 m0, s33, 0xe000
	s_nop 0
	global_load_lds_dwordx4 v[144:145], off
	s_waitcnt vmcnt(8)
	s_waitcnt lgkmcnt(0)
	s_barrier
; #define PG8_STAGE(bufoff, gbase, voff) do { _Pragma("unroll") for (int _i = 0; _i < 2; ++_i) \
;         __builtin_amdgcn_global_load_lds((const unsigned*)((const char*)(gbase) + (voff)[_i]), (PG8_LAS unsigned*)(lds + (bufoff) + ldsw + _i * 8192), 16, 0, 0); } while (0)
; #define PG8_LDA(dst, b, h) do { _Pragma("unroll") for (int m = 0; m < 4; ++m) _Pragma("unroll") for (int k = 0; k < 2; ++k) dst[m][k] = *(const PG8_LAS bf16x8*)(lds + PG8_SA(b, h) + aoff + m * 2048 + k * 1024); } while (0)
; #define PG8_MMA(ai, bj, At, Bt) do { __builtin_amdgcn_s_setprio(1); _Pragma("unroll") for (int m = 0; m < 4; ++m) _Pragma("unroll") for (int n = 0; n < 2; ++n) _Pragma("unroll") for (int k = 0; k < 2; ++k) \
;         acc[ai][bj][m][n] = __builtin_amdgcn_mfma_f32_16x16x32_bf16(Bt[n][k], At[m][k], acc[ai][bj][m][n], 0, 0, 0); __builtin_amdgcn_s_setprio(0); } while (0)
; #define PG8_WAIT_V(n) asm volatile("s_waitcnt vmcnt(" #n ")" ::: "memory")
; #define PG8_WAIT_L(n) asm volatile("s_waitcnt lgkmcnt(" #n ")" ::: "memory")
; #define PG8_BAR __builtin_amdgcn_s_barrier()
; #define PG8_SCHED __builtin_amdgcn_sched_barrier(0)
; template <class Epi, class Sched, bool ALIGN_EPI = false, bool SP2 = false>
; __device__ __forceinline__ void gemm_phase(PG8_LAS unsigned char* lds, const Gemm g, const Sched& S, const Epi& E) {
;     ...
;             PG8_WAIT_V(8); PG8_WAIT_L(0); PG8_BAR; PG8_MMA(0, 0, At, B0); PG8_MMA(0, 1, At, B1); PG8_BAR; PG8_SCHED;
;             PG8_LDA(At, 0, 1); PG8_STAGE(PG8_SB(0, 0), b2, voffB); PG8_STAGE(PG8_SB(0, 1), b2 + hstep, voffB); PG8_STAGE(PG8_SA(0, 0), a2, voffA);
;             PG8_WAIT_V(8); PG8_WAIT_L(0); PG8_BAR; PG8_MMA(1, 0, At, B0); PG8_MMA(1, 1, At, B1); PG8_BAR; PG8_SCHED;
	s_setprio 1
	s_waitcnt lgkmcnt(0)
	v_mfma_f32_16x16x32_bf16 v[124:127], v[156:159], v[188:191], v[124:127]
	v_mfma_f32_16x16x32_bf16 v[120:123], v[164:167], v[188:191], v[120:123]
	v_mfma_f32_16x16x32_bf16 v[112:115], v[156:159], v[196:199], v[112:115]
	v_mfma_f32_16x16x32_bf16 v[104:107], v[164:167], v[196:199], v[104:107]
	v_mfma_f32_16x16x32_bf16 v[96:99], v[156:159], v[208:211], v[96:99]
	v_mfma_f32_16x16x32_bf16 v[88:91], v[164:167], v[208:211], v[88:91]
	v_mfma_f32_16x16x32_bf16 v[80:83], v[156:159], v[216:219], v[80:83]
	v_mfma_f32_16x16x32_bf16 v[72:75], v[164:167], v[216:219], v[72:75]
	v_mfma_f32_16x16x32_bf16 v[124:127], v[160:163], v[192:195], v[124:127]
	v_mfma_f32_16x16x32_bf16 v[120:123], v[168:171], v[192:195], v[120:123]
	v_mfma_f32_16x16x32_bf16 v[112:115], v[160:163], v[200:203], v[112:115]
	v_mfma_f32_16x16x32_bf16 v[104:107], v[168:171], v[200:203], v[104:107]
	v_mfma_f32_16x16x32_bf16 v[96:99], v[160:163], v[212:215], v[96:99]
	v_mfma_f32_16x16x32_bf16 v[88:91], v[168:171], v[212:215], v[88:91]
	v_mfma_f32_16x16x32_bf16 v[80:83], v[160:163], v[220:223], v[80:83]
	v_mfma_f32_16x16x32_bf16 v[72:75], v[168:171], v[220:223], v[72:75]
	v_mfma_f32_16x16x32_bf16 v[116:119], v[172:175], v[188:191], v[116:119]
	v_mfma_f32_16x16x32_bf16 v[108:111], v[180:183], v[188:191], v[108:111]
	v_mfma_f32_16x16x32_bf16 v[100:103], v[172:175], v[196:199], v[100:103]
	v_mfma_f32_16x16x32_bf16 v[92:95], v[180:183], v[196:199], v[92:95]
	v_mfma_f32_16x16x32_bf16 v[84:87], v[172:175], v[208:211], v[84:87]
	v_mfma_f32_16x16x32_bf16 v[76:79], v[180:183], v[208:211], v[76:79]
	v_mfma_f32_16x16x32_bf16 v[68:71], v[172:175], v[216:219], v[68:71]
	v_mfma_f32_16x16x32_bf16 v[64:67], v[180:183], v[216:219], v[64:67]
	v_mfma_f32_16x16x32_bf16 v[116:119], v[176:179], v[192:195], v[116:119]
	v_mfma_f32_16x16x32_bf16 v[108:111], v[184:187], v[192:195], v[108:111]
	v_mfma_f32_16x16x32_bf16 v[100:103], v[176:179], v[200:203], v[100:103]
	v_mfma_f32_16x16x32_bf16 v[92:95], v[184:187], v[200:203], v[92:95]
	v_mfma_f32_16x16x32_bf16 v[84:87], v[176:179], v[212:215], v[84:87]
	v_mfma_f32_16x16x32_bf16 v[76:79], v[184:187], v[212:215], v[76:79]
	v_mfma_f32_16x16x32_bf16 v[68:71], v[176:179], v[220:223], v[68:71]
	v_mfma_f32_16x16x32_bf16 v[64:67], v[184:187], v[220:223], v[64:67]
	s_setprio 0
	s_barrier
	s_add_i32 s19, s83, s23
	v_lshl_add_u64 v[144:145], s[60:61], 0, v[130:131]
	s_mov_b32 m0, s19
	ds_read_b128 v[188:191], v148 offset:16384
	ds_read_b128 v[192:195], v148 offset:17408
	ds_read_b128 v[196:199], v148 offset:18432
	ds_read_b128 v[200:203], v148 offset:19456
	ds_read_b128 v[208:211], v148 offset:20480
	ds_read_b128 v[212:215], v148 offset:21504
	ds_read_b128 v[216:219], v148 offset:22528
	ds_read_b128 v[220:223], v148 offset:23552
	global_load_lds_dwordx4 v[144:145], off
	s_add_i32 m0, s19, 0x2000
	s_add_u32 s70, s60, 0x40000
	v_lshl_add_u64 v[152:153], s[60:61], 0, v[134:135]
	s_addc_u32 s71, s61, 0
	s_add_i32 s19, s84, s23
	global_load_lds_dwordx4 v[152:153], off
	v_lshl_add_u64 v[204:205], s[70:71], 0, v[130:131]
	s_mov_b32 m0, s19
	v_lshl_add_u64 v[224:225], s[62:63], 0, v[132:133]
	global_load_lds_dwordx4 v[204:205], off
	v_lshl_add_u64 v[204:205], s[70:71], 0, v[134:135]
	s_add_i32 m0, s19, 0x2000
	s_nop 0
	global_load_lds_dwordx4 v[204:205], off
	v_lshl_add_u64 v[204:205], s[62:63], 0, v[128:129]
	s_mov_b32 m0, s33
	s_nop 0
	global_load_lds_dwordx4 v[204:205], off
	s_mov_b32 m0, s35
	s_nop 0
	global_load_lds_dwordx4 v[224:225], off
	s_waitcnt vmcnt(8)
	s_waitcnt lgkmcnt(0)
	s_barrier
	s_setprio 1
	s_waitcnt lgkmcnt(0)
	v_mfma_f32_16x16x32_bf16 v[60:63], v[156:159], v[188:191], v[60:63]
	v_mfma_f32_16x16x32_bf16 v[56:59], v[164:167], v[188:191], v[56:59]
	v_mfma_f32_16x16x32_bf16 v[48:51], v[156:159], v[196:199], v[48:51]
	v_mfma_f32_16x16x32_bf16 v[40:43], v[164:167], v[196:199], v[40:43]
	v_mfma_f32_16x16x32_bf16 v[32:35], v[156:159], v[208:211], v[32:35]
	v_mfma_f32_16x16x32_bf16 v[24:27], v[164:167], v[208:211], v[24:27]
	v_mfma_f32_16x16x32_bf16 v[16:19], v[156:159], v[216:219], v[16:19]
	v_mfma_f32_16x16x32_bf16 v[8:11], v[164:167], v[216:219], v[8:11]
	v_mfma_f32_16x16x32_bf16 v[60:63], v[160:163], v[192:195], v[60:63]
	v_mfma_f32_16x16x32_bf16 v[56:59], v[168:171], v[192:195], v[56:59]
	v_mfma_f32_16x16x32_bf16 v[48:51], v[160:163], v[200:203], v[48:51]
	v_mfma_f32_16x16x32_bf16 v[40:43], v[168:171], v[200:203], v[40:43]
	v_mfma_f32_16x16x32_bf16 v[32:35], v[160:163], v[212:215], v[32:35]
	v_mfma_f32_16x16x32_bf16 v[24:27], v[168:171], v[212:215], v[24:27]
	v_mfma_f32_16x16x32_bf16 v[16:19], v[160:163], v[220:223], v[16:19]
	v_mfma_f32_16x16x32_bf16 v[8:11], v[168:171], v[220:223], v[8:11]
	v_mfma_f32_16x16x32_bf16 v[52:55], v[172:175], v[188:191], v[52:55]
	v_mfma_f32_16x16x32_bf16 v[44:47], v[180:183], v[188:191], v[44:47]
	v_mfma_f32_16x16x32_bf16 v[36:39], v[172:175], v[196:199], v[36:39]
	v_mfma_f32_16x16x32_bf16 v[28:31], v[180:183], v[196:199], v[28:31]
	v_mfma_f32_16x16x32_bf16 v[20:23], v[172:175], v[208:211], v[20:23]
	v_mfma_f32_16x16x32_bf16 v[12:15], v[180:183], v[208:211], v[12:15]
	v_mfma_f32_16x16x32_bf16 v[4:7], v[172:175], v[216:219], v[4:7]
	v_mfma_f32_16x16x32_bf16 v[0:3], v[180:183], v[216:219], v[0:3]
	v_mfma_f32_16x16x32_bf16 v[52:55], v[176:179], v[192:195], v[52:55]
	v_mfma_f32_16x16x32_bf16 v[44:47], v[184:187], v[192:195], v[44:47]
	v_mfma_f32_16x16x32_bf16 v[36:39], v[176:179], v[200:203], v[36:39]
	v_mfma_f32_16x16x32_bf16 v[28:31], v[184:187], v[200:203], v[28:31]
	v_mfma_f32_16x16x32_bf16 v[20:23], v[176:179], v[212:215], v[20:23]
	v_mfma_f32_16x16x32_bf16 v[12:15], v[184:187], v[212:215], v[12:15]
	v_mfma_f32_16x16x32_bf16 v[4:7], v[176:179], v[220:223], v[4:7]
	v_mfma_f32_16x16x32_bf16 v[0:3], v[184:187], v[220:223], v[0:3]
	s_setprio 0
	s_barrier
; #define PG8_STAGE(bufoff, gbase, voff) do { _Pragma("unroll") for (int _i = 0; _i < 2; ++_i) \
;         __builtin_amdgcn_global_load_lds((const unsigned*)((const char*)(gbase) + (voff)[_i]), (PG8_LAS unsigned*)(lds + (bufoff) + ldsw + _i * 8192), 16, 0, 0); } while (0)
; #define PG8_LDA(dst, b, h) do { _Pragma("unroll") for (int m = 0; m < 4; ++m) _Pragma("unroll") for (int k = 0; k < 2; ++k) dst[m][k] = *(const PG8_LAS bf16x8*)(lds + PG8_SA(b, h) + aoff + m * 2048 + k * 1024); } while (0)
; #define PG8_LDB(dst, b, h) do { _Pragma("unroll") for (int n = 0; n < 2; ++n) _Pragma("unroll") for (int k = 0; k < 2; ++k) dst[n][k] = *(const PG8_LAS bf16x8*)(lds + PG8_SB(b, h) + boff + n * 2048 + k * 1024); } while (0)
; #define PG8_MMA(ai, bj, At, Bt) do { __builtin_amdgcn_s_setprio(1); _Pragma("unroll") for (int m = 0; m < 4; ++m) _Pragma("unroll") for (int n = 0; n < 2; ++n) _Pragma("unroll") for (int k = 0; k < 2; ++k) \
;         acc[ai][bj][m][n] = __builtin_amdgcn_mfma_f32_16x16x32_bf16(Bt[n][k], At[m][k], acc[ai][bj][m][n], 0, 0, 0); __builtin_amdgcn_s_setprio(0); } while (0)
; #define PG8_WAIT_V(n) asm volatile("s_waitcnt vmcnt(" #n ")" ::: "memory")
; #define PG8_WAIT_L(n) asm volatile("s_waitcnt lgkmcnt(" #n ")" ::: "memory")
; #define PG8_BAR __builtin_amdgcn_s_barrier()
; #define PG8_SCHED __builtin_amdgcn_sched_barrier(0)
; template <class Epi, class Sched, bool ALIGN_EPI = false, bool SP2 = false>
; __device__ __forceinline__ void gemm_phase(PG8_LAS unsigned char* lds, const Gemm g, const Sched& S, const Epi& E) {
;     ...
;             PG8_LDB(B0, 1, 0); PG8_LDB(B1, 1, 1); PG8_SCHED; PG8_LDA(At, 1, 0); PG8_STAGE(PG8_SA(0, 1), a2 + hstep, voffA);
;             PG8_WAIT_V(8); PG8_WAIT_L(0); PG8_BAR; PG8_MMA(0, 0, At, B0); PG8_MMA(0, 1, At, B1); PG8_BAR; PG8_SCHED;
	s_add_i32 s19, 0, 0x18000
	v_add_u32_e32 v150, s19, v151
	s_add_i32 s70, 0, 0x1c000
	ds_read_b128 v[156:159], v150
	ds_read_b128 v[160:163], v150 offset:1024
	ds_read_b128 v[164:167], v150 offset:2048
	ds_read_b128 v[168:171], v150 offset:3072
	v_add_u32_e32 v150, s70, v151
	ds_read_b128 v[172:175], v150
	ds_read_b128 v[176:179], v150 offset:1024
	ds_read_b128 v[180:183], v150 offset:2048
	ds_read_b128 v[184:187], v150 offset:3072
	s_add_u32 s62, s62, 0x40000
	s_addc_u32 s63, s63, 0
	s_mov_b32 m0, s57
	v_lshl_add_u64 v[226:227], s[62:63], 0, v[128:129]
	ds_read_b128 v[188:191], v148 offset:32768
	ds_read_b128 v[192:195], v148 offset:33792
	ds_read_b128 v[196:199], v148 offset:34816
	ds_read_b128 v[200:203], v148 offset:35840
	ds_read_b128 v[208:211], v148 offset:36864
	ds_read_b128 v[212:215], v148 offset:37888
	ds_read_b128 v[216:219], v148 offset:38912
	ds_read_b128 v[220:223], v148 offset:39936
	global_load_lds_dwordx4 v[226:227], off
	v_lshl_add_u64 v[226:227], s[62:63], 0, v[132:133]
	s_mov_b32 m0, s64
	s_nop 0
	global_load_lds_dwordx4 v[226:227], off
	s_waitcnt vmcnt(8)
	s_waitcnt lgkmcnt(0)
	s_barrier
	s_setprio 1
	s_waitcnt lgkmcnt(0)
	v_mfma_f32_16x16x32_bf16 v[124:127], v[156:159], v[188:191], v[124:127]
	v_mfma_f32_16x16x32_bf16 v[120:123], v[164:167], v[188:191], v[120:123]
	v_mfma_f32_16x16x32_bf16 v[112:115], v[156:159], v[196:199], v[112:115]
	v_mfma_f32_16x16x32_bf16 v[104:107], v[164:167], v[196:199], v[104:107]
	v_mfma_f32_16x16x32_bf16 v[96:99], v[156:159], v[208:211], v[96:99]
	v_mfma_f32_16x16x32_bf16 v[88:91], v[164:167], v[208:211], v[88:91]
	v_mfma_f32_16x16x32_bf16 v[80:83], v[156:159], v[216:219], v[80:83]
	v_mfma_f32_16x16x32_bf16 v[72:75], v[164:167], v[216:219], v[72:75]
	v_mfma_f32_16x16x32_bf16 v[124:127], v[160:163], v[192:195], v[124:127]
	v_mfma_f32_16x16x32_bf16 v[120:123], v[168:171], v[192:195], v[120:123]
	v_mfma_f32_16x16x32_bf16 v[112:115], v[160:163], v[200:203], v[112:115]
	v_mfma_f32_16x16x32_bf16 v[104:107], v[168:171], v[200:203], v[104:107]
	v_mfma_f32_16x16x32_bf16 v[96:99], v[160:163], v[212:215], v[96:99]
	v_mfma_f32_16x16x32_bf16 v[88:91], v[168:171], v[212:215], v[88:91]
	v_mfma_f32_16x16x32_bf16 v[80:83], v[160:163], v[220:223], v[80:83]
	v_mfma_f32_16x16x32_bf16 v[72:75], v[168:171], v[220:223], v[72:75]
	v_mfma_f32_16x16x32_bf16 v[116:119], v[172:175], v[188:191], v[116:119]
	v_mfma_f32_16x16x32_bf16 v[108:111], v[180:183], v[188:191], v[108:111]
	v_mfma_f32_16x16x32_bf16 v[100:103], v[172:175], v[196:199], v[100:103]
	v_mfma_f32_16x16x32_bf16 v[92:95], v[180:183], v[196:199], v[92:95]
	v_mfma_f32_16x16x32_bf16 v[84:87], v[172:175], v[208:211], v[84:87]
	v_mfma_f32_16x16x32_bf16 v[76:79], v[180:183], v[208:211], v[76:79]
	v_mfma_f32_16x16x32_bf16 v[68:71], v[172:175], v[216:219], v[68:71]
	v_mfma_f32_16x16x32_bf16 v[64:67], v[180:183], v[216:219], v[64:67]
	v_mfma_f32_16x16x32_bf16 v[116:119], v[176:179], v[192:195], v[116:119]
	v_mfma_f32_16x16x32_bf16 v[108:111], v[184:187], v[192:195], v[108:111]
	v_mfma_f32_16x16x32_bf16 v[100:103], v[176:179], v[200:203], v[100:103]
	v_mfma_f32_16x16x32_bf16 v[92:95], v[184:187], v[200:203], v[92:95]
	v_mfma_f32_16x16x32_bf16 v[84:87], v[176:179], v[212:215], v[84:87]
	v_mfma_f32_16x16x32_bf16 v[76:79], v[184:187], v[212:215], v[76:79]
	v_mfma_f32_16x16x32_bf16 v[68:71], v[176:179], v[220:223], v[68:71]
	v_mfma_f32_16x16x32_bf16 v[64:67], v[184:187], v[220:223], v[64:67]
	s_setprio 0
	s_barrier
; #define PG8_STAGE(bufoff, gbase, voff) do { _Pragma("unroll") for (int _i = 0; _i < 2; ++_i) \
;         __builtin_amdgcn_global_load_lds((const unsigned*)((const char*)(gbase) + (voff)[_i]), (PG8_LAS unsigned*)(lds + (bufoff) + ldsw + _i * 8192), 16, 0, 0); } while (0)
; #define PG8_LDA(dst, b, h) do { _Pragma("unroll") for (int m = 0; m < 4; ++m) _Pragma("unroll") for (int k = 0; k < 2; ++k) dst[m][k] = *(const PG8_LAS bf16x8*)(lds + PG8_SA(b, h) + aoff + m * 2048 + k * 1024); } while (0)
; #define PG8_MMA(ai, bj, At, Bt) do { __builtin_amdgcn_s_setprio(1); _Pragma("unroll") for (int m = 0; m < 4; ++m) _Pragma("unroll") for (int n = 0; n < 2; ++n) _Pragma("unroll") for (int k = 0; k < 2; ++k) \
;         acc[ai][bj][m][n] = __builtin_amdgcn_mfma_f32_16x16x32_bf16(Bt[n][k], At[m][k], acc[ai][bj][m][n], 0, 0, 0); __builtin_amdgcn_s_setprio(0); } while (0)
; #define PG8_WAIT_V(n) asm volatile("s_waitcnt vmcnt(" #n ")" ::: "memory")
; #define PG8_WAIT_L(n) asm volatile("s_waitcnt lgkmcnt(" #n ")" ::: "memory")
; #define PG8_BAR __builtin_amdgcn_s_barrier()
; #define PG8_SCHED __builtin_amdgcn_sched_barrier(0)
; template <class Epi, class Sched, bool ALIGN_EPI = false, bool SP2 = false>
; __device__ __forceinline__ void gemm_phase(PG8_LAS unsigned char* lds, const Gemm g, const Sched& S, const Epi& E) {
;     ...
;         for (int t = 0; t < nt; t += 2) {
;     ...
;             PG8_LDA(At, 1, 1); PG8_STAGE(PG8_SB(1, 0), b3, voffB); PG8_STAGE(PG8_SB(1, 1), b3 + hstep, voffB); PG8_STAGE(PG8_SA(1, 0), a3, voffA);
;             PG8_WAIT_V(8); PG8_WAIT_L(0); PG8_BAR; PG8_MMA(1, 0, At, B0); PG8_MMA(1, 1, At, B1); PG8_BAR; PG8_SCHED;
	s_add_i32 s19, s19, s23
	v_lshl_add_u64 v[144:145], v[144:145], 0, s[8:9]
	s_mov_b32 m0, s19
	ds_read_b128 v[188:191], v148 offset:49152
	ds_read_b128 v[192:195], v148 offset:50176
	ds_read_b128 v[196:199], v148 offset:51200
	ds_read_b128 v[200:203], v148 offset:52224
	ds_read_b128 v[208:211], v148 offset:53248
	ds_read_b128 v[212:215], v148 offset:54272
	ds_read_b128 v[216:219], v148 offset:55296
	ds_read_b128 v[220:223], v148 offset:56320
	global_load_lds_dwordx4 v[144:145], off
	s_add_i32 m0, s19, 0x2000
	s_add_u32 s60, s60, 0x40080
	v_lshl_add_u64 v[144:145], v[152:153], 0, s[8:9]
	s_addc_u32 s61, s61, 0
	s_add_i32 s19, s70, s23
	global_load_lds_dwordx4 v[144:145], off
	v_lshl_add_u64 v[144:145], s[60:61], 0, v[130:131]
	s_mov_b32 m0, s19
	s_nop 0
	global_load_lds_dwordx4 v[144:145], off
	v_lshl_add_u64 v[144:145], s[60:61], 0, v[134:135]
	s_add_i32 m0, s19, 0x2000
	s_nop 0
	global_load_lds_dwordx4 v[144:145], off
	v_lshl_add_u64 v[144:145], v[204:205], 0, s[8:9]
	s_mov_b32 m0, s66
	s_nop 0
	global_load_lds_dwordx4 v[144:145], off
	v_lshl_add_u64 v[144:145], v[224:225], 0, s[8:9]
	s_mov_b32 m0, s67
	s_nop 0
	global_load_lds_dwordx4 v[144:145], off
	s_waitcnt vmcnt(8)
	s_waitcnt lgkmcnt(0)
	s_barrier
	s_setprio 1
	s_waitcnt lgkmcnt(0)
	v_mfma_f32_16x16x32_bf16 v[60:63], v[156:159], v[188:191], v[60:63]
	v_mfma_f32_16x16x32_bf16 v[56:59], v[164:167], v[188:191], v[56:59]
	v_mfma_f32_16x16x32_bf16 v[48:51], v[156:159], v[196:199], v[48:51]
	v_mfma_f32_16x16x32_bf16 v[40:43], v[164:167], v[196:199], v[40:43]
	v_mfma_f32_16x16x32_bf16 v[32:35], v[156:159], v[208:211], v[32:35]
	v_mfma_f32_16x16x32_bf16 v[24:27], v[164:167], v[208:211], v[24:27]
	v_mfma_f32_16x16x32_bf16 v[16:19], v[156:159], v[216:219], v[16:19]
	v_mfma_f32_16x16x32_bf16 v[8:11], v[164:167], v[216:219], v[8:11]
	v_mfma_f32_16x16x32_bf16 v[60:63], v[160:163], v[192:195], v[60:63]
	v_mfma_f32_16x16x32_bf16 v[56:59], v[168:171], v[192:195], v[56:59]
	v_mfma_f32_16x16x32_bf16 v[48:51], v[160:163], v[200:203], v[48:51]
	v_mfma_f32_16x16x32_bf16 v[40:43], v[168:171], v[200:203], v[40:43]
	v_mfma_f32_16x16x32_bf16 v[32:35], v[160:163], v[212:215], v[32:35]
	v_mfma_f32_16x16x32_bf16 v[24:27], v[168:171], v[212:215], v[24:27]
	v_mfma_f32_16x16x32_bf16 v[16:19], v[160:163], v[220:223], v[16:19]
	v_mfma_f32_16x16x32_bf16 v[8:11], v[168:171], v[220:223], v[8:11]
	v_mfma_f32_16x16x32_bf16 v[52:55], v[172:175], v[188:191], v[52:55]
	v_mfma_f32_16x16x32_bf16 v[44:47], v[180:183], v[188:191], v[44:47]
	v_mfma_f32_16x16x32_bf16 v[36:39], v[172:175], v[196:199], v[36:39]
	v_mfma_f32_16x16x32_bf16 v[28:31], v[180:183], v[196:199], v[28:31]
	v_mfma_f32_16x16x32_bf16 v[20:23], v[172:175], v[208:211], v[20:23]
	v_mfma_f32_16x16x32_bf16 v[12:15], v[180:183], v[208:211], v[12:15]
	v_mfma_f32_16x16x32_bf16 v[4:7], v[172:175], v[216:219], v[4:7]
	v_mfma_f32_16x16x32_bf16 v[0:3], v[180:183], v[216:219], v[0:3]
	v_mfma_f32_16x16x32_bf16 v[52:55], v[176:179], v[192:195], v[52:55]
	v_mfma_f32_16x16x32_bf16 v[44:47], v[184:187], v[192:195], v[44:47]
	v_mfma_f32_16x16x32_bf16 v[36:39], v[176:179], v[200:203], v[36:39]
	v_mfma_f32_16x16x32_bf16 v[28:31], v[184:187], v[200:203], v[28:31]
	v_mfma_f32_16x16x32_bf16 v[20:23], v[176:179], v[212:215], v[20:23]
	v_mfma_f32_16x16x32_bf16 v[12:15], v[184:187], v[212:215], v[12:15]
	v_mfma_f32_16x16x32_bf16 v[4:7], v[176:179], v[220:223], v[4:7]
	v_mfma_f32_16x16x32_bf16 v[0:3], v[184:187], v[220:223], v[0:3]
	s_setprio 0
	s_barrier
	s_add_i32 s93, s93, 2
	s_add_u32 s58, s58, 0x100
	s_addc_u32 s59, s59, 0
	s_add_u32 s91, s91, 0x100
	s_addc_u32 s92, s92, 0
	s_cmp_gt_u32 s93, 13
	s_cbranch_scc0 .LBB0_152

; #define PG8_STAGE(bufoff, gbase, voff) do { _Pragma("unroll") for (int _i = 0; _i < 2; ++_i) \
;         __builtin_amdgcn_global_load_lds((const unsigned*)((const char*)(gbase) + (voff)[_i]), (PG8_LAS unsigned*)(lds + (bufoff) + ldsw + _i * 8192), 16, 0, 0); } while (0)
; #define PG8_LDA(dst, b, h) do { _Pragma("unroll") for (int m = 0; m < 4; ++m) _Pragma("unroll") for (int k = 0; k < 2; ++k) dst[m][k] = *(const PG8_LAS bf16x8*)(lds + PG8_SA(b, h) + aoff + m * 2048 + k * 1024); } while (0)
; #define PG8_LDB(dst, b, h) do { _Pragma("unroll") for (int n = 0; n < 2; ++n) _Pragma("unroll") for (int k = 0; k < 2; ++k) dst[n][k] = *(const PG8_LAS bf16x8*)(lds + PG8_SB(b, h) + boff + n * 2048 + k * 1024); } while (0)
; #define PG8_WAIT_V(n) asm volatile("s_waitcnt vmcnt(" #n ")" ::: "memory")
; #define PG8_WAIT_L(n) asm volatile("s_waitcnt lgkmcnt(" #n ")" ::: "memory")
; #define PG8_BAR __builtin_amdgcn_s_barrier()
; #define PG8_SCHED __builtin_amdgcn_sched_barrier(0)
; template <class Epi, class Sched, bool ALIGN_EPI = false, bool SP2 = false>
; __device__ __forceinline__ void gemm_phase(PG8_LAS unsigned char* lds, const Gemm g, const Sched& S, const Epi& E) {
;     ...
;         const bool has_next = S.next(ui + 1, nxt);
;         const char* nA = has_next ? (const char*)g.A + (size_t)nxt.pm * tstep : cA; const char* nB = has_next ? (const char*)g.Bt + (size_t)nxt.pn * tstep : cB;
;         for (int t = 0; t < nt; t += 2) {
;             const bool last = (t == nt - 2);
;             const char* a1 = cA + (size_t)(t + 1) * kstep;
;             const char* a2 = last ? nA : cA + (size_t)(t + 2) * kstep; const char* b2 = last ? nB : cB + (size_t)(t + 2) * kstep;
;             const char* a3 = a2 + kstep; const char* b3 = b2 + kstep;
;             if (last && has_next) S.a_ready(nxt);
;             if constexpr (SP2) {
;             PG8_LDB(B0, 0, 0); PG8_LDB(B1, 0, 1); PG8_SCHED; PG8_LDA(At, 0, 0); PG8_STAGE(PG8_SA(1, 1), a1 + hstep, voffA);
;             PG8_WAIT_V(8); PG8_WAIT_L(0); PG8_BAR; PG8_MMA(0, 0, At, B0); PG8_MMA(0, 1, At, B1); PG8_BAR; PG8_SCHED;
;             PG8_LDA(At, 0, 1); PG8_STAGE(PG8_SB(0, 0), b2, voffB); PG8_STAGE(PG8_SB(0, 1), b2 + hstep, voffB); PG8_STAGE(PG8_SA(0, 0), a2, voffA);
;             PG8_WAIT_V(8); PG8_WAIT_L(0); PG8_BAR; PG8_MMA(1, 0, At, B0); PG8_MMA(1, 1, At, B1); PG8_BAR; PG8_SCHED;
.LBB0_479:
	s_ashr_i32 s45, s44, 31
	s_lshl_b64 s[46:47], s[44:45], 19
	s_add_u32 s46, s40, s46
	s_addc_u32 s47, s41, s47
	s_and_b64 s[48:49], s[4:5], exec
	s_cselect_b32 s45, s47, s55
	s_cselect_b32 s51, s46, s54
	s_ashr_i32 s43, s42, 31
	s_lshl_b64 s[48:49], s[42:43], 19
	s_add_u32 s48, s72, s48
	s_addc_u32 s49, s73, s49
	s_and_b64 s[58:59], s[4:5], exec
	s_cselect_b32 s43, s49, s57
	s_cselect_b32 s67, s48, s56
	s_add_u32 s54, s54, 0x40080
	s_addc_u32 s55, s55, 0
	s_add_u32 s74, s56, 0x100
	s_addc_u32 s75, s57, 0
	s_mov_b32 s76, -2
	s_waitcnt lgkmcnt(0)
	ds_read_b128 v[128:131], v167
	ds_read_b128 v[132:135], v167 offset:1024
	ds_read_b128 v[160:163], v167 offset:2048
	ds_read_b128 v[172:175], v167 offset:3072
	ds_read_b128 v[178:181], v171
	ds_read_b128 v[184:187], v171 offset:1024
	ds_read_b128 v[188:191], v171 offset:2048
	ds_read_b128 v[192:195], v171 offset:3072
	s_add_u32 s19, s54, 0xfffc0080
	s_addc_u32 s56, s55, -1
	s_cmp_eq_u32 s76, 12
	s_cselect_b32 s59, s45, s56
	s_cselect_b32 s58, s51, s19
	s_cselect_b32 s57, s43, s75
	s_cselect_b32 s56, s67, s74
	v_lshl_add_u64 v[152:153], s[54:55], 0, v[144:145]
	s_add_i32 m0, s15, 0xc000
	ds_read_b128 v[196:199], v177
	ds_read_b128 v[200:203], v177 offset:1024
	ds_read_b128 v[208:211], v177 offset:2048
	ds_read_b128 v[212:215], v177 offset:3072
	ds_read_b128 v[216:219], v177 offset:4096
	ds_read_b128 v[220:223], v177 offset:5120
	ds_read_b128 v[224:227], v177 offset:6144
	ds_read_b128 v[228:231], v177 offset:7168
	global_load_lds_dwordx4 v[152:153], off
	v_lshl_add_u64 v[152:153], s[54:55], 0, v[146:147]
	s_add_i32 m0, s15, 0xe000
	s_nop 0
	global_load_lds_dwordx4 v[152:153], off
	s_waitcnt vmcnt(8)
	s_waitcnt lgkmcnt(0)
	s_barrier
	s_setprio 1
	s_waitcnt lgkmcnt(0)
	v_mfma_f32_16x16x32_bf16 v[124:127], v[128:131], v[196:199], 0
	v_mfma_f32_16x16x32_bf16 v[120:123], v[160:163], v[196:199], 0
	v_mfma_f32_16x16x32_bf16 v[108:111], v[128:131], v[208:211], 0
	v_mfma_f32_16x16x32_bf16 v[104:107], v[160:163], v[208:211], 0
	v_mfma_f32_16x16x32_bf16 v[92:95], v[128:131], v[216:219], 0
	v_mfma_f32_16x16x32_bf16 v[88:91], v[160:163], v[216:219], 0
	v_mfma_f32_16x16x32_bf16 v[76:79], v[128:131], v[224:227], 0
	v_mfma_f32_16x16x32_bf16 v[72:75], v[160:163], v[224:227], 0
	v_mfma_f32_16x16x32_bf16 v[124:127], v[132:135], v[200:203], v[124:127]
	v_mfma_f32_16x16x32_bf16 v[120:123], v[172:175], v[200:203], v[120:123]
	v_mfma_f32_16x16x32_bf16 v[108:111], v[132:135], v[212:215], v[108:111]
	v_mfma_f32_16x16x32_bf16 v[104:107], v[172:175], v[212:215], v[104:107]
	v_mfma_f32_16x16x32_bf16 v[92:95], v[132:135], v[220:223], v[92:95]
	v_mfma_f32_16x16x32_bf16 v[88:91], v[172:175], v[220:223], v[88:91]
	v_mfma_f32_16x16x32_bf16 v[76:79], v[132:135], v[228:231], v[76:79]
	v_mfma_f32_16x16x32_bf16 v[72:75], v[172:175], v[228:231], v[72:75]
	v_mfma_f32_16x16x32_bf16 v[116:119], v[178:181], v[196:199], 0
	v_mfma_f32_16x16x32_bf16 v[112:115], v[188:191], v[196:199], 0
	v_mfma_f32_16x16x32_bf16 v[100:103], v[178:181], v[208:211], 0
	v_mfma_f32_16x16x32_bf16 v[96:99], v[188:191], v[208:211], 0
	v_mfma_f32_16x16x32_bf16 v[84:87], v[178:181], v[216:219], 0
	v_mfma_f32_16x16x32_bf16 v[80:83], v[188:191], v[216:219], 0
	v_mfma_f32_16x16x32_bf16 v[68:71], v[178:181], v[224:227], 0
	v_mfma_f32_16x16x32_bf16 v[64:67], v[188:191], v[224:227], 0
	v_mfma_f32_16x16x32_bf16 v[116:119], v[184:187], v[200:203], v[116:119]
	v_mfma_f32_16x16x32_bf16 v[112:115], v[192:195], v[200:203], v[112:115]
	v_mfma_f32_16x16x32_bf16 v[100:103], v[184:187], v[212:215], v[100:103]
	v_mfma_f32_16x16x32_bf16 v[96:99], v[192:195], v[212:215], v[96:99]
	v_mfma_f32_16x16x32_bf16 v[84:87], v[184:187], v[220:223], v[84:87]
	v_mfma_f32_16x16x32_bf16 v[80:83], v[192:195], v[220:223], v[80:83]
	v_mfma_f32_16x16x32_bf16 v[68:71], v[184:187], v[228:231], v[68:71]
	v_mfma_f32_16x16x32_bf16 v[64:67], v[192:195], v[228:231], v[64:67]
	s_setprio 0
	s_barrier
	s_add_i32 s19, s64, s14
	v_lshl_add_u64 v[152:153], s[56:57], 0, v[138:139]
	s_mov_b32 m0, s19
	ds_read_b128 v[196:199], v177 offset:16384
	ds_read_b128 v[200:203], v177 offset:17408
	ds_read_b128 v[208:211], v177 offset:18432
	ds_read_b128 v[212:215], v177 offset:19456
	ds_read_b128 v[216:219], v177 offset:20480
	ds_read_b128 v[220:223], v177 offset:21504
	ds_read_b128 v[224:227], v177 offset:22528
	ds_read_b128 v[228:231], v177 offset:23552
	global_load_lds_dwordx4 v[152:153], off
	s_add_i32 m0, s19, 0x2000
	s_add_u32 s70, s56, 0x40000
	v_lshl_add_u64 v[156:157], s[56:57], 0, v[142:143]
	s_addc_u32 s71, s57, 0
	s_add_i32 s19, s65, s14
	global_load_lds_dwordx4 v[156:157], off
	v_lshl_add_u64 v[168:169], s[70:71], 0, v[138:139]
	s_mov_b32 m0, s19
	v_lshl_add_u64 v[204:205], s[58:59], 0, v[140:141]
	global_load_lds_dwordx4 v[168:169], off
	v_lshl_add_u64 v[168:169], s[70:71], 0, v[142:143]
	s_add_i32 m0, s19, 0x2000
	s_nop 0
	global_load_lds_dwordx4 v[168:169], off
	v_lshl_add_u64 v[168:169], s[58:59], 0, v[136:137]
	s_mov_b32 m0, s15
	s_nop 0
	global_load_lds_dwordx4 v[168:169], off
	s_mov_b32 m0, s18
	s_nop 0
	global_load_lds_dwordx4 v[204:205], off
	s_waitcnt vmcnt(8)
	s_waitcnt lgkmcnt(0)
	s_barrier
; #define PG8_STAGE(bufoff, gbase, voff) do { _Pragma("unroll") for (int _i = 0; _i < 2; ++_i) \
;         __builtin_amdgcn_global_load_lds((const unsigned*)((const char*)(gbase) + (voff)[_i]), (PG8_LAS unsigned*)(lds + (bufoff) + ldsw + _i * 8192), 16, 0, 0); } while (0)
; #define PG8_LDA(dst, b, h) do { _Pragma("unroll") for (int m = 0; m < 4; ++m) _Pragma("unroll") for (int k = 0; k < 2; ++k) dst[m][k] = *(const PG8_LAS bf16x8*)(lds + PG8_SA(b, h) + aoff + m * 2048 + k * 1024); } while (0)
; #define PG8_LDB(dst, b, h) do { _Pragma("unroll") for (int n = 0; n < 2; ++n) _Pragma("unroll") for (int k = 0; k < 2; ++k) dst[n][k] = *(const PG8_LAS bf16x8*)(lds + PG8_SB(b, h) + boff + n * 2048 + k * 1024); } while (0)
; #define PG8_MMA(ai, bj, At, Bt) do { __builtin_amdgcn_s_setprio(1); _Pragma("unroll") for (int m = 0; m < 4; ++m) _Pragma("unroll") for (int n = 0; n < 2; ++n) _Pragma("unroll") for (int k = 0; k < 2; ++k) \
;         acc[ai][bj][m][n] = __builtin_amdgcn_mfma_f32_16x16x32_bf16(Bt[n][k], At[m][k], acc[ai][bj][m][n], 0, 0, 0); __builtin_amdgcn_s_setprio(0); } while (0)
; #define PG8_WAIT_V(n) asm volatile("s_waitcnt vmcnt(" #n ")" ::: "memory")
; #define PG8_WAIT_L(n) asm volatile("s_waitcnt lgkmcnt(" #n ")" ::: "memory")
; #define PG8_BAR __builtin_amdgcn_s_barrier()
; #define PG8_SCHED __builtin_amdgcn_sched_barrier(0)
; template <class Epi, class Sched, bool ALIGN_EPI = false, bool SP2 = false>
; __device__ __forceinline__ void gemm_phase(PG8_LAS unsigned char* lds, const Gemm g, const Sched& S, const Epi& E) {
;     ...
;             PG8_WAIT_V(8); PG8_WAIT_L(0); PG8_BAR; PG8_MMA(1, 0, At, B0); PG8_MMA(1, 1, At, B1); PG8_BAR; PG8_SCHED;
;             PG8_LDB(B0, 1, 0); PG8_LDB(B1, 1, 1); PG8_SCHED; PG8_LDA(At, 1, 0); PG8_STAGE(PG8_SA(0, 1), a2 + hstep, voffA);
;             PG8_WAIT_V(8); PG8_WAIT_L(0); PG8_BAR; PG8_MMA(0, 0, At, B0); PG8_MMA(0, 1, At, B1); PG8_BAR; PG8_SCHED;
	s_setprio 1
	s_waitcnt lgkmcnt(0)
	v_mfma_f32_16x16x32_bf16 v[60:63], v[128:131], v[196:199], 0
	v_mfma_f32_16x16x32_bf16 v[56:59], v[160:163], v[196:199], 0
	v_mfma_f32_16x16x32_bf16 v[44:47], v[128:131], v[208:211], 0
	v_mfma_f32_16x16x32_bf16 v[40:43], v[160:163], v[208:211], 0
	v_mfma_f32_16x16x32_bf16 v[28:31], v[128:131], v[216:219], 0
	v_mfma_f32_16x16x32_bf16 v[24:27], v[160:163], v[216:219], 0
	v_mfma_f32_16x16x32_bf16 v[12:15], v[128:131], v[224:227], 0
	v_mfma_f32_16x16x32_bf16 v[8:11], v[160:163], v[224:227], 0
	v_mfma_f32_16x16x32_bf16 v[60:63], v[132:135], v[200:203], v[60:63]
	v_mfma_f32_16x16x32_bf16 v[56:59], v[172:175], v[200:203], v[56:59]
	v_mfma_f32_16x16x32_bf16 v[44:47], v[132:135], v[212:215], v[44:47]
	v_mfma_f32_16x16x32_bf16 v[40:43], v[172:175], v[212:215], v[40:43]
	v_mfma_f32_16x16x32_bf16 v[28:31], v[132:135], v[220:223], v[28:31]
	v_mfma_f32_16x16x32_bf16 v[24:27], v[172:175], v[220:223], v[24:27]
	v_mfma_f32_16x16x32_bf16 v[12:15], v[132:135], v[228:231], v[12:15]
	v_mfma_f32_16x16x32_bf16 v[8:11], v[172:175], v[228:231], v[8:11]
	v_mfma_f32_16x16x32_bf16 v[52:55], v[178:181], v[196:199], 0
	v_mfma_f32_16x16x32_bf16 v[48:51], v[188:191], v[196:199], 0
	v_mfma_f32_16x16x32_bf16 v[36:39], v[178:181], v[208:211], 0
	v_mfma_f32_16x16x32_bf16 v[32:35], v[188:191], v[208:211], 0
	v_mfma_f32_16x16x32_bf16 v[20:23], v[178:181], v[216:219], 0
	v_mfma_f32_16x16x32_bf16 v[16:19], v[188:191], v[216:219], 0
	v_mfma_f32_16x16x32_bf16 v[4:7], v[178:181], v[224:227], 0
	v_mfma_f32_16x16x32_bf16 v[0:3], v[188:191], v[224:227], 0
	v_mfma_f32_16x16x32_bf16 v[52:55], v[184:187], v[200:203], v[52:55]
	v_mfma_f32_16x16x32_bf16 v[48:51], v[192:195], v[200:203], v[48:51]
	v_mfma_f32_16x16x32_bf16 v[36:39], v[184:187], v[212:215], v[36:39]
	v_mfma_f32_16x16x32_bf16 v[32:35], v[192:195], v[212:215], v[32:35]
	v_mfma_f32_16x16x32_bf16 v[20:23], v[184:187], v[220:223], v[20:23]
	v_mfma_f32_16x16x32_bf16 v[16:19], v[192:195], v[220:223], v[16:19]
	v_mfma_f32_16x16x32_bf16 v[4:7], v[184:187], v[228:231], v[4:7]
	v_mfma_f32_16x16x32_bf16 v[0:3], v[192:195], v[228:231], v[0:3]
	s_setprio 0
	s_barrier
	s_add_i32 s19, 0, 0x18000
	v_add_u32_e32 v154, s19, v159
	s_add_i32 s70, 0, 0x1c000
	ds_read_b128 v[128:131], v154
	ds_read_b128 v[132:135], v154 offset:1024
	ds_read_b128 v[160:163], v154 offset:2048
	ds_read_b128 v[172:175], v154 offset:3072
	v_add_u32_e32 v154, s70, v159
	ds_read_b128 v[178:181], v154
	ds_read_b128 v[184:187], v154 offset:1024
	ds_read_b128 v[188:191], v154 offset:2048
	ds_read_b128 v[192:195], v154 offset:3072
	s_add_u32 s58, s58, 0x40000
	s_addc_u32 s59, s59, 0
	s_mov_b32 m0, s23
	v_lshl_add_u64 v[232:233], s[58:59], 0, v[136:137]
	ds_read_b128 v[196:199], v177 offset:32768
	ds_read_b128 v[200:203], v177 offset:33792
	ds_read_b128 v[208:211], v177 offset:34816
	ds_read_b128 v[212:215], v177 offset:35840
	ds_read_b128 v[216:219], v177 offset:36864
	ds_read_b128 v[220:223], v177 offset:37888
	ds_read_b128 v[224:227], v177 offset:38912
	ds_read_b128 v[228:231], v177 offset:39936
	global_load_lds_dwordx4 v[232:233], off
	v_lshl_add_u64 v[232:233], s[58:59], 0, v[140:141]
	s_mov_b32 m0, s33
	s_nop 0
	global_load_lds_dwordx4 v[232:233], off
	s_waitcnt vmcnt(8)
	s_waitcnt lgkmcnt(0)
	s_barrier
	s_setprio 1
	s_waitcnt lgkmcnt(0)
	v_mfma_f32_16x16x32_bf16 v[124:127], v[128:131], v[196:199], v[124:127]
	v_mfma_f32_16x16x32_bf16 v[120:123], v[160:163], v[196:199], v[120:123]
	v_mfma_f32_16x16x32_bf16 v[108:111], v[128:131], v[208:211], v[108:111]
	v_mfma_f32_16x16x32_bf16 v[104:107], v[160:163], v[208:211], v[104:107]
	v_mfma_f32_16x16x32_bf16 v[92:95], v[128:131], v[216:219], v[92:95]
	v_mfma_f32_16x16x32_bf16 v[88:91], v[160:163], v[216:219], v[88:91]
	v_mfma_f32_16x16x32_bf16 v[76:79], v[128:131], v[224:227], v[76:79]
	v_mfma_f32_16x16x32_bf16 v[72:75], v[160:163], v[224:227], v[72:75]
	v_mfma_f32_16x16x32_bf16 v[124:127], v[132:135], v[200:203], v[124:127]
	v_mfma_f32_16x16x32_bf16 v[120:123], v[172:175], v[200:203], v[120:123]
	v_mfma_f32_16x16x32_bf16 v[108:111], v[132:135], v[212:215], v[108:111]
	v_mfma_f32_16x16x32_bf16 v[104:107], v[172:175], v[212:215], v[104:107]
	v_mfma_f32_16x16x32_bf16 v[92:95], v[132:135], v[220:223], v[92:95]
	v_mfma_f32_16x16x32_bf16 v[88:91], v[172:175], v[220:223], v[88:91]
	v_mfma_f32_16x16x32_bf16 v[76:79], v[132:135], v[228:231], v[76:79]
	v_mfma_f32_16x16x32_bf16 v[72:75], v[172:175], v[228:231], v[72:75]
	v_mfma_f32_16x16x32_bf16 v[116:119], v[178:181], v[196:199], v[116:119]
	v_mfma_f32_16x16x32_bf16 v[112:115], v[188:191], v[196:199], v[112:115]
	v_mfma_f32_16x16x32_bf16 v[100:103], v[178:181], v[208:211], v[100:103]
	v_mfma_f32_16x16x32_bf16 v[96:99], v[188:191], v[208:211], v[96:99]
	v_mfma_f32_16x16x32_bf16 v[84:87], v[178:181], v[216:219], v[84:87]
	v_mfma_f32_16x16x32_bf16 v[80:83], v[188:191], v[216:219], v[80:83]
	v_mfma_f32_16x16x32_bf16 v[68:71], v[178:181], v[224:227], v[68:71]
	v_mfma_f32_16x16x32_bf16 v[64:67], v[188:191], v[224:227], v[64:67]
	v_mfma_f32_16x16x32_bf16 v[116:119], v[184:187], v[200:203], v[116:119]
	v_mfma_f32_16x16x32_bf16 v[112:115], v[192:195], v[200:203], v[112:115]
	v_mfma_f32_16x16x32_bf16 v[100:103], v[184:187], v[212:215], v[100:103]
	v_mfma_f32_16x16x32_bf16 v[96:99], v[192:195], v[212:215], v[96:99]
	v_mfma_f32_16x16x32_bf16 v[84:87], v[184:187], v[220:223], v[84:87]
	v_mfma_f32_16x16x32_bf16 v[80:83], v[192:195], v[220:223], v[80:83]
	v_mfma_f32_16x16x32_bf16 v[68:71], v[184:187], v[228:231], v[68:71]
	v_mfma_f32_16x16x32_bf16 v[64:67], v[192:195], v[228:231], v[64:67]
	s_setprio 0
	s_barrier
; #define PG8_STAGE(bufoff, gbase, voff) do { _Pragma("unroll") for (int _i = 0; _i < 2; ++_i) \
;         __builtin_amdgcn_global_load_lds((const unsigned*)((const char*)(gbase) + (voff)[_i]), (PG8_LAS unsigned*)(lds + (bufoff) + ldsw + _i * 8192), 16, 0, 0); } while (0)
; #define PG8_LDA(dst, b, h) do { _Pragma("unroll") for (int m = 0; m < 4; ++m) _Pragma("unroll") for (int k = 0; k < 2; ++k) dst[m][k] = *(const PG8_LAS bf16x8*)(lds + PG8_SA(b, h) + aoff + m * 2048 + k * 1024); } while (0)
; #define PG8_LDB(dst, b, h) do { _Pragma("unroll") for (int n = 0; n < 2; ++n) _Pragma("unroll") for (int k = 0; k < 2; ++k) dst[n][k] = *(const PG8_LAS bf16x8*)(lds + PG8_SB(b, h) + boff + n * 2048 + k * 1024); } while (0)
; #define PG8_MMA(ai, bj, At, Bt) do { __builtin_amdgcn_s_setprio(1); _Pragma("unroll") for (int m = 0; m < 4; ++m) _Pragma("unroll") for (int n = 0; n < 2; ++n) _Pragma("unroll") for (int k = 0; k < 2; ++k) \
;         acc[ai][bj][m][n] = __builtin_amdgcn_mfma_f32_16x16x32_bf16(Bt[n][k], At[m][k], acc[ai][bj][m][n], 0, 0, 0); __builtin_amdgcn_s_setprio(0); } while (0)
; #define PG8_WAIT_V(n) asm volatile("s_waitcnt vmcnt(" #n ")" ::: "memory")
; template <class Epi, class Sched, bool ALIGN_EPI = false, bool SP2 = false>
; __device__ __forceinline__ void gemm_phase(PG8_LAS unsigned char* lds, const Gemm g, const Sched& S, const Epi& E) {
;     ...
;             PG8_LDB(B0, 0, 0); PG8_LDB(B1, 0, 1); PG8_SCHED; PG8_LDA(At, 0, 0); PG8_STAGE(PG8_SA(1, 1), a1 + hstep, voffA);
;             PG8_WAIT_V(8); PG8_WAIT_L(0); PG8_BAR; PG8_MMA(0, 0, At, B0); PG8_MMA(0, 1, At, B1); PG8_BAR; PG8_SCHED;
;             PG8_LDA(At, 0, 1); PG8_STAGE(PG8_SB(0, 0), b2, voffB); PG8_STAGE(PG8_SB(0, 1), b2 + hstep, voffB); PG8_STAGE(PG8_SA(0, 0), a2, voffA);
;             PG8_WAIT_V(8); PG8_WAIT_L(0); PG8_BAR; PG8_MMA(1, 0, At, B0); PG8_MMA(1, 1, At, B1); PG8_BAR; PG8_SCHED;
;             PG8_LDB(B0, 1, 0); PG8_LDB(B1, 1, 1); PG8_SCHED; PG8_LDA(At, 1, 0); PG8_STAGE(PG8_SA(0, 1), a2 + hstep, voffA);
;             PG8_WAIT_V(8); PG8_WAIT_L(0); PG8_BAR; PG8_MMA(0, 0, At, B0); PG8_MMA(0, 1, At, B1); PG8_BAR; PG8_SCHED;
;             PG8_LDA(At, 1, 1); PG8_STAGE(PG8_SB(1, 0), b3, voffB); PG8_STAGE(PG8_SB(1, 1), b3 + hstep, voffB); PG8_STAGE(PG8_SA(1, 0), a3, voffA);
;             PG8_WAIT_V(8); PG8_WAIT_L(0); PG8_BAR; PG8_MMA(1, 0, At, B0); PG8_MMA(1, 1, At, B1); PG8_BAR; PG8_SCHED;
	s_add_i32 s19, s19, s14
	v_lshl_add_u64 v[152:153], v[152:153], 0, s[12:13]
	s_mov_b32 m0, s19
	ds_read_b128 v[196:199], v177 offset:49152
	ds_read_b128 v[200:203], v177 offset:50176
	ds_read_b128 v[208:211], v177 offset:51200
	ds_read_b128 v[212:215], v177 offset:52224
	ds_read_b128 v[216:219], v177 offset:53248
	ds_read_b128 v[220:223], v177 offset:54272
	ds_read_b128 v[224:227], v177 offset:55296
	ds_read_b128 v[228:231], v177 offset:56320
	global_load_lds_dwordx4 v[152:153], off
	s_add_i32 m0, s19, 0x2000
	s_add_u32 s56, s56, 0x40080
	v_lshl_add_u64 v[152:153], v[156:157], 0, s[12:13]
	s_addc_u32 s57, s57, 0
	s_add_i32 s19, s70, s14
	global_load_lds_dwordx4 v[152:153], off
	v_lshl_add_u64 v[152:153], s[56:57], 0, v[138:139]
	s_mov_b32 m0, s19
	s_nop 0
	global_load_lds_dwordx4 v[152:153], off
	v_lshl_add_u64 v[152:153], s[56:57], 0, v[142:143]
	s_add_i32 m0, s19, 0x2000
	s_nop 0
	global_load_lds_dwordx4 v[152:153], off
	v_lshl_add_u64 v[152:153], v[168:169], 0, s[12:13]
	s_mov_b32 m0, s53
	s_nop 0
	global_load_lds_dwordx4 v[152:153], off
	v_lshl_add_u64 v[152:153], v[204:205], 0, s[12:13]
	s_mov_b32 m0, s60
	s_nop 0
	global_load_lds_dwordx4 v[152:153], off
	s_waitcnt vmcnt(8)
	s_waitcnt lgkmcnt(0)
	s_barrier
	s_setprio 1
	s_waitcnt lgkmcnt(0)
	v_mfma_f32_16x16x32_bf16 v[60:63], v[128:131], v[196:199], v[60:63]
	v_mfma_f32_16x16x32_bf16 v[56:59], v[160:163], v[196:199], v[56:59]
	v_mfma_f32_16x16x32_bf16 v[44:47], v[128:131], v[208:211], v[44:47]
	v_mfma_f32_16x16x32_bf16 v[40:43], v[160:163], v[208:211], v[40:43]
	v_mfma_f32_16x16x32_bf16 v[28:31], v[128:131], v[216:219], v[28:31]
	v_mfma_f32_16x16x32_bf16 v[24:27], v[160:163], v[216:219], v[24:27]
	v_mfma_f32_16x16x32_bf16 v[12:15], v[128:131], v[224:227], v[12:15]
	v_mfma_f32_16x16x32_bf16 v[8:11], v[160:163], v[224:227], v[8:11]
	v_mfma_f32_16x16x32_bf16 v[60:63], v[132:135], v[200:203], v[60:63]
	v_mfma_f32_16x16x32_bf16 v[56:59], v[172:175], v[200:203], v[56:59]
	v_mfma_f32_16x16x32_bf16 v[44:47], v[132:135], v[212:215], v[44:47]
	v_mfma_f32_16x16x32_bf16 v[40:43], v[172:175], v[212:215], v[40:43]
	v_mfma_f32_16x16x32_bf16 v[28:31], v[132:135], v[220:223], v[28:31]
	v_mfma_f32_16x16x32_bf16 v[24:27], v[172:175], v[220:223], v[24:27]
	v_mfma_f32_16x16x32_bf16 v[12:15], v[132:135], v[228:231], v[12:15]
	v_mfma_f32_16x16x32_bf16 v[8:11], v[172:175], v[228:231], v[8:11]
	v_mfma_f32_16x16x32_bf16 v[52:55], v[178:181], v[196:199], v[52:55]
	v_mfma_f32_16x16x32_bf16 v[48:51], v[188:191], v[196:199], v[48:51]
	v_mfma_f32_16x16x32_bf16 v[36:39], v[178:181], v[208:211], v[36:39]
	v_mfma_f32_16x16x32_bf16 v[32:35], v[188:191], v[208:211], v[32:35]
	v_mfma_f32_16x16x32_bf16 v[20:23], v[178:181], v[216:219], v[20:23]
	v_mfma_f32_16x16x32_bf16 v[16:19], v[188:191], v[216:219], v[16:19]
	v_mfma_f32_16x16x32_bf16 v[4:7], v[178:181], v[224:227], v[4:7]
	v_mfma_f32_16x16x32_bf16 v[0:3], v[188:191], v[224:227], v[0:3]
	v_mfma_f32_16x16x32_bf16 v[52:55], v[184:187], v[200:203], v[52:55]
	v_mfma_f32_16x16x32_bf16 v[48:51], v[192:195], v[200:203], v[48:51]
	v_mfma_f32_16x16x32_bf16 v[36:39], v[184:187], v[212:215], v[36:39]
	v_mfma_f32_16x16x32_bf16 v[32:35], v[192:195], v[212:215], v[32:35]
	v_mfma_f32_16x16x32_bf16 v[20:23], v[184:187], v[220:223], v[20:23]
	v_mfma_f32_16x16x32_bf16 v[16:19], v[192:195], v[220:223], v[16:19]
	v_mfma_f32_16x16x32_bf16 v[4:7], v[184:187], v[228:231], v[4:7]
	v_mfma_f32_16x16x32_bf16 v[0:3], v[192:195], v[228:231], v[0:3]
	s_setprio 0
	s_barrier
	s_add_i32 s76, s76, 2
	s_add_u32 s54, s54, 0x100
	s_addc_u32 s55, s55, 0
	s_add_u32 s74, s74, 0x100
	s_addc_u32 s75, s75, 0
	s_cmp_gt_u32 s76, 13
	s_cbranch_scc1 .Lpeel_exit_2
	.p2align	6
.LBB0_480:
	ds_read_b128 v[128:131], v167
	ds_read_b128 v[132:135], v167 offset:1024
	ds_read_b128 v[160:163], v167 offset:2048
	ds_read_b128 v[172:175], v167 offset:3072
	ds_read_b128 v[178:181], v171
	ds_read_b128 v[184:187], v171 offset:1024
	ds_read_b128 v[188:191], v171 offset:2048
	ds_read_b128 v[192:195], v171 offset:3072
	s_add_u32 s19, s54, 0xfffc0080
	s_addc_u32 s56, s55, -1
	s_cmp_eq_u32 s76, 12
	s_cselect_b32 s59, s45, s56
	s_cselect_b32 s58, s51, s19
	s_cselect_b32 s57, s43, s75
	s_cselect_b32 s56, s67, s74
	v_lshl_add_u64 v[152:153], s[54:55], 0, v[144:145]
	s_add_i32 m0, s15, 0xc000
	ds_read_b128 v[196:199], v177
	ds_read_b128 v[200:203], v177 offset:1024
	ds_read_b128 v[208:211], v177 offset:2048
	ds_read_b128 v[212:215], v177 offset:3072
	ds_read_b128 v[216:219], v177 offset:4096
	ds_read_b128 v[220:223], v177 offset:5120
	ds_read_b128 v[224:227], v177 offset:6144
	ds_read_b128 v[228:231], v177 offset:7168
	global_load_lds_dwordx4 v[152:153], off
	v_lshl_add_u64 v[152:153], s[54:55], 0, v[146:147]
	s_add_i32 m0, s15, 0xe000
	s_nop 0
	global_load_lds_dwordx4 v[152:153], off
	s_waitcnt vmcnt(8)
	s_waitcnt lgkmcnt(0)
	s_barrier
; #define PG8_STAGE(bufoff, gbase, voff) do { _Pragma("unroll") for (int _i = 0; _i < 2; ++_i) \
;         __builtin_amdgcn_global_load_lds((const unsigned*)((const char*)(gbase) + (voff)[_i]), (PG8_LAS unsigned*)(lds + (bufoff) + ldsw + _i * 8192), 16, 0, 0); } while (0)
; #define PG8_LDA(dst, b, h) do { _Pragma("unroll") for (int m = 0; m < 4; ++m) _Pragma("unroll") for (int k = 0; k < 2; ++k) dst[m][k] = *(const PG8_LAS bf16x8*)(lds + PG8_SA(b, h) + aoff + m * 2048 + k * 1024); } while (0)
; #define PG8_LDB(dst, b, h) do { _Pragma("unroll") for (int n = 0; n < 2; ++n) _Pragma("unroll") for (int k = 0; k < 2; ++k) dst[n][k] = *(const PG8_LAS bf16x8*)(lds + PG8_SB(b, h) + boff + n * 2048 + k * 1024); } while (0)
; #define PG8_MMA(ai, bj, At, Bt) do { __builtin_amdgcn_s_setprio(1); _Pragma("unroll") for (int m = 0; m < 4; ++m) _Pragma("unroll") for (int n = 0; n < 2; ++n) _Pragma("unroll") for (int k = 0; k < 2; ++k) \
;         acc[ai][bj][m][n] = __builtin_amdgcn_mfma_f32_16x16x32_bf16(Bt[n][k], At[m][k], acc[ai][bj][m][n], 0, 0, 0); __builtin_amdgcn_s_setprio(0); } while (0)
; #define PG8_WAIT_V(n) asm volatile("s_waitcnt vmcnt(" #n ")" ::: "memory")
; #define PG8_WAIT_L(n) asm volatile("s_waitcnt lgkmcnt(" #n ")" ::: "memory")
; #define PG8_BAR __builtin_amdgcn_s_barrier()
; #define PG8_SCHED __builtin_amdgcn_sched_barrier(0)
; template <class Epi, class Sched, bool ALIGN_EPI = false, bool SP2 = false>
; __device__ __forceinline__ void gemm_phase(PG8_LAS unsigned char* lds, const Gemm g, const Sched& S, const Epi& E) {
;     ...
;             PG8_LDB(B0, 0, 0); PG8_LDB(B1, 0, 1); PG8_SCHED; PG8_LDA(At, 0, 0); PG8_STAGE(PG8_SA(1, 1), a1 + hstep, voffA);
;             PG8_WAIT_V(8); PG8_WAIT_L(0); PG8_BAR; PG8_MMA(0, 0, At, B0); PG8_MMA(0, 1, At, B1); PG8_BAR; PG8_SCHED;
;             PG8_LDA(At, 0, 1); PG8_STAGE(PG8_SB(0, 0), b2, voffB); PG8_STAGE(PG8_SB(0, 1), b2 + hstep, voffB); PG8_STAGE(PG8_SA(0, 0), a2, voffA);
;             PG8_WAIT_V(8); PG8_WAIT_L(0); PG8_BAR; PG8_MMA(1, 0, At, B0); PG8_MMA(1, 1, At, B1); PG8_BAR; PG8_SCHED;
	s_setprio 1
	s_waitcnt lgkmcnt(0)
	v_mfma_f32_16x16x32_bf16 v[124:127], v[128:131], v[196:199], v[124:127]
	v_mfma_f32_16x16x32_bf16 v[120:123], v[160:163], v[196:199], v[120:123]
	v_mfma_f32_16x16x32_bf16 v[108:111], v[128:131], v[208:211], v[108:111]
	v_mfma_f32_16x16x32_bf16 v[104:107], v[160:163], v[208:211], v[104:107]
	v_mfma_f32_16x16x32_bf16 v[92:95], v[128:131], v[216:219], v[92:95]
	v_mfma_f32_16x16x32_bf16 v[88:91], v[160:163], v[216:219], v[88:91]
	v_mfma_f32_16x16x32_bf16 v[76:79], v[128:131], v[224:227], v[76:79]
	v_mfma_f32_16x16x32_bf16 v[72:75], v[160:163], v[224:227], v[72:75]
	v_mfma_f32_16x16x32_bf16 v[124:127], v[132:135], v[200:203], v[124:127]
	v_mfma_f32_16x16x32_bf16 v[120:123], v[172:175], v[200:203], v[120:123]
	v_mfma_f32_16x16x32_bf16 v[108:111], v[132:135], v[212:215], v[108:111]
	v_mfma_f32_16x16x32_bf16 v[104:107], v[172:175], v[212:215], v[104:107]
	v_mfma_f32_16x16x32_bf16 v[92:95], v[132:135], v[220:223], v[92:95]
	v_mfma_f32_16x16x32_bf16 v[88:91], v[172:175], v[220:223], v[88:91]
	v_mfma_f32_16x16x32_bf16 v[76:79], v[132:135], v[228:231], v[76:79]
	v_mfma_f32_16x16x32_bf16 v[72:75], v[172:175], v[228:231], v[72:75]
	v_mfma_f32_16x16x32_bf16 v[116:119], v[178:181], v[196:199], v[116:119]
	v_mfma_f32_16x16x32_bf16 v[112:115], v[188:191], v[196:199], v[112:115]
	v_mfma_f32_16x16x32_bf16 v[100:103], v[178:181], v[208:211], v[100:103]
	v_mfma_f32_16x16x32_bf16 v[96:99], v[188:191], v[208:211], v[96:99]
	v_mfma_f32_16x16x32_bf16 v[84:87], v[178:181], v[216:219], v[84:87]
	v_mfma_f32_16x16x32_bf16 v[80:83], v[188:191], v[216:219], v[80:83]
	v_mfma_f32_16x16x32_bf16 v[68:71], v[178:181], v[224:227], v[68:71]
	v_mfma_f32_16x16x32_bf16 v[64:67], v[188:191], v[224:227], v[64:67]
	v_mfma_f32_16x16x32_bf16 v[116:119], v[184:187], v[200:203], v[116:119]
	v_mfma_f32_16x16x32_bf16 v[112:115], v[192:195], v[200:203], v[112:115]
	v_mfma_f32_16x16x32_bf16 v[100:103], v[184:187], v[212:215], v[100:103]
	v_mfma_f32_16x16x32_bf16 v[96:99], v[192:195], v[212:215], v[96:99]
	v_mfma_f32_16x16x32_bf16 v[84:87], v[184:187], v[220:223], v[84:87]
	v_mfma_f32_16x16x32_bf16 v[80:83], v[192:195], v[220:223], v[80:83]
	v_mfma_f32_16x16x32_bf16 v[68:71], v[184:187], v[228:231], v[68:71]
	v_mfma_f32_16x16x32_bf16 v[64:67], v[192:195], v[228:231], v[64:67]
	s_setprio 0
	s_barrier
	s_add_i32 s19, s64, s14
	v_lshl_add_u64 v[152:153], s[56:57], 0, v[138:139]
	s_mov_b32 m0, s19
	ds_read_b128 v[196:199], v177 offset:16384
	ds_read_b128 v[200:203], v177 offset:17408
	ds_read_b128 v[208:211], v177 offset:18432
	ds_read_b128 v[212:215], v177 offset:19456
	ds_read_b128 v[216:219], v177 offset:20480
	ds_read_b128 v[220:223], v177 offset:21504
	ds_read_b128 v[224:227], v177 offset:22528
	ds_read_b128 v[228:231], v177 offset:23552
	global_load_lds_dwordx4 v[152:153], off
	s_add_i32 m0, s19, 0x2000
	s_add_u32 s70, s56, 0x40000
	v_lshl_add_u64 v[156:157], s[56:57], 0, v[142:143]
	s_addc_u32 s71, s57, 0
	s_add_i32 s19, s65, s14
	global_load_lds_dwordx4 v[156:157], off
	v_lshl_add_u64 v[168:169], s[70:71], 0, v[138:139]
	s_mov_b32 m0, s19
	v_lshl_add_u64 v[204:205], s[58:59], 0, v[140:141]
	global_load_lds_dwordx4 v[168:169], off
	v_lshl_add_u64 v[168:169], s[70:71], 0, v[142:143]
	s_add_i32 m0, s19, 0x2000
	s_nop 0
	global_load_lds_dwordx4 v[168:169], off
	v_lshl_add_u64 v[168:169], s[58:59], 0, v[136:137]
	s_mov_b32 m0, s15
	s_nop 0
	global_load_lds_dwordx4 v[168:169], off
	s_mov_b32 m0, s18
	s_nop 0
	global_load_lds_dwordx4 v[204:205], off
	s_waitcnt vmcnt(8)
	s_waitcnt lgkmcnt(0)
	s_barrier
	s_setprio 1
	s_waitcnt lgkmcnt(0)
	v_mfma_f32_16x16x32_bf16 v[60:63], v[128:131], v[196:199], v[60:63]
	v_mfma_f32_16x16x32_bf16 v[56:59], v[160:163], v[196:199], v[56:59]
	v_mfma_f32_16x16x32_bf16 v[44:47], v[128:131], v[208:211], v[44:47]
	v_mfma_f32_16x16x32_bf16 v[40:43], v[160:163], v[208:211], v[40:43]
	v_mfma_f32_16x16x32_bf16 v[28:31], v[128:131], v[216:219], v[28:31]
	v_mfma_f32_16x16x32_bf16 v[24:27], v[160:163], v[216:219], v[24:27]
	v_mfma_f32_16x16x32_bf16 v[12:15], v[128:131], v[224:227], v[12:15]
	v_mfma_f32_16x16x32_bf16 v[8:11], v[160:163], v[224:227], v[8:11]
	v_mfma_f32_16x16x32_bf16 v[60:63], v[132:135], v[200:203], v[60:63]
	v_mfma_f32_16x16x32_bf16 v[56:59], v[172:175], v[200:203], v[56:59]
	v_mfma_f32_16x16x32_bf16 v[44:47], v[132:135], v[212:215], v[44:47]
	v_mfma_f32_16x16x32_bf16 v[40:43], v[172:175], v[212:215], v[40:43]
	v_mfma_f32_16x16x32_bf16 v[28:31], v[132:135], v[220:223], v[28:31]
	v_mfma_f32_16x16x32_bf16 v[24:27], v[172:175], v[220:223], v[24:27]
	v_mfma_f32_16x16x32_bf16 v[12:15], v[132:135], v[228:231], v[12:15]
	v_mfma_f32_16x16x32_bf16 v[8:11], v[172:175], v[228:231], v[8:11]
	v_mfma_f32_16x16x32_bf16 v[52:55], v[178:181], v[196:199], v[52:55]
	v_mfma_f32_16x16x32_bf16 v[48:51], v[188:191], v[196:199], v[48:51]
	v_mfma_f32_16x16x32_bf16 v[36:39], v[178:181], v[208:211], v[36:39]
	v_mfma_f32_16x16x32_bf16 v[32:35], v[188:191], v[208:211], v[32:35]
	v_mfma_f32_16x16x32_bf16 v[20:23], v[178:181], v[216:219], v[20:23]
	v_mfma_f32_16x16x32_bf16 v[16:19], v[188:191], v[216:219], v[16:19]
	v_mfma_f32_16x16x32_bf16 v[4:7], v[178:181], v[224:227], v[4:7]
	v_mfma_f32_16x16x32_bf16 v[0:3], v[188:191], v[224:227], v[0:3]
	v_mfma_f32_16x16x32_bf16 v[52:55], v[184:187], v[200:203], v[52:55]
	v_mfma_f32_16x16x32_bf16 v[48:51], v[192:195], v[200:203], v[48:51]
	v_mfma_f32_16x16x32_bf16 v[36:39], v[184:187], v[212:215], v[36:39]
	v_mfma_f32_16x16x32_bf16 v[32:35], v[192:195], v[212:215], v[32:35]
	v_mfma_f32_16x16x32_bf16 v[20:23], v[184:187], v[220:223], v[20:23]
	v_mfma_f32_16x16x32_bf16 v[16:19], v[192:195], v[220:223], v[16:19]
	v_mfma_f32_16x16x32_bf16 v[4:7], v[184:187], v[228:231], v[4:7]
	v_mfma_f32_16x16x32_bf16 v[0:3], v[192:195], v[228:231], v[0:3]
	s_setprio 0
	s_barrier
; #define PG8_STAGE(bufoff, gbase, voff) do { _Pragma("unroll") for (int _i = 0; _i < 2; ++_i) \
;         __builtin_amdgcn_global_load_lds((const unsigned*)((const char*)(gbase) + (voff)[_i]), (PG8_LAS unsigned*)(lds + (bufoff) + ldsw + _i * 8192), 16, 0, 0); } while (0)
; #define PG8_LDA(dst, b, h) do { _Pragma("unroll") for (int m = 0; m < 4; ++m) _Pragma("unroll") for (int k = 0; k < 2; ++k) dst[m][k] = *(const PG8_LAS bf16x8*)(lds + PG8_SA(b, h) + aoff + m * 2048 + k * 1024); } while (0)
; #define PG8_LDB(dst, b, h) do { _Pragma("unroll") for (int n = 0; n < 2; ++n) _Pragma("unroll") for (int k = 0; k < 2; ++k) dst[n][k] = *(const PG8_LAS bf16x8*)(lds + PG8_SB(b, h) + boff + n * 2048 + k * 1024); } while (0)
; #define PG8_MMA(ai, bj, At, Bt) do { __builtin_amdgcn_s_setprio(1); _Pragma("unroll") for (int m = 0; m < 4; ++m) _Pragma("unroll") for (int n = 0; n < 2; ++n) _Pragma("unroll") for (int k = 0; k < 2; ++k) \
;         acc[ai][bj][m][n] = __builtin_amdgcn_mfma_f32_16x16x32_bf16(Bt[n][k], At[m][k], acc[ai][bj][m][n], 0, 0, 0); __builtin_amdgcn_s_setprio(0); } while (0)
; #define PG8_WAIT_V(n) asm volatile("s_waitcnt vmcnt(" #n ")" ::: "memory")
; #define PG8_WAIT_L(n) asm volatile("s_waitcnt lgkmcnt(" #n ")" ::: "memory")
; #define PG8_BAR __builtin_amdgcn_s_barrier()
; #define PG8_SCHED __builtin_amdgcn_sched_barrier(0)
; template <class Epi, class Sched, bool ALIGN_EPI = false, bool SP2 = false>
; __device__ __forceinline__ void gemm_phase(PG8_LAS unsigned char* lds, const Gemm g, const Sched& S, const Epi& E) {
;     ...
;             PG8_LDB(B0, 1, 0); PG8_LDB(B1, 1, 1); PG8_SCHED; PG8_LDA(At, 1, 0); PG8_STAGE(PG8_SA(0, 1), a2 + hstep, voffA);
;             PG8_WAIT_V(8); PG8_WAIT_L(0); PG8_BAR; PG8_MMA(0, 0, At, B0); PG8_MMA(0, 1, At, B1); PG8_BAR; PG8_SCHED;
	s_add_i32 s19, 0, 0x18000
	v_add_u32_e32 v154, s19, v159
	s_add_i32 s70, 0, 0x1c000
	ds_read_b128 v[128:131], v154
	ds_read_b128 v[132:135], v154 offset:1024
	ds_read_b128 v[160:163], v154 offset:2048
	ds_read_b128 v[172:175], v154 offset:3072
	v_add_u32_e32 v154, s70, v159
	ds_read_b128 v[178:181], v154
	ds_read_b128 v[184:187], v154 offset:1024
	ds_read_b128 v[188:191], v154 offset:2048
	ds_read_b128 v[192:195], v154 offset:3072
	s_add_u32 s58, s58, 0x40000
	s_addc_u32 s59, s59, 0
	s_mov_b32 m0, s23
	v_lshl_add_u64 v[232:233], s[58:59], 0, v[136:137]
	ds_read_b128 v[196:199], v177 offset:32768
	ds_read_b128 v[200:203], v177 offset:33792
	ds_read_b128 v[208:211], v177 offset:34816
	ds_read_b128 v[212:215], v177 offset:35840
	ds_read_b128 v[216:219], v177 offset:36864
	ds_read_b128 v[220:223], v177 offset:37888
	ds_read_b128 v[224:227], v177 offset:38912
	ds_read_b128 v[228:231], v177 offset:39936
	global_load_lds_dwordx4 v[232:233], off
	v_lshl_add_u64 v[232:233], s[58:59], 0, v[140:141]
	s_mov_b32 m0, s33
	s_nop 0
	global_load_lds_dwordx4 v[232:233], off
	s_waitcnt vmcnt(8)
	s_waitcnt lgkmcnt(0)
	s_barrier
	s_setprio 1
	s_waitcnt lgkmcnt(0)
	v_mfma_f32_16x16x32_bf16 v[124:127], v[128:131], v[196:199], v[124:127]
	v_mfma_f32_16x16x32_bf16 v[120:123], v[160:163], v[196:199], v[120:123]
	v_mfma_f32_16x16x32_bf16 v[108:111], v[128:131], v[208:211], v[108:111]
	v_mfma_f32_16x16x32_bf16 v[104:107], v[160:163], v[208:211], v[104:107]
	v_mfma_f32_16x16x32_bf16 v[92:95], v[128:131], v[216:219], v[92:95]
	v_mfma_f32_16x16x32_bf16 v[88:91], v[160:163], v[216:219], v[88:91]
	v_mfma_f32_16x16x32_bf16 v[76:79], v[128:131], v[224:227], v[76:79]
	v_mfma_f32_16x16x32_bf16 v[72:75], v[160:163], v[224:227], v[72:75]
	v_mfma_f32_16x16x32_bf16 v[124:127], v[132:135], v[200:203], v[124:127]
	v_mfma_f32_16x16x32_bf16 v[120:123], v[172:175], v[200:203], v[120:123]
	v_mfma_f32_16x16x32_bf16 v[108:111], v[132:135], v[212:215], v[108:111]
	v_mfma_f32_16x16x32_bf16 v[104:107], v[172:175], v[212:215], v[104:107]
	v_mfma_f32_16x16x32_bf16 v[92:95], v[132:135], v[220:223], v[92:95]
	v_mfma_f32_16x16x32_bf16 v[88:91], v[172:175], v[220:223], v[88:91]
	v_mfma_f32_16x16x32_bf16 v[76:79], v[132:135], v[228:231], v[76:79]
	v_mfma_f32_16x16x32_bf16 v[72:75], v[172:175], v[228:231], v[72:75]
	v_mfma_f32_16x16x32_bf16 v[116:119], v[178:181], v[196:199], v[116:119]
	v_mfma_f32_16x16x32_bf16 v[112:115], v[188:191], v[196:199], v[112:115]
	v_mfma_f32_16x16x32_bf16 v[100:103], v[178:181], v[208:211], v[100:103]
	v_mfma_f32_16x16x32_bf16 v[96:99], v[188:191], v[208:211], v[96:99]
	v_mfma_f32_16x16x32_bf16 v[84:87], v[178:181], v[216:219], v[84:87]
	v_mfma_f32_16x16x32_bf16 v[80:83], v[188:191], v[216:219], v[80:83]
	v_mfma_f32_16x16x32_bf16 v[68:71], v[178:181], v[224:227], v[68:71]
	v_mfma_f32_16x16x32_bf16 v[64:67], v[188:191], v[224:227], v[64:67]
	v_mfma_f32_16x16x32_bf16 v[116:119], v[184:187], v[200:203], v[116:119]
	v_mfma_f32_16x16x32_bf16 v[112:115], v[192:195], v[200:203], v[112:115]
	v_mfma_f32_16x16x32_bf16 v[100:103], v[184:187], v[212:215], v[100:103]
	v_mfma_f32_16x16x32_bf16 v[96:99], v[192:195], v[212:215], v[96:99]
	v_mfma_f32_16x16x32_bf16 v[84:87], v[184:187], v[220:223], v[84:87]
	v_mfma_f32_16x16x32_bf16 v[80:83], v[192:195], v[220:223], v[80:83]
	v_mfma_f32_16x16x32_bf16 v[68:71], v[184:187], v[228:231], v[68:71]
	v_mfma_f32_16x16x32_bf16 v[64:67], v[192:195], v[228:231], v[64:67]
	s_setprio 0
	s_barrier
; #define PG8_STAGE(bufoff, gbase, voff) do { _Pragma("unroll") for (int _i = 0; _i < 2; ++_i) \
;         __builtin_amdgcn_global_load_lds((const unsigned*)((const char*)(gbase) + (voff)[_i]), (PG8_LAS unsigned*)(lds + (bufoff) + ldsw + _i * 8192), 16, 0, 0); } while (0)
; #define PG8_LDA(dst, b, h) do { _Pragma("unroll") for (int m = 0; m < 4; ++m) _Pragma("unroll") for (int k = 0; k < 2; ++k) dst[m][k] = *(const PG8_LAS bf16x8*)(lds + PG8_SA(b, h) + aoff + m * 2048 + k * 1024); } while (0)
; #define PG8_MMA(ai, bj, At, Bt) do { __builtin_amdgcn_s_setprio(1); _Pragma("unroll") for (int m = 0; m < 4; ++m) _Pragma("unroll") for (int n = 0; n < 2; ++n) _Pragma("unroll") for (int k = 0; k < 2; ++k) \
;         acc[ai][bj][m][n] = __builtin_amdgcn_mfma_f32_16x16x32_bf16(Bt[n][k], At[m][k], acc[ai][bj][m][n], 0, 0, 0); __builtin_amdgcn_s_setprio(0); } while (0)
; #define PG8_WAIT_V(n) asm volatile("s_waitcnt vmcnt(" #n ")" ::: "memory")
; #define PG8_WAIT_L(n) asm volatile("s_waitcnt lgkmcnt(" #n ")" ::: "memory")
; #define PG8_BAR __builtin_amdgcn_s_barrier()
; #define PG8_SCHED __builtin_amdgcn_sched_barrier(0)
; template <class Epi, class Sched, bool ALIGN_EPI = false, bool SP2 = false>
; __device__ __forceinline__ void gemm_phase(PG8_LAS unsigned char* lds, const Gemm g, const Sched& S, const Epi& E) {
;     ...
;             PG8_LDA(At, 1, 1); PG8_STAGE(PG8_SB(1, 0), b3, voffB); PG8_STAGE(PG8_SB(1, 1), b3 + hstep, voffB); PG8_STAGE(PG8_SA(1, 0), a3, voffA);
;             PG8_WAIT_V(8); PG8_WAIT_L(0); PG8_BAR; PG8_MMA(1, 0, At, B0); PG8_MMA(1, 1, At, B1); PG8_BAR; PG8_SCHED;
	s_add_i32 s19, s19, s14
	v_lshl_add_u64 v[152:153], v[152:153], 0, s[12:13]
	s_mov_b32 m0, s19
	ds_read_b128 v[196:199], v177 offset:49152
	ds_read_b128 v[200:203], v177 offset:50176
	ds_read_b128 v[208:211], v177 offset:51200
	ds_read_b128 v[212:215], v177 offset:52224
	ds_read_b128 v[216:219], v177 offset:53248
	ds_read_b128 v[220:223], v177 offset:54272
	ds_read_b128 v[224:227], v177 offset:55296
	ds_read_b128 v[228:231], v177 offset:56320
	global_load_lds_dwordx4 v[152:153], off
	s_add_i32 m0, s19, 0x2000
	s_add_u32 s56, s56, 0x40080
	v_lshl_add_u64 v[152:153], v[156:157], 0, s[12:13]
	s_addc_u32 s57, s57, 0
	s_add_i32 s19, s70, s14
	global_load_lds_dwordx4 v[152:153], off
	v_lshl_add_u64 v[152:153], s[56:57], 0, v[138:139]
	s_mov_b32 m0, s19
	s_nop 0
	global_load_lds_dwordx4 v[152:153], off
	v_lshl_add_u64 v[152:153], s[56:57], 0, v[142:143]
	s_add_i32 m0, s19, 0x2000
	s_nop 0
	global_load_lds_dwordx4 v[152:153], off
	v_lshl_add_u64 v[152:153], v[168:169], 0, s[12:13]
	s_mov_b32 m0, s53
	s_nop 0
	global_load_lds_dwordx4 v[152:153], off
	v_lshl_add_u64 v[152:153], v[204:205], 0, s[12:13]
	s_mov_b32 m0, s60
	s_nop 0
	global_load_lds_dwordx4 v[152:153], off
	s_waitcnt vmcnt(8)
	s_waitcnt lgkmcnt(0)
	s_barrier
	s_setprio 1
	s_waitcnt lgkmcnt(0)
	v_mfma_f32_16x16x32_bf16 v[60:63], v[128:131], v[196:199], v[60:63]
	v_mfma_f32_16x16x32_bf16 v[56:59], v[160:163], v[196:199], v[56:59]
	v_mfma_f32_16x16x32_bf16 v[44:47], v[128:131], v[208:211], v[44:47]
	v_mfma_f32_16x16x32_bf16 v[40:43], v[160:163], v[208:211], v[40:43]
	v_mfma_f32_16x16x32_bf16 v[28:31], v[128:131], v[216:219], v[28:31]
	v_mfma_f32_16x16x32_bf16 v[24:27], v[160:163], v[216:219], v[24:27]
	v_mfma_f32_16x16x32_bf16 v[12:15], v[128:131], v[224:227], v[12:15]
	v_mfma_f32_16x16x32_bf16 v[8:11], v[160:163], v[224:227], v[8:11]
	v_mfma_f32_16x16x32_bf16 v[60:63], v[132:135], v[200:203], v[60:63]
	v_mfma_f32_16x16x32_bf16 v[56:59], v[172:175], v[200:203], v[56:59]
	v_mfma_f32_16x16x32_bf16 v[44:47], v[132:135], v[212:215], v[44:47]
	v_mfma_f32_16x16x32_bf16 v[40:43], v[172:175], v[212:215], v[40:43]
	v_mfma_f32_16x16x32_bf16 v[28:31], v[132:135], v[220:223], v[28:31]
	v_mfma_f32_16x16x32_bf16 v[24:27], v[172:175], v[220:223], v[24:27]
	v_mfma_f32_16x16x32_bf16 v[12:15], v[132:135], v[228:231], v[12:15]
	v_mfma_f32_16x16x32_bf16 v[8:11], v[172:175], v[228:231], v[8:11]
	v_mfma_f32_16x16x32_bf16 v[52:55], v[178:181], v[196:199], v[52:55]
	v_mfma_f32_16x16x32_bf16 v[48:51], v[188:191], v[196:199], v[48:51]
	v_mfma_f32_16x16x32_bf16 v[36:39], v[178:181], v[208:211], v[36:39]
	v_mfma_f32_16x16x32_bf16 v[32:35], v[188:191], v[208:211], v[32:35]
	v_mfma_f32_16x16x32_bf16 v[20:23], v[178:181], v[216:219], v[20:23]
	v_mfma_f32_16x16x32_bf16 v[16:19], v[188:191], v[216:219], v[16:19]
	v_mfma_f32_16x16x32_bf16 v[4:7], v[178:181], v[224:227], v[4:7]
	v_mfma_f32_16x16x32_bf16 v[0:3], v[188:191], v[224:227], v[0:3]
	v_mfma_f32_16x16x32_bf16 v[52:55], v[184:187], v[200:203], v[52:55]
	v_mfma_f32_16x16x32_bf16 v[48:51], v[192:195], v[200:203], v[48:51]
	v_mfma_f32_16x16x32_bf16 v[36:39], v[184:187], v[212:215], v[36:39]
	v_mfma_f32_16x16x32_bf16 v[32:35], v[192:195], v[212:215], v[32:35]
	v_mfma_f32_16x16x32_bf16 v[20:23], v[184:187], v[220:223], v[20:23]
	v_mfma_f32_16x16x32_bf16 v[16:19], v[192:195], v[220:223], v[16:19]
	v_mfma_f32_16x16x32_bf16 v[4:7], v[184:187], v[228:231], v[4:7]
	v_mfma_f32_16x16x32_bf16 v[0:3], v[192:195], v[228:231], v[0:3]
	s_setprio 0
	s_barrier
	s_add_i32 s76, s76, 2
	s_add_u32 s54, s54, 0x100
	s_addc_u32 s55, s55, 0
	s_add_u32 s74, s74, 0x100
	s_addc_u32 s75, s75, 0
	s_cmp_gt_u32 s76, 13
	s_cbranch_scc0 .LBB0_480

; #define PG8_STAGE(bufoff, gbase, voff) do { _Pragma("unroll") for (int _i = 0; _i < 2; ++_i) \
;         __builtin_amdgcn_global_load_lds((const unsigned*)((const char*)(gbase) + (voff)[_i]), (PG8_LAS unsigned*)(lds + (bufoff) + ldsw + _i * 8192), 16, 0, 0); } while (0)
; #define PG8_LDA(dst, b, h) do { _Pragma("unroll") for (int m = 0; m < 4; ++m) _Pragma("unroll") for (int k = 0; k < 2; ++k) dst[m][k] = *(const PG8_LAS bf16x8*)(lds + PG8_SA(b, h) + aoff + m * 2048 + k * 1024); } while (0)
; #define PG8_LDB(dst, b, h) do { _Pragma("unroll") for (int n = 0; n < 2; ++n) _Pragma("unroll") for (int k = 0; k < 2; ++k) dst[n][k] = *(const PG8_LAS bf16x8*)(lds + PG8_SB(b, h) + boff + n * 2048 + k * 1024); } while (0)
; #define PG8_WAIT_V(n) asm volatile("s_waitcnt vmcnt(" #n ")" ::: "memory")
; #define PG8_WAIT_L(n) asm volatile("s_waitcnt lgkmcnt(" #n ")" ::: "memory")
; #define PG8_BAR __builtin_amdgcn_s_barrier()
; #define PG8_SCHED __builtin_amdgcn_sched_barrier(0)
; template <class Epi, class Sched, bool ALIGN_EPI = false, bool SP2 = false>
; __device__ __forceinline__ void gemm_phase(PG8_LAS unsigned char* lds, const Gemm g, const Sched& S, const Epi& E) {
;     ...
;         const bool has_next = S.next(ui + 1, nxt);
;         const char* nA = has_next ? (const char*)g.A + (size_t)nxt.pm * tstep : cA; const char* nB = has_next ? (const char*)g.Bt + (size_t)nxt.pn * tstep : cB;
;         for (int t = 0; t < nt; t += 2) {
;             const bool last = (t == nt - 2);
;             const char* a1 = cA + (size_t)(t + 1) * kstep;
;             const char* a2 = last ? nA : cA + (size_t)(t + 2) * kstep; const char* b2 = last ? nB : cB + (size_t)(t + 2) * kstep;
;             const char* a3 = a2 + kstep; const char* b3 = b2 + kstep;
;             if (last && has_next) S.a_ready(nxt);
;             if constexpr (SP2) {
;             PG8_LDB(B0, 0, 0); PG8_LDB(B1, 0, 1); PG8_SCHED; PG8_LDA(At, 0, 0); PG8_STAGE(PG8_SA(1, 1), a1 + hstep, voffA);
;             PG8_WAIT_V(8); PG8_WAIT_L(0); PG8_BAR; PG8_MMA(0, 0, At, B0); PG8_MMA(0, 1, At, B1); PG8_BAR; PG8_SCHED;
;             PG8_LDA(At, 0, 1); PG8_STAGE(PG8_SB(0, 0), b2, voffB); PG8_STAGE(PG8_SB(0, 1), b2 + hstep, voffB); PG8_STAGE(PG8_SA(0, 0), a2, voffA);
;             PG8_WAIT_V(8); PG8_WAIT_L(0); PG8_BAR; PG8_MMA(1, 0, At, B0); PG8_MMA(1, 1, At, B1); PG8_BAR; PG8_SCHED;
.LBB0_566:
	s_ashr_i32 s17, s16, 31
	s_lshl_b64 s[40:41], s[16:17], 19
	s_add_u32 s40, s36, s40
	s_addc_u32 s41, s37, s41
	s_and_b64 s[42:43], s[2:3], exec
	s_cselect_b32 s62, s41, s1
	s_cselect_b32 s63, s40, s0
	s_ashr_i32 s13, s12, 31
	s_lshl_b64 s[42:43], s[12:13], 19
	s_add_u32 s42, s20, s42
	s_addc_u32 s43, s21, s43
	s_and_b64 s[48:49], s[2:3], exec
	s_cselect_b32 s13, s43, s47
	s_cselect_b32 s64, s42, s46
	s_add_u32 s0, s0, 0x40080
	s_addc_u32 s1, s1, 0
	s_add_u32 s65, s46, 0x100
	s_addc_u32 s66, s47, 0
	s_mov_b32 s67, -2
	ds_read_b128 v[156:159], v150
	ds_read_b128 v[160:163], v150 offset:1024
	ds_read_b128 v[164:167], v150 offset:2048
	ds_read_b128 v[168:171], v150 offset:3072
	ds_read_b128 v[172:175], v151
	ds_read_b128 v[176:179], v151 offset:1024
	ds_read_b128 v[180:183], v151 offset:2048
	ds_read_b128 v[184:187], v151 offset:3072
	s_add_u32 s19, s0, 0xfffc0080
	s_addc_u32 s46, s1, -1
	s_cmp_eq_u32 s67, 12
	s_cselect_b32 s49, s62, s46
	s_cselect_b32 s48, s63, s19
	s_cselect_b32 s47, s13, s66
	s_cselect_b32 s46, s64, s65
	v_lshl_add_u64 v[204:205], s[0:1], 0, v[138:139]
	s_add_i32 m0, s33, 0xc000
	ds_read_b128 v[188:191], v152
	ds_read_b128 v[192:195], v152 offset:1024
	ds_read_b128 v[196:199], v152 offset:2048
	ds_read_b128 v[200:203], v152 offset:3072
	ds_read_b128 v[208:211], v152 offset:4096
	ds_read_b128 v[212:215], v152 offset:5120
	ds_read_b128 v[216:219], v152 offset:6144
	ds_read_b128 v[220:223], v152 offset:7168
	global_load_lds_dwordx4 v[204:205], off
	v_lshl_add_u64 v[204:205], s[0:1], 0, v[140:141]
	s_add_i32 m0, s33, 0xe000
	s_nop 0
	global_load_lds_dwordx4 v[204:205], off
	s_waitcnt vmcnt(8)
	s_waitcnt lgkmcnt(0)
	s_barrier
	s_setprio 1
	s_waitcnt lgkmcnt(0)
	v_mfma_f32_16x16x32_bf16 v[124:127], v[156:159], v[188:191], 0
	v_mfma_f32_16x16x32_bf16 v[116:119], v[164:167], v[188:191], 0
	v_mfma_f32_16x16x32_bf16 v[108:111], v[156:159], v[196:199], 0
	v_mfma_f32_16x16x32_bf16 v[100:103], v[164:167], v[196:199], 0
	v_mfma_f32_16x16x32_bf16 v[92:95], v[156:159], v[208:211], 0
	v_mfma_f32_16x16x32_bf16 v[84:87], v[164:167], v[208:211], 0
	v_mfma_f32_16x16x32_bf16 v[76:79], v[156:159], v[216:219], 0
	v_mfma_f32_16x16x32_bf16 v[68:71], v[164:167], v[216:219], 0
	v_mfma_f32_16x16x32_bf16 v[124:127], v[160:163], v[192:195], v[124:127]
	v_mfma_f32_16x16x32_bf16 v[116:119], v[168:171], v[192:195], v[116:119]
	v_mfma_f32_16x16x32_bf16 v[108:111], v[160:163], v[200:203], v[108:111]
	v_mfma_f32_16x16x32_bf16 v[100:103], v[168:171], v[200:203], v[100:103]
	v_mfma_f32_16x16x32_bf16 v[92:95], v[160:163], v[212:215], v[92:95]
	v_mfma_f32_16x16x32_bf16 v[84:87], v[168:171], v[212:215], v[84:87]
	v_mfma_f32_16x16x32_bf16 v[76:79], v[160:163], v[220:223], v[76:79]
	v_mfma_f32_16x16x32_bf16 v[68:71], v[168:171], v[220:223], v[68:71]
	v_mfma_f32_16x16x32_bf16 v[120:123], v[172:175], v[188:191], 0
	v_mfma_f32_16x16x32_bf16 v[112:115], v[180:183], v[188:191], 0
	v_mfma_f32_16x16x32_bf16 v[104:107], v[172:175], v[196:199], 0
	v_mfma_f32_16x16x32_bf16 v[96:99], v[180:183], v[196:199], 0
	v_mfma_f32_16x16x32_bf16 v[88:91], v[172:175], v[208:211], 0
	v_mfma_f32_16x16x32_bf16 v[80:83], v[180:183], v[208:211], 0
	v_mfma_f32_16x16x32_bf16 v[72:75], v[172:175], v[216:219], 0
	v_mfma_f32_16x16x32_bf16 v[64:67], v[180:183], v[216:219], 0
	v_mfma_f32_16x16x32_bf16 v[120:123], v[176:179], v[192:195], v[120:123]
	v_mfma_f32_16x16x32_bf16 v[112:115], v[184:187], v[192:195], v[112:115]
	v_mfma_f32_16x16x32_bf16 v[104:107], v[176:179], v[200:203], v[104:107]
	v_mfma_f32_16x16x32_bf16 v[96:99], v[184:187], v[200:203], v[96:99]
	v_mfma_f32_16x16x32_bf16 v[88:91], v[176:179], v[212:215], v[88:91]
	v_mfma_f32_16x16x32_bf16 v[80:83], v[184:187], v[212:215], v[80:83]
	v_mfma_f32_16x16x32_bf16 v[72:75], v[176:179], v[220:223], v[72:75]
	v_mfma_f32_16x16x32_bf16 v[64:67], v[184:187], v[220:223], v[64:67]
	s_setprio 0
	s_barrier
	s_add_i32 s19, s55, s14
	v_lshl_add_u64 v[204:205], s[46:47], 0, v[132:133]
	s_mov_b32 m0, s19
	ds_read_b128 v[188:191], v152 offset:16384
	ds_read_b128 v[192:195], v152 offset:17408
	ds_read_b128 v[196:199], v152 offset:18432
	ds_read_b128 v[200:203], v152 offset:19456
	ds_read_b128 v[208:211], v152 offset:20480
	ds_read_b128 v[212:215], v152 offset:21504
	ds_read_b128 v[216:219], v152 offset:22528
	ds_read_b128 v[220:223], v152 offset:23552
	global_load_lds_dwordx4 v[204:205], off
	s_add_i32 m0, s19, 0x2000
	s_add_u32 s70, s46, 0x40000
	v_lshl_add_u64 v[224:225], s[46:47], 0, v[128:129]
	s_addc_u32 s71, s47, 0
	s_add_i32 s19, s56, s14
	global_load_lds_dwordx4 v[224:225], off
	v_lshl_add_u64 v[226:227], s[70:71], 0, v[132:133]
	s_mov_b32 m0, s19
	v_lshl_add_u64 v[228:229], s[48:49], 0, v[130:131]
	global_load_lds_dwordx4 v[226:227], off
	v_lshl_add_u64 v[226:227], s[70:71], 0, v[128:129]
	s_add_i32 m0, s19, 0x2000
	s_nop 0
	global_load_lds_dwordx4 v[226:227], off
	v_lshl_add_u64 v[226:227], s[48:49], 0, v[134:135]
	s_mov_b32 m0, s33
	s_nop 0
	global_load_lds_dwordx4 v[226:227], off
	s_mov_b32 m0, s35
	s_nop 0
	global_load_lds_dwordx4 v[228:229], off
	s_waitcnt vmcnt(8)
	s_waitcnt lgkmcnt(0)
	s_barrier
; #define PG8_STAGE(bufoff, gbase, voff) do { _Pragma("unroll") for (int _i = 0; _i < 2; ++_i) \
;         __builtin_amdgcn_global_load_lds((const unsigned*)((const char*)(gbase) + (voff)[_i]), (PG8_LAS unsigned*)(lds + (bufoff) + ldsw + _i * 8192), 16, 0, 0); } while (0)
; #define PG8_LDA(dst, b, h) do { _Pragma("unroll") for (int m = 0; m < 4; ++m) _Pragma("unroll") for (int k = 0; k < 2; ++k) dst[m][k] = *(const PG8_LAS bf16x8*)(lds + PG8_SA(b, h) + aoff + m * 2048 + k * 1024); } while (0)
; #define PG8_LDB(dst, b, h) do { _Pragma("unroll") for (int n = 0; n < 2; ++n) _Pragma("unroll") for (int k = 0; k < 2; ++k) dst[n][k] = *(const PG8_LAS bf16x8*)(lds + PG8_SB(b, h) + boff + n * 2048 + k * 1024); } while (0)
; #define PG8_MMA(ai, bj, At, Bt) do { __builtin_amdgcn_s_setprio(1); _Pragma("unroll") for (int m = 0; m < 4; ++m) _Pragma("unroll") for (int n = 0; n < 2; ++n) _Pragma("unroll") for (int k = 0; k < 2; ++k) \
;         acc[ai][bj][m][n] = __builtin_amdgcn_mfma_f32_16x16x32_bf16(Bt[n][k], At[m][k], acc[ai][bj][m][n], 0, 0, 0); __builtin_amdgcn_s_setprio(0); } while (0)
; #define PG8_WAIT_V(n) asm volatile("s_waitcnt vmcnt(" #n ")" ::: "memory")
; #define PG8_WAIT_L(n) asm volatile("s_waitcnt lgkmcnt(" #n ")" ::: "memory")
; #define PG8_BAR __builtin_amdgcn_s_barrier()
; #define PG8_SCHED __builtin_amdgcn_sched_barrier(0)
; template <class Epi, class Sched, bool ALIGN_EPI = false, bool SP2 = false>
; __device__ __forceinline__ void gemm_phase(PG8_LAS unsigned char* lds, const Gemm g, const Sched& S, const Epi& E) {
;     ...
;             PG8_WAIT_V(8); PG8_WAIT_L(0); PG8_BAR; PG8_MMA(1, 0, At, B0); PG8_MMA(1, 1, At, B1); PG8_BAR; PG8_SCHED;
;             PG8_LDB(B0, 1, 0); PG8_LDB(B1, 1, 1); PG8_SCHED; PG8_LDA(At, 1, 0); PG8_STAGE(PG8_SA(0, 1), a2 + hstep, voffA);
;             PG8_WAIT_V(8); PG8_WAIT_L(0); PG8_BAR; PG8_MMA(0, 0, At, B0); PG8_MMA(0, 1, At, B1); PG8_BAR; PG8_SCHED;
	s_setprio 1
	s_waitcnt lgkmcnt(0)
	v_mfma_f32_16x16x32_bf16 v[60:63], v[156:159], v[188:191], 0
	v_mfma_f32_16x16x32_bf16 v[52:55], v[164:167], v[188:191], 0
	v_mfma_f32_16x16x32_bf16 v[44:47], v[156:159], v[196:199], 0
	v_mfma_f32_16x16x32_bf16 v[36:39], v[164:167], v[196:199], 0
	v_mfma_f32_16x16x32_bf16 v[28:31], v[156:159], v[208:211], 0
	v_mfma_f32_16x16x32_bf16 v[20:23], v[164:167], v[208:211], 0
	v_mfma_f32_16x16x32_bf16 v[12:15], v[156:159], v[216:219], 0
	v_mfma_f32_16x16x32_bf16 v[4:7], v[164:167], v[216:219], 0
	v_mfma_f32_16x16x32_bf16 v[60:63], v[160:163], v[192:195], v[60:63]
	v_mfma_f32_16x16x32_bf16 v[52:55], v[168:171], v[192:195], v[52:55]
	v_mfma_f32_16x16x32_bf16 v[44:47], v[160:163], v[200:203], v[44:47]
	v_mfma_f32_16x16x32_bf16 v[36:39], v[168:171], v[200:203], v[36:39]
	v_mfma_f32_16x16x32_bf16 v[28:31], v[160:163], v[212:215], v[28:31]
	v_mfma_f32_16x16x32_bf16 v[20:23], v[168:171], v[212:215], v[20:23]
	v_mfma_f32_16x16x32_bf16 v[12:15], v[160:163], v[220:223], v[12:15]
	v_mfma_f32_16x16x32_bf16 v[4:7], v[168:171], v[220:223], v[4:7]
	v_mfma_f32_16x16x32_bf16 v[56:59], v[172:175], v[188:191], 0
	v_mfma_f32_16x16x32_bf16 v[48:51], v[180:183], v[188:191], 0
	v_mfma_f32_16x16x32_bf16 v[40:43], v[172:175], v[196:199], 0
	v_mfma_f32_16x16x32_bf16 v[32:35], v[180:183], v[196:199], 0
	v_mfma_f32_16x16x32_bf16 v[24:27], v[172:175], v[208:211], 0
	v_mfma_f32_16x16x32_bf16 v[16:19], v[180:183], v[208:211], 0
	v_mfma_f32_16x16x32_bf16 v[8:11], v[172:175], v[216:219], 0
	v_mfma_f32_16x16x32_bf16 v[0:3], v[180:183], v[216:219], 0
	v_mfma_f32_16x16x32_bf16 v[56:59], v[176:179], v[192:195], v[56:59]
	v_mfma_f32_16x16x32_bf16 v[48:51], v[184:187], v[192:195], v[48:51]
	v_mfma_f32_16x16x32_bf16 v[40:43], v[176:179], v[200:203], v[40:43]
	v_mfma_f32_16x16x32_bf16 v[32:35], v[184:187], v[200:203], v[32:35]
	v_mfma_f32_16x16x32_bf16 v[24:27], v[176:179], v[212:215], v[24:27]
	v_mfma_f32_16x16x32_bf16 v[16:19], v[184:187], v[212:215], v[16:19]
	v_mfma_f32_16x16x32_bf16 v[8:11], v[176:179], v[220:223], v[8:11]
	v_mfma_f32_16x16x32_bf16 v[0:3], v[184:187], v[220:223], v[0:3]
	s_setprio 0
	s_barrier
	s_add_i32 s19, 0, 0x18000
	v_add_u32_e32 v155, s19, v147
	s_add_i32 s70, 0, 0x1c000
	ds_read_b128 v[156:159], v155
	ds_read_b128 v[160:163], v155 offset:1024
	ds_read_b128 v[164:167], v155 offset:2048
	ds_read_b128 v[168:171], v155 offset:3072
	v_add_u32_e32 v155, s70, v147
	ds_read_b128 v[172:175], v155
	ds_read_b128 v[176:179], v155 offset:1024
	ds_read_b128 v[180:183], v155 offset:2048
	ds_read_b128 v[184:187], v155 offset:3072
	s_add_u32 s48, s48, 0x40000
	s_addc_u32 s49, s49, 0
	s_mov_b32 m0, s45
	v_lshl_add_u64 v[230:231], s[48:49], 0, v[134:135]
	ds_read_b128 v[188:191], v152 offset:32768
	ds_read_b128 v[192:195], v152 offset:33792
	ds_read_b128 v[196:199], v152 offset:34816
	ds_read_b128 v[200:203], v152 offset:35840
	ds_read_b128 v[208:211], v152 offset:36864
	ds_read_b128 v[212:215], v152 offset:37888
	ds_read_b128 v[216:219], v152 offset:38912
	ds_read_b128 v[220:223], v152 offset:39936
	global_load_lds_dwordx4 v[230:231], off
	v_lshl_add_u64 v[230:231], s[48:49], 0, v[130:131]
	s_mov_b32 m0, s50
	s_nop 0
	global_load_lds_dwordx4 v[230:231], off
	s_waitcnt vmcnt(8)
	s_waitcnt lgkmcnt(0)
	s_barrier
	s_setprio 1
	s_waitcnt lgkmcnt(0)
	v_mfma_f32_16x16x32_bf16 v[124:127], v[156:159], v[188:191], v[124:127]
	v_mfma_f32_16x16x32_bf16 v[116:119], v[164:167], v[188:191], v[116:119]
	v_mfma_f32_16x16x32_bf16 v[108:111], v[156:159], v[196:199], v[108:111]
	v_mfma_f32_16x16x32_bf16 v[100:103], v[164:167], v[196:199], v[100:103]
	v_mfma_f32_16x16x32_bf16 v[92:95], v[156:159], v[208:211], v[92:95]
	v_mfma_f32_16x16x32_bf16 v[84:87], v[164:167], v[208:211], v[84:87]
	v_mfma_f32_16x16x32_bf16 v[76:79], v[156:159], v[216:219], v[76:79]
	v_mfma_f32_16x16x32_bf16 v[68:71], v[164:167], v[216:219], v[68:71]
	v_mfma_f32_16x16x32_bf16 v[124:127], v[160:163], v[192:195], v[124:127]
	v_mfma_f32_16x16x32_bf16 v[116:119], v[168:171], v[192:195], v[116:119]
	v_mfma_f32_16x16x32_bf16 v[108:111], v[160:163], v[200:203], v[108:111]
	v_mfma_f32_16x16x32_bf16 v[100:103], v[168:171], v[200:203], v[100:103]
	v_mfma_f32_16x16x32_bf16 v[92:95], v[160:163], v[212:215], v[92:95]
	v_mfma_f32_16x16x32_bf16 v[84:87], v[168:171], v[212:215], v[84:87]
	v_mfma_f32_16x16x32_bf16 v[76:79], v[160:163], v[220:223], v[76:79]
	v_mfma_f32_16x16x32_bf16 v[68:71], v[168:171], v[220:223], v[68:71]
	v_mfma_f32_16x16x32_bf16 v[120:123], v[172:175], v[188:191], v[120:123]
	v_mfma_f32_16x16x32_bf16 v[112:115], v[180:183], v[188:191], v[112:115]
	v_mfma_f32_16x16x32_bf16 v[104:107], v[172:175], v[196:199], v[104:107]
	v_mfma_f32_16x16x32_bf16 v[96:99], v[180:183], v[196:199], v[96:99]
	v_mfma_f32_16x16x32_bf16 v[88:91], v[172:175], v[208:211], v[88:91]
	v_mfma_f32_16x16x32_bf16 v[80:83], v[180:183], v[208:211], v[80:83]
	v_mfma_f32_16x16x32_bf16 v[72:75], v[172:175], v[216:219], v[72:75]
	v_mfma_f32_16x16x32_bf16 v[64:67], v[180:183], v[216:219], v[64:67]
	v_mfma_f32_16x16x32_bf16 v[120:123], v[176:179], v[192:195], v[120:123]
	v_mfma_f32_16x16x32_bf16 v[112:115], v[184:187], v[192:195], v[112:115]
	v_mfma_f32_16x16x32_bf16 v[104:107], v[176:179], v[200:203], v[104:107]
	v_mfma_f32_16x16x32_bf16 v[96:99], v[184:187], v[200:203], v[96:99]
	v_mfma_f32_16x16x32_bf16 v[88:91], v[176:179], v[212:215], v[88:91]
	v_mfma_f32_16x16x32_bf16 v[80:83], v[184:187], v[212:215], v[80:83]
	v_mfma_f32_16x16x32_bf16 v[72:75], v[176:179], v[220:223], v[72:75]
	v_mfma_f32_16x16x32_bf16 v[64:67], v[184:187], v[220:223], v[64:67]
	s_setprio 0
	s_barrier
; #define PG8_STAGE(bufoff, gbase, voff) do { _Pragma("unroll") for (int _i = 0; _i < 2; ++_i) \
;         __builtin_amdgcn_global_load_lds((const unsigned*)((const char*)(gbase) + (voff)[_i]), (PG8_LAS unsigned*)(lds + (bufoff) + ldsw + _i * 8192), 16, 0, 0); } while (0)
; #define PG8_LDA(dst, b, h) do { _Pragma("unroll") for (int m = 0; m < 4; ++m) _Pragma("unroll") for (int k = 0; k < 2; ++k) dst[m][k] = *(const PG8_LAS bf16x8*)(lds + PG8_SA(b, h) + aoff + m * 2048 + k * 1024); } while (0)
; #define PG8_LDB(dst, b, h) do { _Pragma("unroll") for (int n = 0; n < 2; ++n) _Pragma("unroll") for (int k = 0; k < 2; ++k) dst[n][k] = *(const PG8_LAS bf16x8*)(lds + PG8_SB(b, h) + boff + n * 2048 + k * 1024); } while (0)
; #define PG8_MMA(ai, bj, At, Bt) do { __builtin_amdgcn_s_setprio(1); _Pragma("unroll") for (int m = 0; m < 4; ++m) _Pragma("unroll") for (int n = 0; n < 2; ++n) _Pragma("unroll") for (int k = 0; k < 2; ++k) \
;         acc[ai][bj][m][n] = __builtin_amdgcn_mfma_f32_16x16x32_bf16(Bt[n][k], At[m][k], acc[ai][bj][m][n], 0, 0, 0); __builtin_amdgcn_s_setprio(0); } while (0)
; #define PG8_WAIT_V(n) asm volatile("s_waitcnt vmcnt(" #n ")" ::: "memory")
; template <class Epi, class Sched, bool ALIGN_EPI = false, bool SP2 = false>
; __device__ __forceinline__ void gemm_phase(PG8_LAS unsigned char* lds, const Gemm g, const Sched& S, const Epi& E) {
;     ...
;             PG8_LDB(B0, 0, 0); PG8_LDB(B1, 0, 1); PG8_SCHED; PG8_LDA(At, 0, 0); PG8_STAGE(PG8_SA(1, 1), a1 + hstep, voffA);
;             PG8_WAIT_V(8); PG8_WAIT_L(0); PG8_BAR; PG8_MMA(0, 0, At, B0); PG8_MMA(0, 1, At, B1); PG8_BAR; PG8_SCHED;
;             PG8_LDA(At, 0, 1); PG8_STAGE(PG8_SB(0, 0), b2, voffB); PG8_STAGE(PG8_SB(0, 1), b2 + hstep, voffB); PG8_STAGE(PG8_SA(0, 0), a2, voffA);
;             PG8_WAIT_V(8); PG8_WAIT_L(0); PG8_BAR; PG8_MMA(1, 0, At, B0); PG8_MMA(1, 1, At, B1); PG8_BAR; PG8_SCHED;
;             PG8_LDB(B0, 1, 0); PG8_LDB(B1, 1, 1); PG8_SCHED; PG8_LDA(At, 1, 0); PG8_STAGE(PG8_SA(0, 1), a2 + hstep, voffA);
;             PG8_WAIT_V(8); PG8_WAIT_L(0); PG8_BAR; PG8_MMA(0, 0, At, B0); PG8_MMA(0, 1, At, B1); PG8_BAR; PG8_SCHED;
;             PG8_LDA(At, 1, 1); PG8_STAGE(PG8_SB(1, 0), b3, voffB); PG8_STAGE(PG8_SB(1, 1), b3 + hstep, voffB); PG8_STAGE(PG8_SA(1, 0), a3, voffA);
;             PG8_WAIT_V(8); PG8_WAIT_L(0); PG8_BAR; PG8_MMA(1, 0, At, B0); PG8_MMA(1, 1, At, B1); PG8_BAR; PG8_SCHED;
	s_add_i32 s19, s19, s14
	v_lshl_add_u64 v[204:205], v[204:205], 0, s[8:9]
	s_mov_b32 m0, s19
	ds_read_b128 v[188:191], v152 offset:49152
	ds_read_b128 v[192:195], v152 offset:50176
	ds_read_b128 v[196:199], v152 offset:51200
	ds_read_b128 v[200:203], v152 offset:52224
	ds_read_b128 v[208:211], v152 offset:53248
	ds_read_b128 v[212:215], v152 offset:54272
	ds_read_b128 v[216:219], v152 offset:55296
	ds_read_b128 v[220:223], v152 offset:56320
	global_load_lds_dwordx4 v[204:205], off
	s_add_i32 m0, s19, 0x2000
	s_add_u32 s46, s46, 0x40080
	v_lshl_add_u64 v[204:205], v[224:225], 0, s[8:9]
	s_addc_u32 s47, s47, 0
	s_add_i32 s19, s70, s14
	global_load_lds_dwordx4 v[204:205], off
	v_lshl_add_u64 v[204:205], s[46:47], 0, v[132:133]
	s_mov_b32 m0, s19
	s_nop 0
	global_load_lds_dwordx4 v[204:205], off
	v_lshl_add_u64 v[204:205], s[46:47], 0, v[128:129]
	s_add_i32 m0, s19, 0x2000
	s_nop 0
	global_load_lds_dwordx4 v[204:205], off
	v_lshl_add_u64 v[204:205], v[226:227], 0, s[8:9]
	s_mov_b32 m0, s51
	s_nop 0
	global_load_lds_dwordx4 v[204:205], off
	v_lshl_add_u64 v[204:205], v[228:229], 0, s[8:9]
	s_mov_b32 m0, s52
	s_nop 0
	global_load_lds_dwordx4 v[204:205], off
	s_waitcnt vmcnt(8)
	s_waitcnt lgkmcnt(0)
	s_barrier
	s_setprio 1
	s_waitcnt lgkmcnt(0)
	v_mfma_f32_16x16x32_bf16 v[60:63], v[156:159], v[188:191], v[60:63]
	v_mfma_f32_16x16x32_bf16 v[52:55], v[164:167], v[188:191], v[52:55]
	v_mfma_f32_16x16x32_bf16 v[44:47], v[156:159], v[196:199], v[44:47]
	v_mfma_f32_16x16x32_bf16 v[36:39], v[164:167], v[196:199], v[36:39]
	v_mfma_f32_16x16x32_bf16 v[28:31], v[156:159], v[208:211], v[28:31]
	v_mfma_f32_16x16x32_bf16 v[20:23], v[164:167], v[208:211], v[20:23]
	v_mfma_f32_16x16x32_bf16 v[12:15], v[156:159], v[216:219], v[12:15]
	v_mfma_f32_16x16x32_bf16 v[4:7], v[164:167], v[216:219], v[4:7]
	v_mfma_f32_16x16x32_bf16 v[60:63], v[160:163], v[192:195], v[60:63]
	v_mfma_f32_16x16x32_bf16 v[52:55], v[168:171], v[192:195], v[52:55]
	v_mfma_f32_16x16x32_bf16 v[44:47], v[160:163], v[200:203], v[44:47]
	v_mfma_f32_16x16x32_bf16 v[36:39], v[168:171], v[200:203], v[36:39]
	v_mfma_f32_16x16x32_bf16 v[28:31], v[160:163], v[212:215], v[28:31]
	v_mfma_f32_16x16x32_bf16 v[20:23], v[168:171], v[212:215], v[20:23]
	v_mfma_f32_16x16x32_bf16 v[12:15], v[160:163], v[220:223], v[12:15]
	v_mfma_f32_16x16x32_bf16 v[4:7], v[168:171], v[220:223], v[4:7]
	v_mfma_f32_16x16x32_bf16 v[56:59], v[172:175], v[188:191], v[56:59]
	v_mfma_f32_16x16x32_bf16 v[48:51], v[180:183], v[188:191], v[48:51]
	v_mfma_f32_16x16x32_bf16 v[40:43], v[172:175], v[196:199], v[40:43]
	v_mfma_f32_16x16x32_bf16 v[32:35], v[180:183], v[196:199], v[32:35]
	v_mfma_f32_16x16x32_bf16 v[24:27], v[172:175], v[208:211], v[24:27]
	v_mfma_f32_16x16x32_bf16 v[16:19], v[180:183], v[208:211], v[16:19]
	v_mfma_f32_16x16x32_bf16 v[8:11], v[172:175], v[216:219], v[8:11]
	v_mfma_f32_16x16x32_bf16 v[0:3], v[180:183], v[216:219], v[0:3]
	v_mfma_f32_16x16x32_bf16 v[56:59], v[176:179], v[192:195], v[56:59]
	v_mfma_f32_16x16x32_bf16 v[48:51], v[184:187], v[192:195], v[48:51]
	v_mfma_f32_16x16x32_bf16 v[40:43], v[176:179], v[200:203], v[40:43]
	v_mfma_f32_16x16x32_bf16 v[32:35], v[184:187], v[200:203], v[32:35]
	v_mfma_f32_16x16x32_bf16 v[24:27], v[176:179], v[212:215], v[24:27]
	v_mfma_f32_16x16x32_bf16 v[16:19], v[184:187], v[212:215], v[16:19]
	v_mfma_f32_16x16x32_bf16 v[8:11], v[176:179], v[220:223], v[8:11]
	v_mfma_f32_16x16x32_bf16 v[0:3], v[184:187], v[220:223], v[0:3]
	s_setprio 0
	s_barrier
	s_add_i32 s67, s67, 2
	s_add_u32 s0, s0, 0x100
	s_addc_u32 s1, s1, 0
	s_add_u32 s65, s65, 0x100
	s_addc_u32 s66, s66, 0
	s_cmp_gt_u32 s67, 13
	s_cbranch_scc1 .Lpeel_exit_3
	.p2align	6
.LBB0_567:
	ds_read_b128 v[156:159], v150
	ds_read_b128 v[160:163], v150 offset:1024
	ds_read_b128 v[164:167], v150 offset:2048
	ds_read_b128 v[168:171], v150 offset:3072
	ds_read_b128 v[172:175], v151
	ds_read_b128 v[176:179], v151 offset:1024
	ds_read_b128 v[180:183], v151 offset:2048
	ds_read_b128 v[184:187], v151 offset:3072
	s_add_u32 s19, s0, 0xfffc0080
	s_addc_u32 s46, s1, -1
	s_cmp_eq_u32 s67, 12
	s_cselect_b32 s49, s62, s46
	s_cselect_b32 s48, s63, s19
	s_cselect_b32 s47, s13, s66
	s_cselect_b32 s46, s64, s65
	v_lshl_add_u64 v[204:205], s[0:1], 0, v[138:139]
	s_add_i32 m0, s33, 0xc000
	ds_read_b128 v[188:191], v152
	ds_read_b128 v[192:195], v152 offset:1024
	ds_read_b128 v[196:199], v152 offset:2048
	ds_read_b128 v[200:203], v152 offset:3072
	ds_read_b128 v[208:211], v152 offset:4096
	ds_read_b128 v[212:215], v152 offset:5120
	ds_read_b128 v[216:219], v152 offset:6144
	ds_read_b128 v[220:223], v152 offset:7168
	global_load_lds_dwordx4 v[204:205], off
	v_lshl_add_u64 v[204:205], s[0:1], 0, v[140:141]
	s_add_i32 m0, s33, 0xe000
	s_nop 0
	global_load_lds_dwordx4 v[204:205], off
	s_waitcnt vmcnt(8)
	s_waitcnt lgkmcnt(0)
	s_barrier
; #define PG8_STAGE(bufoff, gbase, voff) do { _Pragma("unroll") for (int _i = 0; _i < 2; ++_i) \
;         __builtin_amdgcn_global_load_lds((const unsigned*)((const char*)(gbase) + (voff)[_i]), (PG8_LAS unsigned*)(lds + (bufoff) + ldsw + _i * 8192), 16, 0, 0); } while (0)
; #define PG8_LDA(dst, b, h) do { _Pragma("unroll") for (int m = 0; m < 4; ++m) _Pragma("unroll") for (int k = 0; k < 2; ++k) dst[m][k] = *(const PG8_LAS bf16x8*)(lds + PG8_SA(b, h) + aoff + m * 2048 + k * 1024); } while (0)
; #define PG8_LDB(dst, b, h) do { _Pragma("unroll") for (int n = 0; n < 2; ++n) _Pragma("unroll") for (int k = 0; k < 2; ++k) dst[n][k] = *(const PG8_LAS bf16x8*)(lds + PG8_SB(b, h) + boff + n * 2048 + k * 1024); } while (0)
; #define PG8_MMA(ai, bj, At, Bt) do { __builtin_amdgcn_s_setprio(1); _Pragma("unroll") for (int m = 0; m < 4; ++m) _Pragma("unroll") for (int n = 0; n < 2; ++n) _Pragma("unroll") for (int k = 0; k < 2; ++k) \
;         acc[ai][bj][m][n] = __builtin_amdgcn_mfma_f32_16x16x32_bf16(Bt[n][k], At[m][k], acc[ai][bj][m][n], 0, 0, 0); __builtin_amdgcn_s_setprio(0); } while (0)
; #define PG8_WAIT_V(n) asm volatile("s_waitcnt vmcnt(" #n ")" ::: "memory")
; #define PG8_WAIT_L(n) asm volatile("s_waitcnt lgkmcnt(" #n ")" ::: "memory")
; #define PG8_BAR __builtin_amdgcn_s_barrier()
; #define PG8_SCHED __builtin_amdgcn_sched_barrier(0)
; template <class Epi, class Sched, bool ALIGN_EPI = false, bool SP2 = false>
; __device__ __forceinline__ void gemm_phase(PG8_LAS unsigned char* lds, const Gemm g, const Sched& S, const Epi& E) {
;     ...
;             PG8_LDB(B0, 0, 0); PG8_LDB(B1, 0, 1); PG8_SCHED; PG8_LDA(At, 0, 0); PG8_STAGE(PG8_SA(1, 1), a1 + hstep, voffA);
;             PG8_WAIT_V(8); PG8_WAIT_L(0); PG8_BAR; PG8_MMA(0, 0, At, B0); PG8_MMA(0, 1, At, B1); PG8_BAR; PG8_SCHED;
;             PG8_LDA(At, 0, 1); PG8_STAGE(PG8_SB(0, 0), b2, voffB); PG8_STAGE(PG8_SB(0, 1), b2 + hstep, voffB); PG8_STAGE(PG8_SA(0, 0), a2, voffA);
;             PG8_WAIT_V(8); PG8_WAIT_L(0); PG8_BAR; PG8_MMA(1, 0, At, B0); PG8_MMA(1, 1, At, B1); PG8_BAR; PG8_SCHED;
	s_setprio 1
	s_waitcnt lgkmcnt(0)
	v_mfma_f32_16x16x32_bf16 v[124:127], v[156:159], v[188:191], v[124:127]
	v_mfma_f32_16x16x32_bf16 v[116:119], v[164:167], v[188:191], v[116:119]
	v_mfma_f32_16x16x32_bf16 v[108:111], v[156:159], v[196:199], v[108:111]
	v_mfma_f32_16x16x32_bf16 v[100:103], v[164:167], v[196:199], v[100:103]
	v_mfma_f32_16x16x32_bf16 v[92:95], v[156:159], v[208:211], v[92:95]
	v_mfma_f32_16x16x32_bf16 v[84:87], v[164:167], v[208:211], v[84:87]
	v_mfma_f32_16x16x32_bf16 v[76:79], v[156:159], v[216:219], v[76:79]
	v_mfma_f32_16x16x32_bf16 v[68:71], v[164:167], v[216:219], v[68:71]
	v_mfma_f32_16x16x32_bf16 v[124:127], v[160:163], v[192:195], v[124:127]
	v_mfma_f32_16x16x32_bf16 v[116:119], v[168:171], v[192:195], v[116:119]
	v_mfma_f32_16x16x32_bf16 v[108:111], v[160:163], v[200:203], v[108:111]
	v_mfma_f32_16x16x32_bf16 v[100:103], v[168:171], v[200:203], v[100:103]
	v_mfma_f32_16x16x32_bf16 v[92:95], v[160:163], v[212:215], v[92:95]
	v_mfma_f32_16x16x32_bf16 v[84:87], v[168:171], v[212:215], v[84:87]
	v_mfma_f32_16x16x32_bf16 v[76:79], v[160:163], v[220:223], v[76:79]
	v_mfma_f32_16x16x32_bf16 v[68:71], v[168:171], v[220:223], v[68:71]
	v_mfma_f32_16x16x32_bf16 v[120:123], v[172:175], v[188:191], v[120:123]
	v_mfma_f32_16x16x32_bf16 v[112:115], v[180:183], v[188:191], v[112:115]
	v_mfma_f32_16x16x32_bf16 v[104:107], v[172:175], v[196:199], v[104:107]
	v_mfma_f32_16x16x32_bf16 v[96:99], v[180:183], v[196:199], v[96:99]
	v_mfma_f32_16x16x32_bf16 v[88:91], v[172:175], v[208:211], v[88:91]
	v_mfma_f32_16x16x32_bf16 v[80:83], v[180:183], v[208:211], v[80:83]
	v_mfma_f32_16x16x32_bf16 v[72:75], v[172:175], v[216:219], v[72:75]
	v_mfma_f32_16x16x32_bf16 v[64:67], v[180:183], v[216:219], v[64:67]
	v_mfma_f32_16x16x32_bf16 v[120:123], v[176:179], v[192:195], v[120:123]
	v_mfma_f32_16x16x32_bf16 v[112:115], v[184:187], v[192:195], v[112:115]
	v_mfma_f32_16x16x32_bf16 v[104:107], v[176:179], v[200:203], v[104:107]
	v_mfma_f32_16x16x32_bf16 v[96:99], v[184:187], v[200:203], v[96:99]
	v_mfma_f32_16x16x32_bf16 v[88:91], v[176:179], v[212:215], v[88:91]
	v_mfma_f32_16x16x32_bf16 v[80:83], v[184:187], v[212:215], v[80:83]
	v_mfma_f32_16x16x32_bf16 v[72:75], v[176:179], v[220:223], v[72:75]
	v_mfma_f32_16x16x32_bf16 v[64:67], v[184:187], v[220:223], v[64:67]
	s_setprio 0
	s_barrier
	s_add_i32 s19, s55, s14
	v_lshl_add_u64 v[204:205], s[46:47], 0, v[132:133]
	s_mov_b32 m0, s19
	ds_read_b128 v[188:191], v152 offset:16384
	ds_read_b128 v[192:195], v152 offset:17408
	ds_read_b128 v[196:199], v152 offset:18432
	ds_read_b128 v[200:203], v152 offset:19456
	ds_read_b128 v[208:211], v152 offset:20480
	ds_read_b128 v[212:215], v152 offset:21504
	ds_read_b128 v[216:219], v152 offset:22528
	ds_read_b128 v[220:223], v152 offset:23552
	global_load_lds_dwordx4 v[204:205], off
	s_add_i32 m0, s19, 0x2000
	s_add_u32 s70, s46, 0x40000
	v_lshl_add_u64 v[224:225], s[46:47], 0, v[128:129]
	s_addc_u32 s71, s47, 0
	s_add_i32 s19, s56, s14
	global_load_lds_dwordx4 v[224:225], off
	v_lshl_add_u64 v[226:227], s[70:71], 0, v[132:133]
	s_mov_b32 m0, s19
	v_lshl_add_u64 v[228:229], s[48:49], 0, v[130:131]
	global_load_lds_dwordx4 v[226:227], off
	v_lshl_add_u64 v[226:227], s[70:71], 0, v[128:129]
	s_add_i32 m0, s19, 0x2000
	s_nop 0
	global_load_lds_dwordx4 v[226:227], off
	v_lshl_add_u64 v[226:227], s[48:49], 0, v[134:135]
	s_mov_b32 m0, s33
	s_nop 0
	global_load_lds_dwordx4 v[226:227], off
	s_mov_b32 m0, s35
	s_nop 0
	global_load_lds_dwordx4 v[228:229], off
	s_waitcnt vmcnt(8)
	s_waitcnt lgkmcnt(0)
	s_barrier
	s_setprio 1
	s_waitcnt lgkmcnt(0)
	v_mfma_f32_16x16x32_bf16 v[60:63], v[156:159], v[188:191], v[60:63]
	v_mfma_f32_16x16x32_bf16 v[52:55], v[164:167], v[188:191], v[52:55]
	v_mfma_f32_16x16x32_bf16 v[44:47], v[156:159], v[196:199], v[44:47]
	v_mfma_f32_16x16x32_bf16 v[36:39], v[164:167], v[196:199], v[36:39]
	v_mfma_f32_16x16x32_bf16 v[28:31], v[156:159], v[208:211], v[28:31]
	v_mfma_f32_16x16x32_bf16 v[20:23], v[164:167], v[208:211], v[20:23]
	v_mfma_f32_16x16x32_bf16 v[12:15], v[156:159], v[216:219], v[12:15]
	v_mfma_f32_16x16x32_bf16 v[4:7], v[164:167], v[216:219], v[4:7]
	v_mfma_f32_16x16x32_bf16 v[60:63], v[160:163], v[192:195], v[60:63]
	v_mfma_f32_16x16x32_bf16 v[52:55], v[168:171], v[192:195], v[52:55]
	v_mfma_f32_16x16x32_bf16 v[44:47], v[160:163], v[200:203], v[44:47]
	v_mfma_f32_16x16x32_bf16 v[36:39], v[168:171], v[200:203], v[36:39]
	v_mfma_f32_16x16x32_bf16 v[28:31], v[160:163], v[212:215], v[28:31]
	v_mfma_f32_16x16x32_bf16 v[20:23], v[168:171], v[212:215], v[20:23]
	v_mfma_f32_16x16x32_bf16 v[12:15], v[160:163], v[220:223], v[12:15]
	v_mfma_f32_16x16x32_bf16 v[4:7], v[168:171], v[220:223], v[4:7]
	v_mfma_f32_16x16x32_bf16 v[56:59], v[172:175], v[188:191], v[56:59]
	v_mfma_f32_16x16x32_bf16 v[48:51], v[180:183], v[188:191], v[48:51]
	v_mfma_f32_16x16x32_bf16 v[40:43], v[172:175], v[196:199], v[40:43]
	v_mfma_f32_16x16x32_bf16 v[32:35], v[180:183], v[196:199], v[32:35]
	v_mfma_f32_16x16x32_bf16 v[24:27], v[172:175], v[208:211], v[24:27]
	v_mfma_f32_16x16x32_bf16 v[16:19], v[180:183], v[208:211], v[16:19]
	v_mfma_f32_16x16x32_bf16 v[8:11], v[172:175], v[216:219], v[8:11]
	v_mfma_f32_16x16x32_bf16 v[0:3], v[180:183], v[216:219], v[0:3]
	v_mfma_f32_16x16x32_bf16 v[56:59], v[176:179], v[192:195], v[56:59]
	v_mfma_f32_16x16x32_bf16 v[48:51], v[184:187], v[192:195], v[48:51]
	v_mfma_f32_16x16x32_bf16 v[40:43], v[176:179], v[200:203], v[40:43]
	v_mfma_f32_16x16x32_bf16 v[32:35], v[184:187], v[200:203], v[32:35]
	v_mfma_f32_16x16x32_bf16 v[24:27], v[176:179], v[212:215], v[24:27]
	v_mfma_f32_16x16x32_bf16 v[16:19], v[184:187], v[212:215], v[16:19]
	v_mfma_f32_16x16x32_bf16 v[8:11], v[176:179], v[220:223], v[8:11]
	v_mfma_f32_16x16x32_bf16 v[0:3], v[184:187], v[220:223], v[0:3]
	s_setprio 0
	s_barrier
; #define PG8_STAGE(bufoff, gbase, voff) do { _Pragma("unroll") for (int _i = 0; _i < 2; ++_i) \
;         __builtin_amdgcn_global_load_lds((const unsigned*)((const char*)(gbase) + (voff)[_i]), (PG8_LAS unsigned*)(lds + (bufoff) + ldsw + _i * 8192), 16, 0, 0); } while (0)
; #define PG8_LDA(dst, b, h) do { _Pragma("unroll") for (int m = 0; m < 4; ++m) _Pragma("unroll") for (int k = 0; k < 2; ++k) dst[m][k] = *(const PG8_LAS bf16x8*)(lds + PG8_SA(b, h) + aoff + m * 2048 + k * 1024); } while (0)
; #define PG8_LDB(dst, b, h) do { _Pragma("unroll") for (int n = 0; n < 2; ++n) _Pragma("unroll") for (int k = 0; k < 2; ++k) dst[n][k] = *(const PG8_LAS bf16x8*)(lds + PG8_SB(b, h) + boff + n * 2048 + k * 1024); } while (0)
; #define PG8_MMA(ai, bj, At, Bt) do { __builtin_amdgcn_s_setprio(1); _Pragma("unroll") for (int m = 0; m < 4; ++m) _Pragma("unroll") for (int n = 0; n < 2; ++n) _Pragma("unroll") for (int k = 0; k < 2; ++k) \
;         acc[ai][bj][m][n] = __builtin_amdgcn_mfma_f32_16x16x32_bf16(Bt[n][k], At[m][k], acc[ai][bj][m][n], 0, 0, 0); __builtin_amdgcn_s_setprio(0); } while (0)
; #define PG8_WAIT_V(n) asm volatile("s_waitcnt vmcnt(" #n ")" ::: "memory")
; #define PG8_WAIT_L(n) asm volatile("s_waitcnt lgkmcnt(" #n ")" ::: "memory")
; #define PG8_BAR __builtin_amdgcn_s_barrier()
; #define PG8_SCHED __builtin_amdgcn_sched_barrier(0)
; template <class Epi, class Sched, bool ALIGN_EPI = false, bool SP2 = false>
; __device__ __forceinline__ void gemm_phase(PG8_LAS unsigned char* lds, const Gemm g, const Sched& S, const Epi& E) {
;     ...
;             PG8_LDB(B0, 1, 0); PG8_LDB(B1, 1, 1); PG8_SCHED; PG8_LDA(At, 1, 0); PG8_STAGE(PG8_SA(0, 1), a2 + hstep, voffA);
;             PG8_WAIT_V(8); PG8_WAIT_L(0); PG8_BAR; PG8_MMA(0, 0, At, B0); PG8_MMA(0, 1, At, B1); PG8_BAR; PG8_SCHED;
	s_add_i32 s19, 0, 0x18000
	v_add_u32_e32 v155, s19, v147
	s_add_i32 s70, 0, 0x1c000
	ds_read_b128 v[156:159], v155
	ds_read_b128 v[160:163], v155 offset:1024
	ds_read_b128 v[164:167], v155 offset:2048
	ds_read_b128 v[168:171], v155 offset:3072
	v_add_u32_e32 v155, s70, v147
	ds_read_b128 v[172:175], v155
	ds_read_b128 v[176:179], v155 offset:1024
	ds_read_b128 v[180:183], v155 offset:2048
	ds_read_b128 v[184:187], v155 offset:3072
	s_add_u32 s48, s48, 0x40000
	s_addc_u32 s49, s49, 0
	s_mov_b32 m0, s45
	v_lshl_add_u64 v[230:231], s[48:49], 0, v[134:135]
	ds_read_b128 v[188:191], v152 offset:32768
	ds_read_b128 v[192:195], v152 offset:33792
	ds_read_b128 v[196:199], v152 offset:34816
	ds_read_b128 v[200:203], v152 offset:35840
	ds_read_b128 v[208:211], v152 offset:36864
	ds_read_b128 v[212:215], v152 offset:37888
	ds_read_b128 v[216:219], v152 offset:38912
	ds_read_b128 v[220:223], v152 offset:39936
	global_load_lds_dwordx4 v[230:231], off
	v_lshl_add_u64 v[230:231], s[48:49], 0, v[130:131]
	s_mov_b32 m0, s50
	s_nop 0
	global_load_lds_dwordx4 v[230:231], off
	s_waitcnt vmcnt(8)
	s_waitcnt lgkmcnt(0)
	s_barrier
	s_setprio 1
	s_waitcnt lgkmcnt(0)
	v_mfma_f32_16x16x32_bf16 v[124:127], v[156:159], v[188:191], v[124:127]
	v_mfma_f32_16x16x32_bf16 v[116:119], v[164:167], v[188:191], v[116:119]
	v_mfma_f32_16x16x32_bf16 v[108:111], v[156:159], v[196:199], v[108:111]
	v_mfma_f32_16x16x32_bf16 v[100:103], v[164:167], v[196:199], v[100:103]
	v_mfma_f32_16x16x32_bf16 v[92:95], v[156:159], v[208:211], v[92:95]
	v_mfma_f32_16x16x32_bf16 v[84:87], v[164:167], v[208:211], v[84:87]
	v_mfma_f32_16x16x32_bf16 v[76:79], v[156:159], v[216:219], v[76:79]
	v_mfma_f32_16x16x32_bf16 v[68:71], v[164:167], v[216:219], v[68:71]
	v_mfma_f32_16x16x32_bf16 v[124:127], v[160:163], v[192:195], v[124:127]
	v_mfma_f32_16x16x32_bf16 v[116:119], v[168:171], v[192:195], v[116:119]
	v_mfma_f32_16x16x32_bf16 v[108:111], v[160:163], v[200:203], v[108:111]
	v_mfma_f32_16x16x32_bf16 v[100:103], v[168:171], v[200:203], v[100:103]
	v_mfma_f32_16x16x32_bf16 v[92:95], v[160:163], v[212:215], v[92:95]
	v_mfma_f32_16x16x32_bf16 v[84:87], v[168:171], v[212:215], v[84:87]
	v_mfma_f32_16x16x32_bf16 v[76:79], v[160:163], v[220:223], v[76:79]
	v_mfma_f32_16x16x32_bf16 v[68:71], v[168:171], v[220:223], v[68:71]
	v_mfma_f32_16x16x32_bf16 v[120:123], v[172:175], v[188:191], v[120:123]
	v_mfma_f32_16x16x32_bf16 v[112:115], v[180:183], v[188:191], v[112:115]
	v_mfma_f32_16x16x32_bf16 v[104:107], v[172:175], v[196:199], v[104:107]
	v_mfma_f32_16x16x32_bf16 v[96:99], v[180:183], v[196:199], v[96:99]
	v_mfma_f32_16x16x32_bf16 v[88:91], v[172:175], v[208:211], v[88:91]
	v_mfma_f32_16x16x32_bf16 v[80:83], v[180:183], v[208:211], v[80:83]
	v_mfma_f32_16x16x32_bf16 v[72:75], v[172:175], v[216:219], v[72:75]
	v_mfma_f32_16x16x32_bf16 v[64:67], v[180:183], v[216:219], v[64:67]
	v_mfma_f32_16x16x32_bf16 v[120:123], v[176:179], v[192:195], v[120:123]
	v_mfma_f32_16x16x32_bf16 v[112:115], v[184:187], v[192:195], v[112:115]
	v_mfma_f32_16x16x32_bf16 v[104:107], v[176:179], v[200:203], v[104:107]
	v_mfma_f32_16x16x32_bf16 v[96:99], v[184:187], v[200:203], v[96:99]
	v_mfma_f32_16x16x32_bf16 v[88:91], v[176:179], v[212:215], v[88:91]
	v_mfma_f32_16x16x32_bf16 v[80:83], v[184:187], v[212:215], v[80:83]
	v_mfma_f32_16x16x32_bf16 v[72:75], v[176:179], v[220:223], v[72:75]
	v_mfma_f32_16x16x32_bf16 v[64:67], v[184:187], v[220:223], v[64:67]
	s_setprio 0
	s_barrier
; #define PG8_STAGE(bufoff, gbase, voff) do { _Pragma("unroll") for (int _i = 0; _i < 2; ++_i) \
;         __builtin_amdgcn_global_load_lds((const unsigned*)((const char*)(gbase) + (voff)[_i]), (PG8_LAS unsigned*)(lds + (bufoff) + ldsw + _i * 8192), 16, 0, 0); } while (0)
; #define PG8_LDA(dst, b, h) do { _Pragma("unroll") for (int m = 0; m < 4; ++m) _Pragma("unroll") for (int k = 0; k < 2; ++k) dst[m][k] = *(const PG8_LAS bf16x8*)(lds + PG8_SA(b, h) + aoff + m * 2048 + k * 1024); } while (0)
; #define PG8_MMA(ai, bj, At, Bt) do { __builtin_amdgcn_s_setprio(1); _Pragma("unroll") for (int m = 0; m < 4; ++m) _Pragma("unroll") for (int n = 0; n < 2; ++n) _Pragma("unroll") for (int k = 0; k < 2; ++k) \
;         acc[ai][bj][m][n] = __builtin_amdgcn_mfma_f32_16x16x32_bf16(Bt[n][k], At[m][k], acc[ai][bj][m][n], 0, 0, 0); __builtin_amdgcn_s_setprio(0); } while (0)
; #define PG8_WAIT_V(n) asm volatile("s_waitcnt vmcnt(" #n ")" ::: "memory")
; #define PG8_WAIT_L(n) asm volatile("s_waitcnt lgkmcnt(" #n ")" ::: "memory")
; #define PG8_BAR __builtin_amdgcn_s_barrier()
; #define PG8_SCHED __builtin_amdgcn_sched_barrier(0)
; template <class Epi, class Sched, bool ALIGN_EPI = false, bool SP2 = false>
; __device__ __forceinline__ void gemm_phase(PG8_LAS unsigned char* lds, const Gemm g, const Sched& S, const Epi& E) {
;     ...
;             PG8_LDA(At, 1, 1); PG8_STAGE(PG8_SB(1, 0), b3, voffB); PG8_STAGE(PG8_SB(1, 1), b3 + hstep, voffB); PG8_STAGE(PG8_SA(1, 0), a3, voffA);
;             PG8_WAIT_V(8); PG8_WAIT_L(0); PG8_BAR; PG8_MMA(1, 0, At, B0); PG8_MMA(1, 1, At, B1); PG8_BAR; PG8_SCHED;
	s_add_i32 s19, s19, s14
	v_lshl_add_u64 v[204:205], v[204:205], 0, s[8:9]
	s_mov_b32 m0, s19
	ds_read_b128 v[188:191], v152 offset:49152
	ds_read_b128 v[192:195], v152 offset:50176
	ds_read_b128 v[196:199], v152 offset:51200
	ds_read_b128 v[200:203], v152 offset:52224
	ds_read_b128 v[208:211], v152 offset:53248
	ds_read_b128 v[212:215], v152 offset:54272
	ds_read_b128 v[216:219], v152 offset:55296
	ds_read_b128 v[220:223], v152 offset:56320
	global_load_lds_dwordx4 v[204:205], off
	s_add_i32 m0, s19, 0x2000
	s_add_u32 s46, s46, 0x40080
	v_lshl_add_u64 v[204:205], v[224:225], 0, s[8:9]
	s_addc_u32 s47, s47, 0
	s_add_i32 s19, s70, s14
	global_load_lds_dwordx4 v[204:205], off
	v_lshl_add_u64 v[204:205], s[46:47], 0, v[132:133]
	s_mov_b32 m0, s19
	s_nop 0
	global_load_lds_dwordx4 v[204:205], off
	v_lshl_add_u64 v[204:205], s[46:47], 0, v[128:129]
	s_add_i32 m0, s19, 0x2000
	s_nop 0
	global_load_lds_dwordx4 v[204:205], off
	v_lshl_add_u64 v[204:205], v[226:227], 0, s[8:9]
	s_mov_b32 m0, s51
	s_nop 0
	global_load_lds_dwordx4 v[204:205], off
	v_lshl_add_u64 v[204:205], v[228:229], 0, s[8:9]
	s_mov_b32 m0, s52
	s_nop 0
	global_load_lds_dwordx4 v[204:205], off
	s_waitcnt vmcnt(8)
	s_waitcnt lgkmcnt(0)
	s_barrier
	s_setprio 1
	s_waitcnt lgkmcnt(0)
	v_mfma_f32_16x16x32_bf16 v[60:63], v[156:159], v[188:191], v[60:63]
	v_mfma_f32_16x16x32_bf16 v[52:55], v[164:167], v[188:191], v[52:55]
	v_mfma_f32_16x16x32_bf16 v[44:47], v[156:159], v[196:199], v[44:47]
	v_mfma_f32_16x16x32_bf16 v[36:39], v[164:167], v[196:199], v[36:39]
	v_mfma_f32_16x16x32_bf16 v[28:31], v[156:159], v[208:211], v[28:31]
	v_mfma_f32_16x16x32_bf16 v[20:23], v[164:167], v[208:211], v[20:23]
	v_mfma_f32_16x16x32_bf16 v[12:15], v[156:159], v[216:219], v[12:15]
	v_mfma_f32_16x16x32_bf16 v[4:7], v[164:167], v[216:219], v[4:7]
	v_mfma_f32_16x16x32_bf16 v[60:63], v[160:163], v[192:195], v[60:63]
	v_mfma_f32_16x16x32_bf16 v[52:55], v[168:171], v[192:195], v[52:55]
	v_mfma_f32_16x16x32_bf16 v[44:47], v[160:163], v[200:203], v[44:47]
	v_mfma_f32_16x16x32_bf16 v[36:39], v[168:171], v[200:203], v[36:39]
	v_mfma_f32_16x16x32_bf16 v[28:31], v[160:163], v[212:215], v[28:31]
	v_mfma_f32_16x16x32_bf16 v[20:23], v[168:171], v[212:215], v[20:23]
	v_mfma_f32_16x16x32_bf16 v[12:15], v[160:163], v[220:223], v[12:15]
	v_mfma_f32_16x16x32_bf16 v[4:7], v[168:171], v[220:223], v[4:7]
	v_mfma_f32_16x16x32_bf16 v[56:59], v[172:175], v[188:191], v[56:59]
	v_mfma_f32_16x16x32_bf16 v[48:51], v[180:183], v[188:191], v[48:51]
	v_mfma_f32_16x16x32_bf16 v[40:43], v[172:175], v[196:199], v[40:43]
	v_mfma_f32_16x16x32_bf16 v[32:35], v[180:183], v[196:199], v[32:35]
	v_mfma_f32_16x16x32_bf16 v[24:27], v[172:175], v[208:211], v[24:27]
	v_mfma_f32_16x16x32_bf16 v[16:19], v[180:183], v[208:211], v[16:19]
	v_mfma_f32_16x16x32_bf16 v[8:11], v[172:175], v[216:219], v[8:11]
	v_mfma_f32_16x16x32_bf16 v[0:3], v[180:183], v[216:219], v[0:3]
	v_mfma_f32_16x16x32_bf16 v[56:59], v[176:179], v[192:195], v[56:59]
	v_mfma_f32_16x16x32_bf16 v[48:51], v[184:187], v[192:195], v[48:51]
	v_mfma_f32_16x16x32_bf16 v[40:43], v[176:179], v[200:203], v[40:43]
	v_mfma_f32_16x16x32_bf16 v[32:35], v[184:187], v[200:203], v[32:35]
	v_mfma_f32_16x16x32_bf16 v[24:27], v[176:179], v[212:215], v[24:27]
	v_mfma_f32_16x16x32_bf16 v[16:19], v[184:187], v[212:215], v[16:19]
	v_mfma_f32_16x16x32_bf16 v[8:11], v[176:179], v[220:223], v[8:11]
	v_mfma_f32_16x16x32_bf16 v[0:3], v[184:187], v[220:223], v[0:3]
	s_setprio 0
	s_barrier
	s_add_i32 s67, s67, 2
	s_add_u32 s0, s0, 0x100
	s_addc_u32 s1, s1, 0
	s_add_u32 s65, s65, 0x100
	s_addc_u32 s66, s66, 0
	s_cmp_gt_u32 s67, 13
	s_cbranch_scc0 .LBB0_567

; #define PG8_STAGE(bufoff, gbase, voff) do { _Pragma("unroll") for (int _i = 0; _i < 2; ++_i) \
;         __builtin_amdgcn_global_load_lds((const unsigned*)((const char*)(gbase) + (voff)[_i]), (PG8_LAS unsigned*)(lds + (bufoff) + ldsw + _i * 8192), 16, 0, 0); } while (0)
; #define PG8_LDA(dst, b, h) do { _Pragma("unroll") for (int m = 0; m < 4; ++m) _Pragma("unroll") for (int k = 0; k < 2; ++k) dst[m][k] = *(const PG8_LAS bf16x8*)(lds + PG8_SA(b, h) + aoff + m * 2048 + k * 1024); } while (0)
; #define PG8_LDB(dst, b, h) do { _Pragma("unroll") for (int n = 0; n < 2; ++n) _Pragma("unroll") for (int k = 0; k < 2; ++k) dst[n][k] = *(const PG8_LAS bf16x8*)(lds + PG8_SB(b, h) + boff + n * 2048 + k * 1024); } while (0)
; #define PG8_MMA(ai, bj, At, Bt) do { __builtin_amdgcn_s_setprio(1); _Pragma("unroll") for (int m = 0; m < 4; ++m) _Pragma("unroll") for (int n = 0; n < 2; ++n) _Pragma("unroll") for (int k = 0; k < 2; ++k) \
;         acc[ai][bj][m][n] = __builtin_amdgcn_mfma_f32_16x16x32_bf16(Bt[n][k], At[m][k], acc[ai][bj][m][n], 0, 0, 0); __builtin_amdgcn_s_setprio(0); } while (0)
; #define PG8_WAIT_V(n) asm volatile("s_waitcnt vmcnt(" #n ")" ::: "memory")
; #define PG8_WAIT_L(n) asm volatile("s_waitcnt lgkmcnt(" #n ")" ::: "memory")
; #define PG8_BAR __builtin_amdgcn_s_barrier()
; #define PG8_SCHED __builtin_amdgcn_sched_barrier(0)
; template <class Epi, class Sched, bool ALIGN_EPI = false, bool SP2 = false>
; __device__ __forceinline__ void gemm_phase(PG8_LAS unsigned char* lds, const Gemm g, const Sched& S, const Epi& E) {
;     ...
;             PG8_LDB(B0, 0, 0); PG8_LDB(B1, 0, 1); PG8_SCHED; PG8_LDA(At, 0, 0); PG8_STAGE(PG8_SA(1, 1), a1 + hstep, voffA);
;             PG8_WAIT_V(8); PG8_WAIT_L(0); PG8_BAR; PG8_MMA(0, 0, At, B0); PG8_MMA(0, 1, At, B1); PG8_BAR; PG8_SCHED;
;             PG8_LDA(At, 0, 1); PG8_STAGE(PG8_SB(0, 0), b2, voffB); PG8_STAGE(PG8_SB(0, 1), b2 + hstep, voffB); PG8_STAGE(PG8_SA(0, 0), a2, voffA);
;             PG8_WAIT_V(8); PG8_WAIT_L(0); PG8_BAR; PG8_MMA(1, 0, At, B0); PG8_MMA(1, 1, At, B1); PG8_BAR; PG8_SCHED;
.LBB0_651:
	ds_read_b128 v[144:147], v153
	ds_read_b128 v[156:159], v153 offset:1024
	ds_read_b128 v[160:163], v153 offset:2048
	ds_read_b128 v[164:167], v153 offset:3072
	ds_read_b128 v[168:171], v154
	ds_read_b128 v[172:175], v154 offset:1024
	ds_read_b128 v[176:179], v154 offset:2048
	ds_read_b128 v[180:183], v154 offset:3072
	s_add_u32 s19, s48, 0xfff50080
	s_addc_u32 s50, s49, -1
	s_cmp_eq_u32 s67, 40
	s_cselect_b32 s53, s1, s50
	s_cselect_b32 s52, s0, s19
	s_cselect_b32 s51, s47, s66
	s_cselect_b32 s50, s46, s65
	v_lshl_add_u64 v[148:149], s[48:49], 0, v[136:137]
	s_add_i32 m0, s18, 0xc000
	ds_read_b128 v[184:187], v155
	ds_read_b128 v[188:191], v155 offset:1024
	ds_read_b128 v[192:195], v155 offset:2048
	ds_read_b128 v[196:199], v155 offset:3072
	ds_read_b128 v[200:203], v155 offset:4096
	ds_read_b128 v[208:211], v155 offset:5120
	ds_read_b128 v[212:215], v155 offset:6144
	ds_read_b128 v[216:219], v155 offset:7168
	global_load_lds_dwordx4 v[148:149], off
	v_lshl_add_u64 v[148:149], s[48:49], 0, v[138:139]
	s_add_i32 m0, s18, 0xe000
	s_nop 0
	global_load_lds_dwordx4 v[148:149], off
	s_waitcnt vmcnt(8)
	s_waitcnt lgkmcnt(0)
	s_barrier
	s_setprio 1
	s_waitcnt lgkmcnt(0)
	v_mfma_f32_16x16x32_bf16 v[124:127], v[144:147], v[184:187], v[124:127]
	v_mfma_f32_16x16x32_bf16 v[120:123], v[160:163], v[184:187], v[120:123]
	v_mfma_f32_16x16x32_bf16 v[108:111], v[144:147], v[192:195], v[108:111]
	v_mfma_f32_16x16x32_bf16 v[104:107], v[160:163], v[192:195], v[104:107]
	v_mfma_f32_16x16x32_bf16 v[92:95], v[144:147], v[200:203], v[92:95]
	v_mfma_f32_16x16x32_bf16 v[88:91], v[160:163], v[200:203], v[88:91]
	v_mfma_f32_16x16x32_bf16 v[76:79], v[144:147], v[212:215], v[76:79]
	v_mfma_f32_16x16x32_bf16 v[72:75], v[160:163], v[212:215], v[72:75]
	v_mfma_f32_16x16x32_bf16 v[124:127], v[156:159], v[188:191], v[124:127]
	v_mfma_f32_16x16x32_bf16 v[120:123], v[164:167], v[188:191], v[120:123]
	v_mfma_f32_16x16x32_bf16 v[108:111], v[156:159], v[196:199], v[108:111]
	v_mfma_f32_16x16x32_bf16 v[104:107], v[164:167], v[196:199], v[104:107]
	v_mfma_f32_16x16x32_bf16 v[92:95], v[156:159], v[208:211], v[92:95]
	v_mfma_f32_16x16x32_bf16 v[88:91], v[164:167], v[208:211], v[88:91]
	v_mfma_f32_16x16x32_bf16 v[76:79], v[156:159], v[216:219], v[76:79]
	v_mfma_f32_16x16x32_bf16 v[72:75], v[164:167], v[216:219], v[72:75]
	v_mfma_f32_16x16x32_bf16 v[116:119], v[168:171], v[184:187], v[116:119]
	v_mfma_f32_16x16x32_bf16 v[112:115], v[176:179], v[184:187], v[112:115]
	v_mfma_f32_16x16x32_bf16 v[100:103], v[168:171], v[192:195], v[100:103]
	v_mfma_f32_16x16x32_bf16 v[96:99], v[176:179], v[192:195], v[96:99]
	v_mfma_f32_16x16x32_bf16 v[84:87], v[168:171], v[200:203], v[84:87]
	v_mfma_f32_16x16x32_bf16 v[80:83], v[176:179], v[200:203], v[80:83]
	v_mfma_f32_16x16x32_bf16 v[68:71], v[168:171], v[212:215], v[68:71]
	v_mfma_f32_16x16x32_bf16 v[64:67], v[176:179], v[212:215], v[64:67]
	v_mfma_f32_16x16x32_bf16 v[116:119], v[172:175], v[188:191], v[116:119]
	v_mfma_f32_16x16x32_bf16 v[112:115], v[180:183], v[188:191], v[112:115]
	v_mfma_f32_16x16x32_bf16 v[100:103], v[172:175], v[196:199], v[100:103]
	v_mfma_f32_16x16x32_bf16 v[96:99], v[180:183], v[196:199], v[96:99]
	v_mfma_f32_16x16x32_bf16 v[84:87], v[172:175], v[208:211], v[84:87]
	v_mfma_f32_16x16x32_bf16 v[80:83], v[180:183], v[208:211], v[80:83]
	v_mfma_f32_16x16x32_bf16 v[68:71], v[172:175], v[216:219], v[68:71]
	v_mfma_f32_16x16x32_bf16 v[64:67], v[180:183], v[216:219], v[64:67]
	s_setprio 0
	s_barrier
	s_add_i32 s19, s59, s15
	v_lshl_add_u64 v[148:149], s[50:51], 0, v[130:131]
	s_mov_b32 m0, s19
	ds_read_b128 v[184:187], v155 offset:16384
	ds_read_b128 v[188:191], v155 offset:17408
	ds_read_b128 v[192:195], v155 offset:18432
	ds_read_b128 v[196:199], v155 offset:19456
	ds_read_b128 v[200:203], v155 offset:20480
	ds_read_b128 v[208:211], v155 offset:21504
	ds_read_b128 v[212:215], v155 offset:22528
	ds_read_b128 v[216:219], v155 offset:23552
	global_load_lds_dwordx4 v[148:149], off
	s_add_i32 m0, s19, 0x2000
	s_add_u32 s70, s50, 0xb0000
	v_lshl_add_u64 v[204:205], s[50:51], 0, v[134:135]
	s_addc_u32 s71, s51, 0
	s_add_i32 s19, s60, s15
	global_load_lds_dwordx4 v[204:205], off
	v_lshl_add_u64 v[220:221], s[70:71], 0, v[130:131]
	s_mov_b32 m0, s19
	v_lshl_add_u64 v[222:223], s[52:53], 0, v[132:133]
	global_load_lds_dwordx4 v[220:221], off
	v_lshl_add_u64 v[220:221], s[70:71], 0, v[134:135]
	s_add_i32 m0, s19, 0x2000
	s_nop 0
	global_load_lds_dwordx4 v[220:221], off
	v_lshl_add_u64 v[220:221], s[52:53], 0, v[128:129]
	s_mov_b32 m0, s18
	s_nop 0
	global_load_lds_dwordx4 v[220:221], off
	s_mov_b32 m0, s23
	s_nop 0
	global_load_lds_dwordx4 v[222:223], off
	s_waitcnt vmcnt(8)
	s_waitcnt lgkmcnt(0)
	s_barrier
; #define PG8_STAGE(bufoff, gbase, voff) do { _Pragma("unroll") for (int _i = 0; _i < 2; ++_i) \
;         __builtin_amdgcn_global_load_lds((const unsigned*)((const char*)(gbase) + (voff)[_i]), (PG8_LAS unsigned*)(lds + (bufoff) + ldsw + _i * 8192), 16, 0, 0); } while (0)
; #define PG8_LDA(dst, b, h) do { _Pragma("unroll") for (int m = 0; m < 4; ++m) _Pragma("unroll") for (int k = 0; k < 2; ++k) dst[m][k] = *(const PG8_LAS bf16x8*)(lds + PG8_SA(b, h) + aoff + m * 2048 + k * 1024); } while (0)
; #define PG8_LDB(dst, b, h) do { _Pragma("unroll") for (int n = 0; n < 2; ++n) _Pragma("unroll") for (int k = 0; k < 2; ++k) dst[n][k] = *(const PG8_LAS bf16x8*)(lds + PG8_SB(b, h) + boff + n * 2048 + k * 1024); } while (0)
; #define PG8_MMA(ai, bj, At, Bt) do { __builtin_amdgcn_s_setprio(1); _Pragma("unroll") for (int m = 0; m < 4; ++m) _Pragma("unroll") for (int n = 0; n < 2; ++n) _Pragma("unroll") for (int k = 0; k < 2; ++k) \
;         acc[ai][bj][m][n] = __builtin_amdgcn_mfma_f32_16x16x32_bf16(Bt[n][k], At[m][k], acc[ai][bj][m][n], 0, 0, 0); __builtin_amdgcn_s_setprio(0); } while (0)
; #define PG8_WAIT_V(n) asm volatile("s_waitcnt vmcnt(" #n ")" ::: "memory")
; #define PG8_WAIT_L(n) asm volatile("s_waitcnt lgkmcnt(" #n ")" ::: "memory")
; #define PG8_BAR __builtin_amdgcn_s_barrier()
; #define PG8_SCHED __builtin_amdgcn_sched_barrier(0)
; template <class Epi, class Sched, bool ALIGN_EPI = false, bool SP2 = false>
; __device__ __forceinline__ void gemm_phase(PG8_LAS unsigned char* lds, const Gemm g, const Sched& S, const Epi& E) {
;     ...
;             PG8_WAIT_V(8); PG8_WAIT_L(0); PG8_BAR; PG8_MMA(1, 0, At, B0); PG8_MMA(1, 1, At, B1); PG8_BAR; PG8_SCHED;
;             PG8_LDB(B0, 1, 0); PG8_LDB(B1, 1, 1); PG8_SCHED; PG8_LDA(At, 1, 0); PG8_STAGE(PG8_SA(0, 1), a2 + hstep, voffA);
;             PG8_WAIT_V(8); PG8_WAIT_L(0); PG8_BAR; PG8_MMA(0, 0, At, B0); PG8_MMA(0, 1, At, B1); PG8_BAR; PG8_SCHED;
	s_setprio 1
	s_waitcnt lgkmcnt(0)
	v_mfma_f32_16x16x32_bf16 v[60:63], v[144:147], v[184:187], v[60:63]
	v_mfma_f32_16x16x32_bf16 v[56:59], v[160:163], v[184:187], v[56:59]
	v_mfma_f32_16x16x32_bf16 v[44:47], v[144:147], v[192:195], v[44:47]
	v_mfma_f32_16x16x32_bf16 v[40:43], v[160:163], v[192:195], v[40:43]
	v_mfma_f32_16x16x32_bf16 v[28:31], v[144:147], v[200:203], v[28:31]
	v_mfma_f32_16x16x32_bf16 v[24:27], v[160:163], v[200:203], v[24:27]
	v_mfma_f32_16x16x32_bf16 v[12:15], v[144:147], v[212:215], v[12:15]
	v_mfma_f32_16x16x32_bf16 v[8:11], v[160:163], v[212:215], v[8:11]
	v_mfma_f32_16x16x32_bf16 v[60:63], v[156:159], v[188:191], v[60:63]
	v_mfma_f32_16x16x32_bf16 v[56:59], v[164:167], v[188:191], v[56:59]
	v_mfma_f32_16x16x32_bf16 v[44:47], v[156:159], v[196:199], v[44:47]
	v_mfma_f32_16x16x32_bf16 v[40:43], v[164:167], v[196:199], v[40:43]
	v_mfma_f32_16x16x32_bf16 v[28:31], v[156:159], v[208:211], v[28:31]
	v_mfma_f32_16x16x32_bf16 v[24:27], v[164:167], v[208:211], v[24:27]
	v_mfma_f32_16x16x32_bf16 v[12:15], v[156:159], v[216:219], v[12:15]
	v_mfma_f32_16x16x32_bf16 v[8:11], v[164:167], v[216:219], v[8:11]
	v_mfma_f32_16x16x32_bf16 v[52:55], v[168:171], v[184:187], v[52:55]
	v_mfma_f32_16x16x32_bf16 v[48:51], v[176:179], v[184:187], v[48:51]
	v_mfma_f32_16x16x32_bf16 v[36:39], v[168:171], v[192:195], v[36:39]
	v_mfma_f32_16x16x32_bf16 v[32:35], v[176:179], v[192:195], v[32:35]
	v_mfma_f32_16x16x32_bf16 v[20:23], v[168:171], v[200:203], v[20:23]
	v_mfma_f32_16x16x32_bf16 v[16:19], v[176:179], v[200:203], v[16:19]
	v_mfma_f32_16x16x32_bf16 v[4:7], v[168:171], v[212:215], v[4:7]
	v_mfma_f32_16x16x32_bf16 v[0:3], v[176:179], v[212:215], v[0:3]
	v_mfma_f32_16x16x32_bf16 v[52:55], v[172:175], v[188:191], v[52:55]
	v_mfma_f32_16x16x32_bf16 v[48:51], v[180:183], v[188:191], v[48:51]
	v_mfma_f32_16x16x32_bf16 v[36:39], v[172:175], v[196:199], v[36:39]
	v_mfma_f32_16x16x32_bf16 v[32:35], v[180:183], v[196:199], v[32:35]
	v_mfma_f32_16x16x32_bf16 v[20:23], v[172:175], v[208:211], v[20:23]
	v_mfma_f32_16x16x32_bf16 v[16:19], v[180:183], v[208:211], v[16:19]
	v_mfma_f32_16x16x32_bf16 v[4:7], v[172:175], v[216:219], v[4:7]
	v_mfma_f32_16x16x32_bf16 v[0:3], v[180:183], v[216:219], v[0:3]
	s_setprio 0
	s_barrier
	s_add_i32 s19, 0, 0x18000
	s_add_i32 s70, 0, 0x1c000
	v_add_u32_e32 v164, s19, v151
	v_add_u32_e32 v180, s70, v151
	ds_read_b128 v[144:147], v164
	ds_read_b128 v[156:159], v164 offset:1024
	ds_read_b128 v[160:163], v164 offset:2048
	ds_read_b128 v[164:167], v164 offset:3072
	ds_read_b128 v[168:171], v180
	ds_read_b128 v[172:175], v180 offset:1024
	ds_read_b128 v[176:179], v180 offset:2048
	ds_read_b128 v[180:183], v180 offset:3072
	s_add_u32 s52, s52, 0xb0000
	s_addc_u32 s53, s53, 0
	s_mov_b32 m0, s33
	v_lshl_add_u64 v[224:225], s[52:53], 0, v[128:129]
	ds_read_b128 v[184:187], v155 offset:32768
	ds_read_b128 v[188:191], v155 offset:33792
	ds_read_b128 v[192:195], v155 offset:34816
	ds_read_b128 v[196:199], v155 offset:35840
	ds_read_b128 v[200:203], v155 offset:36864
	ds_read_b128 v[208:211], v155 offset:37888
	ds_read_b128 v[212:215], v155 offset:38912
	ds_read_b128 v[216:219], v155 offset:39936
	global_load_lds_dwordx4 v[224:225], off
	v_lshl_add_u64 v[224:225], s[52:53], 0, v[132:133]
	s_mov_b32 m0, s35
	s_nop 0
	global_load_lds_dwordx4 v[224:225], off
	s_waitcnt vmcnt(8)
	s_waitcnt lgkmcnt(0)
	s_barrier
	s_setprio 1
	s_waitcnt lgkmcnt(0)
	v_mfma_f32_16x16x32_bf16 v[124:127], v[144:147], v[184:187], v[124:127]
	v_mfma_f32_16x16x32_bf16 v[120:123], v[160:163], v[184:187], v[120:123]
	v_mfma_f32_16x16x32_bf16 v[108:111], v[144:147], v[192:195], v[108:111]
	v_mfma_f32_16x16x32_bf16 v[104:107], v[160:163], v[192:195], v[104:107]
	v_mfma_f32_16x16x32_bf16 v[92:95], v[144:147], v[200:203], v[92:95]
	v_mfma_f32_16x16x32_bf16 v[88:91], v[160:163], v[200:203], v[88:91]
	v_mfma_f32_16x16x32_bf16 v[76:79], v[144:147], v[212:215], v[76:79]
	v_mfma_f32_16x16x32_bf16 v[72:75], v[160:163], v[212:215], v[72:75]
	v_mfma_f32_16x16x32_bf16 v[124:127], v[156:159], v[188:191], v[124:127]
	v_mfma_f32_16x16x32_bf16 v[120:123], v[164:167], v[188:191], v[120:123]
	v_mfma_f32_16x16x32_bf16 v[108:111], v[156:159], v[196:199], v[108:111]
	v_mfma_f32_16x16x32_bf16 v[104:107], v[164:167], v[196:199], v[104:107]
	v_mfma_f32_16x16x32_bf16 v[92:95], v[156:159], v[208:211], v[92:95]
	v_mfma_f32_16x16x32_bf16 v[88:91], v[164:167], v[208:211], v[88:91]
	v_mfma_f32_16x16x32_bf16 v[76:79], v[156:159], v[216:219], v[76:79]
	v_mfma_f32_16x16x32_bf16 v[72:75], v[164:167], v[216:219], v[72:75]
	v_mfma_f32_16x16x32_bf16 v[116:119], v[168:171], v[184:187], v[116:119]
	v_mfma_f32_16x16x32_bf16 v[112:115], v[176:179], v[184:187], v[112:115]
	v_mfma_f32_16x16x32_bf16 v[100:103], v[168:171], v[192:195], v[100:103]
	v_mfma_f32_16x16x32_bf16 v[96:99], v[176:179], v[192:195], v[96:99]
	v_mfma_f32_16x16x32_bf16 v[84:87], v[168:171], v[200:203], v[84:87]
	v_mfma_f32_16x16x32_bf16 v[80:83], v[176:179], v[200:203], v[80:83]
	v_mfma_f32_16x16x32_bf16 v[68:71], v[168:171], v[212:215], v[68:71]
	v_mfma_f32_16x16x32_bf16 v[64:67], v[176:179], v[212:215], v[64:67]
	v_mfma_f32_16x16x32_bf16 v[116:119], v[172:175], v[188:191], v[116:119]
	v_mfma_f32_16x16x32_bf16 v[112:115], v[180:183], v[188:191], v[112:115]
	v_mfma_f32_16x16x32_bf16 v[100:103], v[172:175], v[196:199], v[100:103]
	v_mfma_f32_16x16x32_bf16 v[96:99], v[180:183], v[196:199], v[96:99]
	v_mfma_f32_16x16x32_bf16 v[84:87], v[172:175], v[208:211], v[84:87]
	v_mfma_f32_16x16x32_bf16 v[80:83], v[180:183], v[208:211], v[80:83]
	v_mfma_f32_16x16x32_bf16 v[68:71], v[172:175], v[216:219], v[68:71]
	v_mfma_f32_16x16x32_bf16 v[64:67], v[180:183], v[216:219], v[64:67]
	s_setprio 0
	s_barrier
; #define PG8_STAGE(bufoff, gbase, voff) do { _Pragma("unroll") for (int _i = 0; _i < 2; ++_i) \
;         __builtin_amdgcn_global_load_lds((const unsigned*)((const char*)(gbase) + (voff)[_i]), (PG8_LAS unsigned*)(lds + (bufoff) + ldsw + _i * 8192), 16, 0, 0); } while (0)
; #define PG8_LDA(dst, b, h) do { _Pragma("unroll") for (int m = 0; m < 4; ++m) _Pragma("unroll") for (int k = 0; k < 2; ++k) dst[m][k] = *(const PG8_LAS bf16x8*)(lds + PG8_SA(b, h) + aoff + m * 2048 + k * 1024); } while (0)
; #define PG8_MMA(ai, bj, At, Bt) do { __builtin_amdgcn_s_setprio(1); _Pragma("unroll") for (int m = 0; m < 4; ++m) _Pragma("unroll") for (int n = 0; n < 2; ++n) _Pragma("unroll") for (int k = 0; k < 2; ++k) \
;         acc[ai][bj][m][n] = __builtin_amdgcn_mfma_f32_16x16x32_bf16(Bt[n][k], At[m][k], acc[ai][bj][m][n], 0, 0, 0); __builtin_amdgcn_s_setprio(0); } while (0)
; #define PG8_WAIT_V(n) asm volatile("s_waitcnt vmcnt(" #n ")" ::: "memory")
; #define PG8_WAIT_L(n) asm volatile("s_waitcnt lgkmcnt(" #n ")" ::: "memory")
; #define PG8_BAR __builtin_amdgcn_s_barrier()
; #define PG8_SCHED __builtin_amdgcn_sched_barrier(0)
; template <class Epi, class Sched, bool ALIGN_EPI = false, bool SP2 = false>
; __device__ __forceinline__ void gemm_phase(PG8_LAS unsigned char* lds, const Gemm g, const Sched& S, const Epi& E) {
;     ...
;             PG8_LDA(At, 1, 1); PG8_STAGE(PG8_SB(1, 0), b3, voffB); PG8_STAGE(PG8_SB(1, 1), b3 + hstep, voffB); PG8_STAGE(PG8_SA(1, 0), a3, voffA);
;             PG8_WAIT_V(8); PG8_WAIT_L(0); PG8_BAR; PG8_MMA(1, 0, At, B0); PG8_MMA(1, 1, At, B1); PG8_BAR; PG8_SCHED;
;     ...
;         if constexpr (ALIGN_EPI) { if (wr == 0) PG8_BAR; }
	s_add_i32 s19, s19, s15
	v_lshl_add_u64 v[148:149], v[148:149], 0, s[6:7]
	s_mov_b32 m0, s19
	ds_read_b128 v[184:187], v155 offset:49152
	ds_read_b128 v[188:191], v155 offset:50176
	ds_read_b128 v[192:195], v155 offset:51200
	ds_read_b128 v[196:199], v155 offset:52224
	ds_read_b128 v[200:203], v155 offset:53248
	ds_read_b128 v[208:211], v155 offset:54272
	ds_read_b128 v[212:215], v155 offset:55296
	ds_read_b128 v[216:219], v155 offset:56320
	global_load_lds_dwordx4 v[148:149], off
	s_add_i32 m0, s19, 0x2000
	s_add_u32 s50, s50, 0xb0080
	v_lshl_add_u64 v[148:149], v[204:205], 0, s[6:7]
	s_addc_u32 s51, s51, 0
	s_add_i32 s19, s70, s15
	global_load_lds_dwordx4 v[148:149], off
	v_lshl_add_u64 v[148:149], s[50:51], 0, v[130:131]
	s_mov_b32 m0, s19
	s_nop 0
	global_load_lds_dwordx4 v[148:149], off
	v_lshl_add_u64 v[148:149], s[50:51], 0, v[134:135]
	s_add_i32 m0, s19, 0x2000
	s_nop 0
	global_load_lds_dwordx4 v[148:149], off
	v_lshl_add_u64 v[148:149], v[220:221], 0, s[6:7]
	s_mov_b32 m0, s55
	s_nop 0
	global_load_lds_dwordx4 v[148:149], off
	v_lshl_add_u64 v[148:149], v[222:223], 0, s[6:7]
	s_mov_b32 m0, s56
	s_nop 0
	global_load_lds_dwordx4 v[148:149], off
	s_waitcnt vmcnt(8)
	s_waitcnt lgkmcnt(0)
	s_barrier
	s_setprio 1
	s_waitcnt lgkmcnt(0)
	v_mfma_f32_16x16x32_bf16 v[60:63], v[144:147], v[184:187], v[60:63]
	v_mfma_f32_16x16x32_bf16 v[56:59], v[160:163], v[184:187], v[56:59]
	v_mfma_f32_16x16x32_bf16 v[44:47], v[144:147], v[192:195], v[44:47]
	v_mfma_f32_16x16x32_bf16 v[40:43], v[160:163], v[192:195], v[40:43]
	v_mfma_f32_16x16x32_bf16 v[28:31], v[144:147], v[200:203], v[28:31]
	v_mfma_f32_16x16x32_bf16 v[24:27], v[160:163], v[200:203], v[24:27]
	v_mfma_f32_16x16x32_bf16 v[12:15], v[144:147], v[212:215], v[12:15]
	v_mfma_f32_16x16x32_bf16 v[8:11], v[160:163], v[212:215], v[8:11]
	v_mfma_f32_16x16x32_bf16 v[60:63], v[156:159], v[188:191], v[60:63]
	v_mfma_f32_16x16x32_bf16 v[56:59], v[164:167], v[188:191], v[56:59]
	v_mfma_f32_16x16x32_bf16 v[44:47], v[156:159], v[196:199], v[44:47]
	v_mfma_f32_16x16x32_bf16 v[40:43], v[164:167], v[196:199], v[40:43]
	v_mfma_f32_16x16x32_bf16 v[28:31], v[156:159], v[208:211], v[28:31]
	v_mfma_f32_16x16x32_bf16 v[24:27], v[164:167], v[208:211], v[24:27]
	v_mfma_f32_16x16x32_bf16 v[12:15], v[156:159], v[216:219], v[12:15]
	v_mfma_f32_16x16x32_bf16 v[8:11], v[164:167], v[216:219], v[8:11]
	v_mfma_f32_16x16x32_bf16 v[52:55], v[168:171], v[184:187], v[52:55]
	v_mfma_f32_16x16x32_bf16 v[48:51], v[176:179], v[184:187], v[48:51]
	v_mfma_f32_16x16x32_bf16 v[36:39], v[168:171], v[192:195], v[36:39]
	v_mfma_f32_16x16x32_bf16 v[32:35], v[176:179], v[192:195], v[32:35]
	v_mfma_f32_16x16x32_bf16 v[20:23], v[168:171], v[200:203], v[20:23]
	v_mfma_f32_16x16x32_bf16 v[16:19], v[176:179], v[200:203], v[16:19]
	v_mfma_f32_16x16x32_bf16 v[4:7], v[168:171], v[212:215], v[4:7]
	v_mfma_f32_16x16x32_bf16 v[0:3], v[176:179], v[212:215], v[0:3]
	v_mfma_f32_16x16x32_bf16 v[52:55], v[172:175], v[188:191], v[52:55]
	v_mfma_f32_16x16x32_bf16 v[48:51], v[180:183], v[188:191], v[48:51]
	v_mfma_f32_16x16x32_bf16 v[36:39], v[172:175], v[196:199], v[36:39]
	v_mfma_f32_16x16x32_bf16 v[32:35], v[180:183], v[196:199], v[32:35]
	v_mfma_f32_16x16x32_bf16 v[20:23], v[172:175], v[208:211], v[20:23]
	v_mfma_f32_16x16x32_bf16 v[16:19], v[180:183], v[208:211], v[16:19]
	v_mfma_f32_16x16x32_bf16 v[4:7], v[172:175], v[216:219], v[4:7]
	v_mfma_f32_16x16x32_bf16 v[0:3], v[180:183], v[216:219], v[0:3]
	s_setprio 0
	s_barrier
	s_add_i32 s67, s67, 2
	s_add_u32 s48, s48, 0x100
	s_addc_u32 s49, s49, 0
	s_add_u32 s65, s65, 0x100
	s_addc_u32 s66, s66, 0
	s_cmp_gt_u32 s67, 41
	s_cbranch_scc0 .LBB0_651
	s_and_b64 vcc, exec, s[8:9]
	s_cbranch_vccz .LBB0_654
	s_barrier

; #define PG8_STAGE(bufoff, gbase, voff) do { _Pragma("unroll") for (int _i = 0; _i < 2; ++_i) \
;         __builtin_amdgcn_global_load_lds((const unsigned*)((const char*)(gbase) + (voff)[_i]), (PG8_LAS unsigned*)(lds + (bufoff) + ldsw + _i * 8192), 16, 0, 0); } while (0)
; #define PG8_LDA(dst, b, h) do { _Pragma("unroll") for (int m = 0; m < 4; ++m) _Pragma("unroll") for (int k = 0; k < 2; ++k) dst[m][k] = *(const PG8_LAS bf16x8*)(lds + PG8_SA(b, h) + aoff + m * 2048 + k * 1024); } while (0)
; #define PG8_LDB(dst, b, h) do { _Pragma("unroll") for (int n = 0; n < 2; ++n) _Pragma("unroll") for (int k = 0; k < 2; ++k) dst[n][k] = *(const PG8_LAS bf16x8*)(lds + PG8_SB(b, h) + boff + n * 2048 + k * 1024); } while (0)
; #define PG8_WAIT_V(n) asm volatile("s_waitcnt vmcnt(" #n ")" ::: "memory")
; #define PG8_WAIT_L(n) asm volatile("s_waitcnt lgkmcnt(" #n ")" ::: "memory")
; #define PG8_BAR __builtin_amdgcn_s_barrier()
; #define PG8_SCHED __builtin_amdgcn_sched_barrier(0)
; template <class Epi, class Sched, bool ALIGN_EPI = false, bool SP2 = false>
; __device__ __forceinline__ void gemm_phase(PG8_LAS unsigned char* lds, const Gemm g, const Sched& S, const Epi& E) {
;     ...
;         const bool has_next = S.next(ui + 1, nxt);
;         const char* nA = has_next ? (const char*)g.A + (size_t)nxt.pm * tstep : cA; const char* nB = has_next ? (const char*)g.Bt + (size_t)nxt.pn * tstep : cB;
;         for (int t = 0; t < nt; t += 2) {
;             const bool last = (t == nt - 2);
;             const char* a1 = cA + (size_t)(t + 1) * kstep;
;             const char* a2 = last ? nA : cA + (size_t)(t + 2) * kstep; const char* b2 = last ? nB : cB + (size_t)(t + 2) * kstep;
;             const char* a3 = a2 + kstep; const char* b3 = b2 + kstep;
;             if (last && has_next) S.a_ready(nxt);
;             if constexpr (SP2) {
;             PG8_LDB(B0, 0, 0); PG8_LDB(B1, 0, 1); PG8_SCHED; PG8_LDA(At, 0, 0); PG8_STAGE(PG8_SA(1, 1), a1 + hstep, voffA);
;             PG8_WAIT_V(8); PG8_WAIT_L(0); PG8_BAR; PG8_MMA(0, 0, At, B0); PG8_MMA(0, 1, At, B1); PG8_BAR; PG8_SCHED;
;             PG8_LDA(At, 0, 1); PG8_STAGE(PG8_SB(0, 0), b2, voffB); PG8_STAGE(PG8_SB(0, 1), b2 + hstep, voffB); PG8_STAGE(PG8_SA(0, 0), a2, voffA);
;             PG8_WAIT_V(8); PG8_WAIT_L(0); PG8_BAR; PG8_MMA(1, 0, At, B0); PG8_MMA(1, 1, At, B1); PG8_BAR; PG8_SCHED;
.LBB0_682:
	s_add_u32 s0, s8, 0xb0080
	s_addc_u32 s1, s9, 0
	s_add_u32 s12, s6, 0x100
	s_addc_u32 s13, s7, 0
	s_mov_b32 s16, -2
	ds_read_b128 v[128:131], v199
	ds_read_b128 v[132:135], v199 offset:1024
	ds_read_b128 v[152:155], v199 offset:2048
	ds_read_b128 v[156:159], v199 offset:3072
	ds_read_b128 v[160:163], v200
	ds_read_b128 v[164:167], v200 offset:1024
	ds_read_b128 v[168:171], v200 offset:2048
	ds_read_b128 v[172:175], v200 offset:3072
	s_add_u32 s6, s0, 0xfff50080
	s_addc_u32 s7, s1, -1
	s_cmp_eq_u32 s16, 40
	s_cselect_b32 s9, s59, s7
	s_cselect_b32 s8, s58, s6
	s_cselect_b32 s7, s61, s13
	s_cselect_b32 s6, s60, s12
	v_lshl_add_u64 v[220:221], s[0:1], 0, v[144:145]
	s_add_i32 m0, s15, 0xc000
	ds_read_b128 v[176:179], v201
	ds_read_b128 v[180:183], v201 offset:1024
	ds_read_b128 v[184:187], v201 offset:2048
	ds_read_b128 v[188:191], v201 offset:3072
	ds_read_b128 v[192:195], v201 offset:4096
	ds_read_b128 v[208:211], v201 offset:5120
	ds_read_b128 v[212:215], v201 offset:6144
	ds_read_b128 v[216:219], v201 offset:7168
	global_load_lds_dwordx4 v[220:221], off
	v_lshl_add_u64 v[220:221], s[0:1], 0, v[146:147]
	s_add_i32 m0, s15, 0xe000
	s_nop 0
	global_load_lds_dwordx4 v[220:221], off
	s_waitcnt vmcnt(8)
	s_waitcnt lgkmcnt(0)
	s_barrier
	s_setprio 1
	s_waitcnt lgkmcnt(0)
	v_mfma_f32_16x16x32_bf16 v[124:127], v[128:131], v[176:179], 0
	v_mfma_f32_16x16x32_bf16 v[120:123], v[152:155], v[176:179], 0
	v_mfma_f32_16x16x32_bf16 v[108:111], v[128:131], v[184:187], 0
	v_mfma_f32_16x16x32_bf16 v[104:107], v[152:155], v[184:187], 0
	v_mfma_f32_16x16x32_bf16 v[92:95], v[128:131], v[192:195], 0
	v_mfma_f32_16x16x32_bf16 v[88:91], v[152:155], v[192:195], 0
	v_mfma_f32_16x16x32_bf16 v[76:79], v[128:131], v[212:215], 0
	v_mfma_f32_16x16x32_bf16 v[72:75], v[152:155], v[212:215], 0
	v_mfma_f32_16x16x32_bf16 v[124:127], v[132:135], v[180:183], v[124:127]
	v_mfma_f32_16x16x32_bf16 v[120:123], v[156:159], v[180:183], v[120:123]
	v_mfma_f32_16x16x32_bf16 v[108:111], v[132:135], v[188:191], v[108:111]
	v_mfma_f32_16x16x32_bf16 v[104:107], v[156:159], v[188:191], v[104:107]
	v_mfma_f32_16x16x32_bf16 v[92:95], v[132:135], v[208:211], v[92:95]
	v_mfma_f32_16x16x32_bf16 v[88:91], v[156:159], v[208:211], v[88:91]
	v_mfma_f32_16x16x32_bf16 v[76:79], v[132:135], v[216:219], v[76:79]
	v_mfma_f32_16x16x32_bf16 v[72:75], v[156:159], v[216:219], v[72:75]
	v_mfma_f32_16x16x32_bf16 v[116:119], v[160:163], v[176:179], 0
	v_mfma_f32_16x16x32_bf16 v[112:115], v[168:171], v[176:179], 0
	v_mfma_f32_16x16x32_bf16 v[100:103], v[160:163], v[184:187], 0
	v_mfma_f32_16x16x32_bf16 v[96:99], v[168:171], v[184:187], 0
	v_mfma_f32_16x16x32_bf16 v[84:87], v[160:163], v[192:195], 0
	v_mfma_f32_16x16x32_bf16 v[80:83], v[168:171], v[192:195], 0
	v_mfma_f32_16x16x32_bf16 v[68:71], v[160:163], v[212:215], 0
	v_mfma_f32_16x16x32_bf16 v[64:67], v[168:171], v[212:215], 0
	v_mfma_f32_16x16x32_bf16 v[116:119], v[164:167], v[180:183], v[116:119]
	v_mfma_f32_16x16x32_bf16 v[112:115], v[172:175], v[180:183], v[112:115]
	v_mfma_f32_16x16x32_bf16 v[100:103], v[164:167], v[188:191], v[100:103]
	v_mfma_f32_16x16x32_bf16 v[96:99], v[172:175], v[188:191], v[96:99]
	v_mfma_f32_16x16x32_bf16 v[84:87], v[164:167], v[208:211], v[84:87]
	v_mfma_f32_16x16x32_bf16 v[80:83], v[172:175], v[208:211], v[80:83]
	v_mfma_f32_16x16x32_bf16 v[68:71], v[164:167], v[216:219], v[68:71]
	v_mfma_f32_16x16x32_bf16 v[64:67], v[172:175], v[216:219], v[64:67]
	s_setprio 0
	s_barrier
	s_add_i32 s17, s64, s14
	v_lshl_add_u64 v[220:221], s[6:7], 0, v[138:139]
	s_mov_b32 m0, s17
	ds_read_b128 v[176:179], v201 offset:16384
	ds_read_b128 v[180:183], v201 offset:17408
	ds_read_b128 v[184:187], v201 offset:18432
	ds_read_b128 v[188:191], v201 offset:19456
	ds_read_b128 v[192:195], v201 offset:20480
	ds_read_b128 v[208:211], v201 offset:21504
	ds_read_b128 v[212:215], v201 offset:22528
	ds_read_b128 v[216:219], v201 offset:23552
	global_load_lds_dwordx4 v[220:221], off
	s_add_i32 m0, s17, 0x2000
	s_add_u32 s20, s6, 0xb0000
	v_lshl_add_u64 v[222:223], s[6:7], 0, v[142:143]
	s_addc_u32 s21, s7, 0
	s_add_i32 s17, s65, s14
	global_load_lds_dwordx4 v[222:223], off
	v_lshl_add_u64 v[224:225], s[20:21], 0, v[138:139]
	s_mov_b32 m0, s17
	v_lshl_add_u64 v[226:227], s[8:9], 0, v[140:141]
	global_load_lds_dwordx4 v[224:225], off
	v_lshl_add_u64 v[224:225], s[20:21], 0, v[142:143]
	s_add_i32 m0, s17, 0x2000
	s_nop 0
	global_load_lds_dwordx4 v[224:225], off
	v_lshl_add_u64 v[224:225], s[8:9], 0, v[136:137]
	s_mov_b32 m0, s15
	s_nop 0
	global_load_lds_dwordx4 v[224:225], off
	s_mov_b32 m0, s18
	s_nop 0
	global_load_lds_dwordx4 v[226:227], off
	s_waitcnt vmcnt(8)
	s_waitcnt lgkmcnt(0)
	s_barrier
; #define PG8_STAGE(bufoff, gbase, voff) do { _Pragma("unroll") for (int _i = 0; _i < 2; ++_i) \
;         __builtin_amdgcn_global_load_lds((const unsigned*)((const char*)(gbase) + (voff)[_i]), (PG8_LAS unsigned*)(lds + (bufoff) + ldsw + _i * 8192), 16, 0, 0); } while (0)
; #define PG8_LDA(dst, b, h) do { _Pragma("unroll") for (int m = 0; m < 4; ++m) _Pragma("unroll") for (int k = 0; k < 2; ++k) dst[m][k] = *(const PG8_LAS bf16x8*)(lds + PG8_SA(b, h) + aoff + m * 2048 + k * 1024); } while (0)
; #define PG8_LDB(dst, b, h) do { _Pragma("unroll") for (int n = 0; n < 2; ++n) _Pragma("unroll") for (int k = 0; k < 2; ++k) dst[n][k] = *(const PG8_LAS bf16x8*)(lds + PG8_SB(b, h) + boff + n * 2048 + k * 1024); } while (0)
; #define PG8_MMA(ai, bj, At, Bt) do { __builtin_amdgcn_s_setprio(1); _Pragma("unroll") for (int m = 0; m < 4; ++m) _Pragma("unroll") for (int n = 0; n < 2; ++n) _Pragma("unroll") for (int k = 0; k < 2; ++k) \
;         acc[ai][bj][m][n] = __builtin_amdgcn_mfma_f32_16x16x32_bf16(Bt[n][k], At[m][k], acc[ai][bj][m][n], 0, 0, 0); __builtin_amdgcn_s_setprio(0); } while (0)
; #define PG8_WAIT_V(n) asm volatile("s_waitcnt vmcnt(" #n ")" ::: "memory")
; #define PG8_WAIT_L(n) asm volatile("s_waitcnt lgkmcnt(" #n ")" ::: "memory")
; #define PG8_BAR __builtin_amdgcn_s_barrier()
; #define PG8_SCHED __builtin_amdgcn_sched_barrier(0)
; template <class Epi, class Sched, bool ALIGN_EPI = false, bool SP2 = false>
; __device__ __forceinline__ void gemm_phase(PG8_LAS unsigned char* lds, const Gemm g, const Sched& S, const Epi& E) {
;     ...
;             PG8_WAIT_V(8); PG8_WAIT_L(0); PG8_BAR; PG8_MMA(1, 0, At, B0); PG8_MMA(1, 1, At, B1); PG8_BAR; PG8_SCHED;
;             PG8_LDB(B0, 1, 0); PG8_LDB(B1, 1, 1); PG8_SCHED; PG8_LDA(At, 1, 0); PG8_STAGE(PG8_SA(0, 1), a2 + hstep, voffA);
;             PG8_WAIT_V(8); PG8_WAIT_L(0); PG8_BAR; PG8_MMA(0, 0, At, B0); PG8_MMA(0, 1, At, B1); PG8_BAR; PG8_SCHED;
	s_setprio 1
	s_waitcnt lgkmcnt(0)
	v_mfma_f32_16x16x32_bf16 v[60:63], v[128:131], v[176:179], 0
	v_mfma_f32_16x16x32_bf16 v[56:59], v[152:155], v[176:179], 0
	v_mfma_f32_16x16x32_bf16 v[44:47], v[128:131], v[184:187], 0
	v_mfma_f32_16x16x32_bf16 v[40:43], v[152:155], v[184:187], 0
	v_mfma_f32_16x16x32_bf16 v[28:31], v[128:131], v[192:195], 0
	v_mfma_f32_16x16x32_bf16 v[24:27], v[152:155], v[192:195], 0
	v_mfma_f32_16x16x32_bf16 v[12:15], v[128:131], v[212:215], 0
	v_mfma_f32_16x16x32_bf16 v[8:11], v[152:155], v[212:215], 0
	v_mfma_f32_16x16x32_bf16 v[60:63], v[132:135], v[180:183], v[60:63]
	v_mfma_f32_16x16x32_bf16 v[56:59], v[156:159], v[180:183], v[56:59]
	v_mfma_f32_16x16x32_bf16 v[44:47], v[132:135], v[188:191], v[44:47]
	v_mfma_f32_16x16x32_bf16 v[40:43], v[156:159], v[188:191], v[40:43]
	v_mfma_f32_16x16x32_bf16 v[28:31], v[132:135], v[208:211], v[28:31]
	v_mfma_f32_16x16x32_bf16 v[24:27], v[156:159], v[208:211], v[24:27]
	v_mfma_f32_16x16x32_bf16 v[12:15], v[132:135], v[216:219], v[12:15]
	v_mfma_f32_16x16x32_bf16 v[8:11], v[156:159], v[216:219], v[8:11]
	v_mfma_f32_16x16x32_bf16 v[52:55], v[160:163], v[176:179], 0
	v_mfma_f32_16x16x32_bf16 v[48:51], v[168:171], v[176:179], 0
	v_mfma_f32_16x16x32_bf16 v[36:39], v[160:163], v[184:187], 0
	v_mfma_f32_16x16x32_bf16 v[32:35], v[168:171], v[184:187], 0
	v_mfma_f32_16x16x32_bf16 v[20:23], v[160:163], v[192:195], 0
	v_mfma_f32_16x16x32_bf16 v[16:19], v[168:171], v[192:195], 0
	v_mfma_f32_16x16x32_bf16 v[4:7], v[160:163], v[212:215], 0
	v_mfma_f32_16x16x32_bf16 v[0:3], v[168:171], v[212:215], 0
	v_mfma_f32_16x16x32_bf16 v[52:55], v[164:167], v[180:183], v[52:55]
	v_mfma_f32_16x16x32_bf16 v[48:51], v[172:175], v[180:183], v[48:51]
	v_mfma_f32_16x16x32_bf16 v[36:39], v[164:167], v[188:191], v[36:39]
	v_mfma_f32_16x16x32_bf16 v[32:35], v[172:175], v[188:191], v[32:35]
	v_mfma_f32_16x16x32_bf16 v[20:23], v[164:167], v[208:211], v[20:23]
	v_mfma_f32_16x16x32_bf16 v[16:19], v[172:175], v[208:211], v[16:19]
	v_mfma_f32_16x16x32_bf16 v[4:7], v[164:167], v[216:219], v[4:7]
	v_mfma_f32_16x16x32_bf16 v[0:3], v[172:175], v[216:219], v[0:3]
	s_setprio 0
	s_barrier
	s_add_i32 s17, 0, 0x18000
	s_add_i32 s19, 0, 0x1c000
	v_add_u32_e32 v156, s17, v197
	v_add_u32_e32 v172, s19, v197
	ds_read_b128 v[128:131], v156
	ds_read_b128 v[132:135], v156 offset:1024
	ds_read_b128 v[152:155], v156 offset:2048
	ds_read_b128 v[156:159], v156 offset:3072
	ds_read_b128 v[160:163], v172
	ds_read_b128 v[164:167], v172 offset:1024
	ds_read_b128 v[168:171], v172 offset:2048
	ds_read_b128 v[172:175], v172 offset:3072
	s_add_u32 s8, s8, 0xb0000
	s_addc_u32 s9, s9, 0
	s_mov_b32 m0, s23
	v_lshl_add_u64 v[228:229], s[8:9], 0, v[136:137]
	ds_read_b128 v[176:179], v201 offset:32768
	ds_read_b128 v[180:183], v201 offset:33792
	ds_read_b128 v[184:187], v201 offset:34816
	ds_read_b128 v[188:191], v201 offset:35840
	ds_read_b128 v[192:195], v201 offset:36864
	ds_read_b128 v[208:211], v201 offset:37888
	ds_read_b128 v[212:215], v201 offset:38912
	ds_read_b128 v[216:219], v201 offset:39936
	global_load_lds_dwordx4 v[228:229], off
	v_lshl_add_u64 v[228:229], s[8:9], 0, v[140:141]
	s_mov_b32 m0, s33
	s_nop 0
	global_load_lds_dwordx4 v[228:229], off
	s_waitcnt vmcnt(8)
	s_waitcnt lgkmcnt(0)
	s_barrier
	s_setprio 1
	s_waitcnt lgkmcnt(0)
	v_mfma_f32_16x16x32_bf16 v[124:127], v[128:131], v[176:179], v[124:127]
	v_mfma_f32_16x16x32_bf16 v[120:123], v[152:155], v[176:179], v[120:123]
	v_mfma_f32_16x16x32_bf16 v[108:111], v[128:131], v[184:187], v[108:111]
	v_mfma_f32_16x16x32_bf16 v[104:107], v[152:155], v[184:187], v[104:107]
	v_mfma_f32_16x16x32_bf16 v[92:95], v[128:131], v[192:195], v[92:95]
	v_mfma_f32_16x16x32_bf16 v[88:91], v[152:155], v[192:195], v[88:91]
	v_mfma_f32_16x16x32_bf16 v[76:79], v[128:131], v[212:215], v[76:79]
	v_mfma_f32_16x16x32_bf16 v[72:75], v[152:155], v[212:215], v[72:75]
	v_mfma_f32_16x16x32_bf16 v[124:127], v[132:135], v[180:183], v[124:127]
	v_mfma_f32_16x16x32_bf16 v[120:123], v[156:159], v[180:183], v[120:123]
	v_mfma_f32_16x16x32_bf16 v[108:111], v[132:135], v[188:191], v[108:111]
	v_mfma_f32_16x16x32_bf16 v[104:107], v[156:159], v[188:191], v[104:107]
	v_mfma_f32_16x16x32_bf16 v[92:95], v[132:135], v[208:211], v[92:95]
	v_mfma_f32_16x16x32_bf16 v[88:91], v[156:159], v[208:211], v[88:91]
	v_mfma_f32_16x16x32_bf16 v[76:79], v[132:135], v[216:219], v[76:79]
	v_mfma_f32_16x16x32_bf16 v[72:75], v[156:159], v[216:219], v[72:75]
	v_mfma_f32_16x16x32_bf16 v[116:119], v[160:163], v[176:179], v[116:119]
	v_mfma_f32_16x16x32_bf16 v[112:115], v[168:171], v[176:179], v[112:115]
	v_mfma_f32_16x16x32_bf16 v[100:103], v[160:163], v[184:187], v[100:103]
	v_mfma_f32_16x16x32_bf16 v[96:99], v[168:171], v[184:187], v[96:99]
	v_mfma_f32_16x16x32_bf16 v[84:87], v[160:163], v[192:195], v[84:87]
	v_mfma_f32_16x16x32_bf16 v[80:83], v[168:171], v[192:195], v[80:83]
	v_mfma_f32_16x16x32_bf16 v[68:71], v[160:163], v[212:215], v[68:71]
	v_mfma_f32_16x16x32_bf16 v[64:67], v[168:171], v[212:215], v[64:67]
	v_mfma_f32_16x16x32_bf16 v[116:119], v[164:167], v[180:183], v[116:119]
	v_mfma_f32_16x16x32_bf16 v[112:115], v[172:175], v[180:183], v[112:115]
	v_mfma_f32_16x16x32_bf16 v[100:103], v[164:167], v[188:191], v[100:103]
	v_mfma_f32_16x16x32_bf16 v[96:99], v[172:175], v[188:191], v[96:99]
	v_mfma_f32_16x16x32_bf16 v[84:87], v[164:167], v[208:211], v[84:87]
	v_mfma_f32_16x16x32_bf16 v[80:83], v[172:175], v[208:211], v[80:83]
	v_mfma_f32_16x16x32_bf16 v[68:71], v[164:167], v[216:219], v[68:71]
	v_mfma_f32_16x16x32_bf16 v[64:67], v[172:175], v[216:219], v[64:67]
	s_setprio 0
	s_barrier
; #define PG8_STAGE(bufoff, gbase, voff) do { _Pragma("unroll") for (int _i = 0; _i < 2; ++_i) \
;         __builtin_amdgcn_global_load_lds((const unsigned*)((const char*)(gbase) + (voff)[_i]), (PG8_LAS unsigned*)(lds + (bufoff) + ldsw + _i * 8192), 16, 0, 0); } while (0)
; #define PG8_LDA(dst, b, h) do { _Pragma("unroll") for (int m = 0; m < 4; ++m) _Pragma("unroll") for (int k = 0; k < 2; ++k) dst[m][k] = *(const PG8_LAS bf16x8*)(lds + PG8_SA(b, h) + aoff + m * 2048 + k * 1024); } while (0)
; #define PG8_LDB(dst, b, h) do { _Pragma("unroll") for (int n = 0; n < 2; ++n) _Pragma("unroll") for (int k = 0; k < 2; ++k) dst[n][k] = *(const PG8_LAS bf16x8*)(lds + PG8_SB(b, h) + boff + n * 2048 + k * 1024); } while (0)
; #define PG8_MMA(ai, bj, At, Bt) do { __builtin_amdgcn_s_setprio(1); _Pragma("unroll") for (int m = 0; m < 4; ++m) _Pragma("unroll") for (int n = 0; n < 2; ++n) _Pragma("unroll") for (int k = 0; k < 2; ++k) \
;         acc[ai][bj][m][n] = __builtin_amdgcn_mfma_f32_16x16x32_bf16(Bt[n][k], At[m][k], acc[ai][bj][m][n], 0, 0, 0); __builtin_amdgcn_s_setprio(0); } while (0)
; #define PG8_WAIT_V(n) asm volatile("s_waitcnt vmcnt(" #n ")" ::: "memory")
; template <class Epi, class Sched, bool ALIGN_EPI = false, bool SP2 = false>
; __device__ __forceinline__ void gemm_phase(PG8_LAS unsigned char* lds, const Gemm g, const Sched& S, const Epi& E) {
;     ...
;             PG8_LDB(B0, 0, 0); PG8_LDB(B1, 0, 1); PG8_SCHED; PG8_LDA(At, 0, 0); PG8_STAGE(PG8_SA(1, 1), a1 + hstep, voffA);
;             PG8_WAIT_V(8); PG8_WAIT_L(0); PG8_BAR; PG8_MMA(0, 0, At, B0); PG8_MMA(0, 1, At, B1); PG8_BAR; PG8_SCHED;
;             PG8_LDA(At, 0, 1); PG8_STAGE(PG8_SB(0, 0), b2, voffB); PG8_STAGE(PG8_SB(0, 1), b2 + hstep, voffB); PG8_STAGE(PG8_SA(0, 0), a2, voffA);
;             PG8_WAIT_V(8); PG8_WAIT_L(0); PG8_BAR; PG8_MMA(1, 0, At, B0); PG8_MMA(1, 1, At, B1); PG8_BAR; PG8_SCHED;
;             PG8_LDB(B0, 1, 0); PG8_LDB(B1, 1, 1); PG8_SCHED; PG8_LDA(At, 1, 0); PG8_STAGE(PG8_SA(0, 1), a2 + hstep, voffA);
;             PG8_WAIT_V(8); PG8_WAIT_L(0); PG8_BAR; PG8_MMA(0, 0, At, B0); PG8_MMA(0, 1, At, B1); PG8_BAR; PG8_SCHED;
;             PG8_LDA(At, 1, 1); PG8_STAGE(PG8_SB(1, 0), b3, voffB); PG8_STAGE(PG8_SB(1, 1), b3 + hstep, voffB); PG8_STAGE(PG8_SA(1, 0), a3, voffA);
;             PG8_WAIT_V(8); PG8_WAIT_L(0); PG8_BAR; PG8_MMA(1, 0, At, B0); PG8_MMA(1, 1, At, B1); PG8_BAR; PG8_SCHED;
	s_add_i32 s8, s17, s14
	v_lshl_add_u64 v[220:221], v[220:221], 0, s[52:53]
	s_mov_b32 m0, s8
	ds_read_b128 v[176:179], v201 offset:49152
	ds_read_b128 v[180:183], v201 offset:50176
	ds_read_b128 v[184:187], v201 offset:51200
	ds_read_b128 v[188:191], v201 offset:52224
	ds_read_b128 v[192:195], v201 offset:53248
	ds_read_b128 v[208:211], v201 offset:54272
	ds_read_b128 v[212:215], v201 offset:55296
	ds_read_b128 v[216:219], v201 offset:56320
	global_load_lds_dwordx4 v[220:221], off
	s_add_i32 m0, s8, 0x2000
	s_add_u32 s6, s6, 0xb0080
	v_lshl_add_u64 v[220:221], v[222:223], 0, s[52:53]
	s_addc_u32 s7, s7, 0
	s_add_i32 s8, s19, s14
	global_load_lds_dwordx4 v[220:221], off
	v_lshl_add_u64 v[220:221], s[6:7], 0, v[138:139]
	s_mov_b32 m0, s8
	s_nop 0
	global_load_lds_dwordx4 v[220:221], off
	v_lshl_add_u64 v[220:221], s[6:7], 0, v[142:143]
	s_add_i32 m0, s8, 0x2000
	s_nop 0
	global_load_lds_dwordx4 v[220:221], off
	v_lshl_add_u64 v[220:221], v[224:225], 0, s[52:53]
	s_mov_b32 m0, s35
	s_nop 0
	global_load_lds_dwordx4 v[220:221], off
	v_lshl_add_u64 v[220:221], v[226:227], 0, s[52:53]
	s_mov_b32 m0, s62
	s_nop 0
	global_load_lds_dwordx4 v[220:221], off
	s_waitcnt vmcnt(8)
	s_waitcnt lgkmcnt(0)
	s_barrier
	s_setprio 1
	s_waitcnt lgkmcnt(0)
	v_mfma_f32_16x16x32_bf16 v[60:63], v[128:131], v[176:179], v[60:63]
	v_mfma_f32_16x16x32_bf16 v[56:59], v[152:155], v[176:179], v[56:59]
	v_mfma_f32_16x16x32_bf16 v[44:47], v[128:131], v[184:187], v[44:47]
	v_mfma_f32_16x16x32_bf16 v[40:43], v[152:155], v[184:187], v[40:43]
	v_mfma_f32_16x16x32_bf16 v[28:31], v[128:131], v[192:195], v[28:31]
	v_mfma_f32_16x16x32_bf16 v[24:27], v[152:155], v[192:195], v[24:27]
	v_mfma_f32_16x16x32_bf16 v[12:15], v[128:131], v[212:215], v[12:15]
	v_mfma_f32_16x16x32_bf16 v[8:11], v[152:155], v[212:215], v[8:11]
	v_mfma_f32_16x16x32_bf16 v[60:63], v[132:135], v[180:183], v[60:63]
	v_mfma_f32_16x16x32_bf16 v[56:59], v[156:159], v[180:183], v[56:59]
	v_mfma_f32_16x16x32_bf16 v[44:47], v[132:135], v[188:191], v[44:47]
	v_mfma_f32_16x16x32_bf16 v[40:43], v[156:159], v[188:191], v[40:43]
	v_mfma_f32_16x16x32_bf16 v[28:31], v[132:135], v[208:211], v[28:31]
	v_mfma_f32_16x16x32_bf16 v[24:27], v[156:159], v[208:211], v[24:27]
	v_mfma_f32_16x16x32_bf16 v[12:15], v[132:135], v[216:219], v[12:15]
	v_mfma_f32_16x16x32_bf16 v[8:11], v[156:159], v[216:219], v[8:11]
	v_mfma_f32_16x16x32_bf16 v[52:55], v[160:163], v[176:179], v[52:55]
	v_mfma_f32_16x16x32_bf16 v[48:51], v[168:171], v[176:179], v[48:51]
	v_mfma_f32_16x16x32_bf16 v[36:39], v[160:163], v[184:187], v[36:39]
	v_mfma_f32_16x16x32_bf16 v[32:35], v[168:171], v[184:187], v[32:35]
	v_mfma_f32_16x16x32_bf16 v[20:23], v[160:163], v[192:195], v[20:23]
	v_mfma_f32_16x16x32_bf16 v[16:19], v[168:171], v[192:195], v[16:19]
	v_mfma_f32_16x16x32_bf16 v[4:7], v[160:163], v[212:215], v[4:7]
	v_mfma_f32_16x16x32_bf16 v[0:3], v[168:171], v[212:215], v[0:3]
	v_mfma_f32_16x16x32_bf16 v[52:55], v[164:167], v[180:183], v[52:55]
	v_mfma_f32_16x16x32_bf16 v[48:51], v[172:175], v[180:183], v[48:51]
	v_mfma_f32_16x16x32_bf16 v[36:39], v[164:167], v[188:191], v[36:39]
	v_mfma_f32_16x16x32_bf16 v[32:35], v[172:175], v[188:191], v[32:35]
	v_mfma_f32_16x16x32_bf16 v[20:23], v[164:167], v[208:211], v[20:23]
	v_mfma_f32_16x16x32_bf16 v[16:19], v[172:175], v[208:211], v[16:19]
	v_mfma_f32_16x16x32_bf16 v[4:7], v[164:167], v[216:219], v[4:7]
	v_mfma_f32_16x16x32_bf16 v[0:3], v[172:175], v[216:219], v[0:3]
	s_setprio 0
	s_barrier
	s_add_i32 s16, s16, 2
	s_add_u32 s0, s0, 0x100
	s_addc_u32 s1, s1, 0
	s_add_u32 s12, s12, 0x100
	s_addc_u32 s13, s13, 0
	s_cmp_gt_u32 s16, 41
	s_cbranch_scc1 .Lpeel_exit_4
	.p2align	6
.LBB0_683:
	ds_read_b128 v[128:131], v199
	ds_read_b128 v[132:135], v199 offset:1024
	ds_read_b128 v[152:155], v199 offset:2048
	ds_read_b128 v[156:159], v199 offset:3072
	ds_read_b128 v[160:163], v200
	ds_read_b128 v[164:167], v200 offset:1024
	ds_read_b128 v[168:171], v200 offset:2048
	ds_read_b128 v[172:175], v200 offset:3072
	s_add_u32 s6, s0, 0xfff50080
	s_addc_u32 s7, s1, -1
	s_cmp_eq_u32 s16, 40
	s_cselect_b32 s9, s59, s7
	s_cselect_b32 s8, s58, s6
	s_cselect_b32 s7, s61, s13
	s_cselect_b32 s6, s60, s12
	v_lshl_add_u64 v[220:221], s[0:1], 0, v[144:145]
	s_add_i32 m0, s15, 0xc000
	ds_read_b128 v[176:179], v201
	ds_read_b128 v[180:183], v201 offset:1024
	ds_read_b128 v[184:187], v201 offset:2048
	ds_read_b128 v[188:191], v201 offset:3072
	ds_read_b128 v[192:195], v201 offset:4096
	ds_read_b128 v[208:211], v201 offset:5120
	ds_read_b128 v[212:215], v201 offset:6144
	ds_read_b128 v[216:219], v201 offset:7168
	global_load_lds_dwordx4 v[220:221], off
	v_lshl_add_u64 v[220:221], s[0:1], 0, v[146:147]
	s_add_i32 m0, s15, 0xe000
	s_nop 0
	global_load_lds_dwordx4 v[220:221], off
	s_waitcnt vmcnt(8)
	s_waitcnt lgkmcnt(0)
	s_barrier
; #define PG8_STAGE(bufoff, gbase, voff) do { _Pragma("unroll") for (int _i = 0; _i < 2; ++_i) \
;         __builtin_amdgcn_global_load_lds((const unsigned*)((const char*)(gbase) + (voff)[_i]), (PG8_LAS unsigned*)(lds + (bufoff) + ldsw + _i * 8192), 16, 0, 0); } while (0)
; #define PG8_LDA(dst, b, h) do { _Pragma("unroll") for (int m = 0; m < 4; ++m) _Pragma("unroll") for (int k = 0; k < 2; ++k) dst[m][k] = *(const PG8_LAS bf16x8*)(lds + PG8_SA(b, h) + aoff + m * 2048 + k * 1024); } while (0)
; #define PG8_LDB(dst, b, h) do { _Pragma("unroll") for (int n = 0; n < 2; ++n) _Pragma("unroll") for (int k = 0; k < 2; ++k) dst[n][k] = *(const PG8_LAS bf16x8*)(lds + PG8_SB(b, h) + boff + n * 2048 + k * 1024); } while (0)
; #define PG8_MMA(ai, bj, At, Bt) do { __builtin_amdgcn_s_setprio(1); _Pragma("unroll") for (int m = 0; m < 4; ++m) _Pragma("unroll") for (int n = 0; n < 2; ++n) _Pragma("unroll") for (int k = 0; k < 2; ++k) \
;         acc[ai][bj][m][n] = __builtin_amdgcn_mfma_f32_16x16x32_bf16(Bt[n][k], At[m][k], acc[ai][bj][m][n], 0, 0, 0); __builtin_amdgcn_s_setprio(0); } while (0)
; #define PG8_WAIT_V(n) asm volatile("s_waitcnt vmcnt(" #n ")" ::: "memory")
; #define PG8_WAIT_L(n) asm volatile("s_waitcnt lgkmcnt(" #n ")" ::: "memory")
; #define PG8_BAR __builtin_amdgcn_s_barrier()
; #define PG8_SCHED __builtin_amdgcn_sched_barrier(0)
; template <class Epi, class Sched, bool ALIGN_EPI = false, bool SP2 = false>
; __device__ __forceinline__ void gemm_phase(PG8_LAS unsigned char* lds, const Gemm g, const Sched& S, const Epi& E) {
;     ...
;             PG8_LDB(B0, 0, 0); PG8_LDB(B1, 0, 1); PG8_SCHED; PG8_LDA(At, 0, 0); PG8_STAGE(PG8_SA(1, 1), a1 + hstep, voffA);
;             PG8_WAIT_V(8); PG8_WAIT_L(0); PG8_BAR; PG8_MMA(0, 0, At, B0); PG8_MMA(0, 1, At, B1); PG8_BAR; PG8_SCHED;
;             PG8_LDA(At, 0, 1); PG8_STAGE(PG8_SB(0, 0), b2, voffB); PG8_STAGE(PG8_SB(0, 1), b2 + hstep, voffB); PG8_STAGE(PG8_SA(0, 0), a2, voffA);
;             PG8_WAIT_V(8); PG8_WAIT_L(0); PG8_BAR; PG8_MMA(1, 0, At, B0); PG8_MMA(1, 1, At, B1); PG8_BAR; PG8_SCHED;
	s_setprio 1
	s_waitcnt lgkmcnt(0)
	v_mfma_f32_16x16x32_bf16 v[124:127], v[128:131], v[176:179], v[124:127]
	v_mfma_f32_16x16x32_bf16 v[120:123], v[152:155], v[176:179], v[120:123]
	v_mfma_f32_16x16x32_bf16 v[108:111], v[128:131], v[184:187], v[108:111]
	v_mfma_f32_16x16x32_bf16 v[104:107], v[152:155], v[184:187], v[104:107]
	v_mfma_f32_16x16x32_bf16 v[92:95], v[128:131], v[192:195], v[92:95]
	v_mfma_f32_16x16x32_bf16 v[88:91], v[152:155], v[192:195], v[88:91]
	v_mfma_f32_16x16x32_bf16 v[76:79], v[128:131], v[212:215], v[76:79]
	v_mfma_f32_16x16x32_bf16 v[72:75], v[152:155], v[212:215], v[72:75]
	v_mfma_f32_16x16x32_bf16 v[124:127], v[132:135], v[180:183], v[124:127]
	v_mfma_f32_16x16x32_bf16 v[120:123], v[156:159], v[180:183], v[120:123]
	v_mfma_f32_16x16x32_bf16 v[108:111], v[132:135], v[188:191], v[108:111]
	v_mfma_f32_16x16x32_bf16 v[104:107], v[156:159], v[188:191], v[104:107]
	v_mfma_f32_16x16x32_bf16 v[92:95], v[132:135], v[208:211], v[92:95]
	v_mfma_f32_16x16x32_bf16 v[88:91], v[156:159], v[208:211], v[88:91]
	v_mfma_f32_16x16x32_bf16 v[76:79], v[132:135], v[216:219], v[76:79]
	v_mfma_f32_16x16x32_bf16 v[72:75], v[156:159], v[216:219], v[72:75]
	v_mfma_f32_16x16x32_bf16 v[116:119], v[160:163], v[176:179], v[116:119]
	v_mfma_f32_16x16x32_bf16 v[112:115], v[168:171], v[176:179], v[112:115]
	v_mfma_f32_16x16x32_bf16 v[100:103], v[160:163], v[184:187], v[100:103]
	v_mfma_f32_16x16x32_bf16 v[96:99], v[168:171], v[184:187], v[96:99]
	v_mfma_f32_16x16x32_bf16 v[84:87], v[160:163], v[192:195], v[84:87]
	v_mfma_f32_16x16x32_bf16 v[80:83], v[168:171], v[192:195], v[80:83]
	v_mfma_f32_16x16x32_bf16 v[68:71], v[160:163], v[212:215], v[68:71]
	v_mfma_f32_16x16x32_bf16 v[64:67], v[168:171], v[212:215], v[64:67]
	v_mfma_f32_16x16x32_bf16 v[116:119], v[164:167], v[180:183], v[116:119]
	v_mfma_f32_16x16x32_bf16 v[112:115], v[172:175], v[180:183], v[112:115]
	v_mfma_f32_16x16x32_bf16 v[100:103], v[164:167], v[188:191], v[100:103]
	v_mfma_f32_16x16x32_bf16 v[96:99], v[172:175], v[188:191], v[96:99]
	v_mfma_f32_16x16x32_bf16 v[84:87], v[164:167], v[208:211], v[84:87]
	v_mfma_f32_16x16x32_bf16 v[80:83], v[172:175], v[208:211], v[80:83]
	v_mfma_f32_16x16x32_bf16 v[68:71], v[164:167], v[216:219], v[68:71]
	v_mfma_f32_16x16x32_bf16 v[64:67], v[172:175], v[216:219], v[64:67]
	s_setprio 0
	s_barrier
	s_add_i32 s17, s64, s14
	v_lshl_add_u64 v[220:221], s[6:7], 0, v[138:139]
	s_mov_b32 m0, s17
	ds_read_b128 v[176:179], v201 offset:16384
	ds_read_b128 v[180:183], v201 offset:17408
	ds_read_b128 v[184:187], v201 offset:18432
	ds_read_b128 v[188:191], v201 offset:19456
	ds_read_b128 v[192:195], v201 offset:20480
	ds_read_b128 v[208:211], v201 offset:21504
	ds_read_b128 v[212:215], v201 offset:22528
	ds_read_b128 v[216:219], v201 offset:23552
	global_load_lds_dwordx4 v[220:221], off
	s_add_i32 m0, s17, 0x2000
	s_add_u32 s20, s6, 0xb0000
	v_lshl_add_u64 v[222:223], s[6:7], 0, v[142:143]
	s_addc_u32 s21, s7, 0
	s_add_i32 s17, s65, s14
	global_load_lds_dwordx4 v[222:223], off
	v_lshl_add_u64 v[224:225], s[20:21], 0, v[138:139]
	s_mov_b32 m0, s17
	v_lshl_add_u64 v[226:227], s[8:9], 0, v[140:141]
	global_load_lds_dwordx4 v[224:225], off
	v_lshl_add_u64 v[224:225], s[20:21], 0, v[142:143]
	s_add_i32 m0, s17, 0x2000
	s_nop 0
	global_load_lds_dwordx4 v[224:225], off
	v_lshl_add_u64 v[224:225], s[8:9], 0, v[136:137]
	s_mov_b32 m0, s15
	s_nop 0
	global_load_lds_dwordx4 v[224:225], off
	s_mov_b32 m0, s18
	s_nop 0
	global_load_lds_dwordx4 v[226:227], off
	s_waitcnt vmcnt(8)
	s_waitcnt lgkmcnt(0)
	s_barrier
	s_setprio 1
	s_waitcnt lgkmcnt(0)
	v_mfma_f32_16x16x32_bf16 v[60:63], v[128:131], v[176:179], v[60:63]
	v_mfma_f32_16x16x32_bf16 v[56:59], v[152:155], v[176:179], v[56:59]
	v_mfma_f32_16x16x32_bf16 v[44:47], v[128:131], v[184:187], v[44:47]
	v_mfma_f32_16x16x32_bf16 v[40:43], v[152:155], v[184:187], v[40:43]
	v_mfma_f32_16x16x32_bf16 v[28:31], v[128:131], v[192:195], v[28:31]
	v_mfma_f32_16x16x32_bf16 v[24:27], v[152:155], v[192:195], v[24:27]
	v_mfma_f32_16x16x32_bf16 v[12:15], v[128:131], v[212:215], v[12:15]
	v_mfma_f32_16x16x32_bf16 v[8:11], v[152:155], v[212:215], v[8:11]
	v_mfma_f32_16x16x32_bf16 v[60:63], v[132:135], v[180:183], v[60:63]
	v_mfma_f32_16x16x32_bf16 v[56:59], v[156:159], v[180:183], v[56:59]
	v_mfma_f32_16x16x32_bf16 v[44:47], v[132:135], v[188:191], v[44:47]
	v_mfma_f32_16x16x32_bf16 v[40:43], v[156:159], v[188:191], v[40:43]
	v_mfma_f32_16x16x32_bf16 v[28:31], v[132:135], v[208:211], v[28:31]
	v_mfma_f32_16x16x32_bf16 v[24:27], v[156:159], v[208:211], v[24:27]
	v_mfma_f32_16x16x32_bf16 v[12:15], v[132:135], v[216:219], v[12:15]
	v_mfma_f32_16x16x32_bf16 v[8:11], v[156:159], v[216:219], v[8:11]
	v_mfma_f32_16x16x32_bf16 v[52:55], v[160:163], v[176:179], v[52:55]
	v_mfma_f32_16x16x32_bf16 v[48:51], v[168:171], v[176:179], v[48:51]
	v_mfma_f32_16x16x32_bf16 v[36:39], v[160:163], v[184:187], v[36:39]
	v_mfma_f32_16x16x32_bf16 v[32:35], v[168:171], v[184:187], v[32:35]
	v_mfma_f32_16x16x32_bf16 v[20:23], v[160:163], v[192:195], v[20:23]
	v_mfma_f32_16x16x32_bf16 v[16:19], v[168:171], v[192:195], v[16:19]
	v_mfma_f32_16x16x32_bf16 v[4:7], v[160:163], v[212:215], v[4:7]
	v_mfma_f32_16x16x32_bf16 v[0:3], v[168:171], v[212:215], v[0:3]
	v_mfma_f32_16x16x32_bf16 v[52:55], v[164:167], v[180:183], v[52:55]
	v_mfma_f32_16x16x32_bf16 v[48:51], v[172:175], v[180:183], v[48:51]
	v_mfma_f32_16x16x32_bf16 v[36:39], v[164:167], v[188:191], v[36:39]
	v_mfma_f32_16x16x32_bf16 v[32:35], v[172:175], v[188:191], v[32:35]
	v_mfma_f32_16x16x32_bf16 v[20:23], v[164:167], v[208:211], v[20:23]
	v_mfma_f32_16x16x32_bf16 v[16:19], v[172:175], v[208:211], v[16:19]
	v_mfma_f32_16x16x32_bf16 v[4:7], v[164:167], v[216:219], v[4:7]
	v_mfma_f32_16x16x32_bf16 v[0:3], v[172:175], v[216:219], v[0:3]
	s_setprio 0
	s_barrier
; #define PG8_STAGE(bufoff, gbase, voff) do { _Pragma("unroll") for (int _i = 0; _i < 2; ++_i) \
;         __builtin_amdgcn_global_load_lds((const unsigned*)((const char*)(gbase) + (voff)[_i]), (PG8_LAS unsigned*)(lds + (bufoff) + ldsw + _i * 8192), 16, 0, 0); } while (0)
; #define PG8_LDA(dst, b, h) do { _Pragma("unroll") for (int m = 0; m < 4; ++m) _Pragma("unroll") for (int k = 0; k < 2; ++k) dst[m][k] = *(const PG8_LAS bf16x8*)(lds + PG8_SA(b, h) + aoff + m * 2048 + k * 1024); } while (0)
; #define PG8_LDB(dst, b, h) do { _Pragma("unroll") for (int n = 0; n < 2; ++n) _Pragma("unroll") for (int k = 0; k < 2; ++k) dst[n][k] = *(const PG8_LAS bf16x8*)(lds + PG8_SB(b, h) + boff + n * 2048 + k * 1024); } while (0)
; #define PG8_MMA(ai, bj, At, Bt) do { __builtin_amdgcn_s_setprio(1); _Pragma("unroll") for (int m = 0; m < 4; ++m) _Pragma("unroll") for (int n = 0; n < 2; ++n) _Pragma("unroll") for (int k = 0; k < 2; ++k) \
;         acc[ai][bj][m][n] = __builtin_amdgcn_mfma_f32_16x16x32_bf16(Bt[n][k], At[m][k], acc[ai][bj][m][n], 0, 0, 0); __builtin_amdgcn_s_setprio(0); } while (0)
; #define PG8_WAIT_V(n) asm volatile("s_waitcnt vmcnt(" #n ")" ::: "memory")
; #define PG8_WAIT_L(n) asm volatile("s_waitcnt lgkmcnt(" #n ")" ::: "memory")
; #define PG8_BAR __builtin_amdgcn_s_barrier()
; #define PG8_SCHED __builtin_amdgcn_sched_barrier(0)
; template <class Epi, class Sched, bool ALIGN_EPI = false, bool SP2 = false>
; __device__ __forceinline__ void gemm_phase(PG8_LAS unsigned char* lds, const Gemm g, const Sched& S, const Epi& E) {
;     ...
;             PG8_LDB(B0, 1, 0); PG8_LDB(B1, 1, 1); PG8_SCHED; PG8_LDA(At, 1, 0); PG8_STAGE(PG8_SA(0, 1), a2 + hstep, voffA);
;             PG8_WAIT_V(8); PG8_WAIT_L(0); PG8_BAR; PG8_MMA(0, 0, At, B0); PG8_MMA(0, 1, At, B1); PG8_BAR; PG8_SCHED;
	s_add_i32 s17, 0, 0x18000
	s_add_i32 s19, 0, 0x1c000
	v_add_u32_e32 v156, s17, v197
	v_add_u32_e32 v172, s19, v197
	ds_read_b128 v[128:131], v156
	ds_read_b128 v[132:135], v156 offset:1024
	ds_read_b128 v[152:155], v156 offset:2048
	ds_read_b128 v[156:159], v156 offset:3072
	ds_read_b128 v[160:163], v172
	ds_read_b128 v[164:167], v172 offset:1024
	ds_read_b128 v[168:171], v172 offset:2048
	ds_read_b128 v[172:175], v172 offset:3072
	s_add_u32 s8, s8, 0xb0000
	s_addc_u32 s9, s9, 0
	s_mov_b32 m0, s23
	v_lshl_add_u64 v[228:229], s[8:9], 0, v[136:137]
	ds_read_b128 v[176:179], v201 offset:32768
	ds_read_b128 v[180:183], v201 offset:33792
	ds_read_b128 v[184:187], v201 offset:34816
	ds_read_b128 v[188:191], v201 offset:35840
	ds_read_b128 v[192:195], v201 offset:36864
	ds_read_b128 v[208:211], v201 offset:37888
	ds_read_b128 v[212:215], v201 offset:38912
	ds_read_b128 v[216:219], v201 offset:39936
	global_load_lds_dwordx4 v[228:229], off
	v_lshl_add_u64 v[228:229], s[8:9], 0, v[140:141]
	s_mov_b32 m0, s33
	s_nop 0
	global_load_lds_dwordx4 v[228:229], off
	s_waitcnt vmcnt(8)
	s_waitcnt lgkmcnt(0)
	s_barrier
	s_setprio 1
	s_waitcnt lgkmcnt(0)
	v_mfma_f32_16x16x32_bf16 v[124:127], v[128:131], v[176:179], v[124:127]
	v_mfma_f32_16x16x32_bf16 v[120:123], v[152:155], v[176:179], v[120:123]
	v_mfma_f32_16x16x32_bf16 v[108:111], v[128:131], v[184:187], v[108:111]
	v_mfma_f32_16x16x32_bf16 v[104:107], v[152:155], v[184:187], v[104:107]
	v_mfma_f32_16x16x32_bf16 v[92:95], v[128:131], v[192:195], v[92:95]
	v_mfma_f32_16x16x32_bf16 v[88:91], v[152:155], v[192:195], v[88:91]
	v_mfma_f32_16x16x32_bf16 v[76:79], v[128:131], v[212:215], v[76:79]
	v_mfma_f32_16x16x32_bf16 v[72:75], v[152:155], v[212:215], v[72:75]
	v_mfma_f32_16x16x32_bf16 v[124:127], v[132:135], v[180:183], v[124:127]
	v_mfma_f32_16x16x32_bf16 v[120:123], v[156:159], v[180:183], v[120:123]
	v_mfma_f32_16x16x32_bf16 v[108:111], v[132:135], v[188:191], v[108:111]
	v_mfma_f32_16x16x32_bf16 v[104:107], v[156:159], v[188:191], v[104:107]
	v_mfma_f32_16x16x32_bf16 v[92:95], v[132:135], v[208:211], v[92:95]
	v_mfma_f32_16x16x32_bf16 v[88:91], v[156:159], v[208:211], v[88:91]
	v_mfma_f32_16x16x32_bf16 v[76:79], v[132:135], v[216:219], v[76:79]
	v_mfma_f32_16x16x32_bf16 v[72:75], v[156:159], v[216:219], v[72:75]
	v_mfma_f32_16x16x32_bf16 v[116:119], v[160:163], v[176:179], v[116:119]
	v_mfma_f32_16x16x32_bf16 v[112:115], v[168:171], v[176:179], v[112:115]
	v_mfma_f32_16x16x32_bf16 v[100:103], v[160:163], v[184:187], v[100:103]
	v_mfma_f32_16x16x32_bf16 v[96:99], v[168:171], v[184:187], v[96:99]
	v_mfma_f32_16x16x32_bf16 v[84:87], v[160:163], v[192:195], v[84:87]
	v_mfma_f32_16x16x32_bf16 v[80:83], v[168:171], v[192:195], v[80:83]
	v_mfma_f32_16x16x32_bf16 v[68:71], v[160:163], v[212:215], v[68:71]
	v_mfma_f32_16x16x32_bf16 v[64:67], v[168:171], v[212:215], v[64:67]
	v_mfma_f32_16x16x32_bf16 v[116:119], v[164:167], v[180:183], v[116:119]
	v_mfma_f32_16x16x32_bf16 v[112:115], v[172:175], v[180:183], v[112:115]
	v_mfma_f32_16x16x32_bf16 v[100:103], v[164:167], v[188:191], v[100:103]
	v_mfma_f32_16x16x32_bf16 v[96:99], v[172:175], v[188:191], v[96:99]
	v_mfma_f32_16x16x32_bf16 v[84:87], v[164:167], v[208:211], v[84:87]
	v_mfma_f32_16x16x32_bf16 v[80:83], v[172:175], v[208:211], v[80:83]
	v_mfma_f32_16x16x32_bf16 v[68:71], v[164:167], v[216:219], v[68:71]
	v_mfma_f32_16x16x32_bf16 v[64:67], v[172:175], v[216:219], v[64:67]
	s_setprio 0
	s_barrier
; #define PG8_STAGE(bufoff, gbase, voff) do { _Pragma("unroll") for (int _i = 0; _i < 2; ++_i) \
;         __builtin_amdgcn_global_load_lds((const unsigned*)((const char*)(gbase) + (voff)[_i]), (PG8_LAS unsigned*)(lds + (bufoff) + ldsw + _i * 8192), 16, 0, 0); } while (0)
; #define PG8_LDA(dst, b, h) do { _Pragma("unroll") for (int m = 0; m < 4; ++m) _Pragma("unroll") for (int k = 0; k < 2; ++k) dst[m][k] = *(const PG8_LAS bf16x8*)(lds + PG8_SA(b, h) + aoff + m * 2048 + k * 1024); } while (0)
; #define PG8_MMA(ai, bj, At, Bt) do { __builtin_amdgcn_s_setprio(1); _Pragma("unroll") for (int m = 0; m < 4; ++m) _Pragma("unroll") for (int n = 0; n < 2; ++n) _Pragma("unroll") for (int k = 0; k < 2; ++k) \
;         acc[ai][bj][m][n] = __builtin_amdgcn_mfma_f32_16x16x32_bf16(Bt[n][k], At[m][k], acc[ai][bj][m][n], 0, 0, 0); __builtin_amdgcn_s_setprio(0); } while (0)
; #define PG8_WAIT_V(n) asm volatile("s_waitcnt vmcnt(" #n ")" ::: "memory")
; #define PG8_WAIT_L(n) asm volatile("s_waitcnt lgkmcnt(" #n ")" ::: "memory")
; #define PG8_BAR __builtin_amdgcn_s_barrier()
; #define PG8_SCHED __builtin_amdgcn_sched_barrier(0)
; template <class Epi, class Sched, bool ALIGN_EPI = false, bool SP2 = false>
; __device__ __forceinline__ void gemm_phase(PG8_LAS unsigned char* lds, const Gemm g, const Sched& S, const Epi& E) {
;     ...
;             PG8_LDA(At, 1, 1); PG8_STAGE(PG8_SB(1, 0), b3, voffB); PG8_STAGE(PG8_SB(1, 1), b3 + hstep, voffB); PG8_STAGE(PG8_SA(1, 0), a3, voffA);
;             PG8_WAIT_V(8); PG8_WAIT_L(0); PG8_BAR; PG8_MMA(1, 0, At, B0); PG8_MMA(1, 1, At, B1); PG8_BAR; PG8_SCHED;
	s_add_i32 s8, s17, s14
	v_lshl_add_u64 v[220:221], v[220:221], 0, s[52:53]
	s_mov_b32 m0, s8
	ds_read_b128 v[176:179], v201 offset:49152
	ds_read_b128 v[180:183], v201 offset:50176
	ds_read_b128 v[184:187], v201 offset:51200
	ds_read_b128 v[188:191], v201 offset:52224
	ds_read_b128 v[192:195], v201 offset:53248
	ds_read_b128 v[208:211], v201 offset:54272
	ds_read_b128 v[212:215], v201 offset:55296
	ds_read_b128 v[216:219], v201 offset:56320
	global_load_lds_dwordx4 v[220:221], off
	s_add_i32 m0, s8, 0x2000
	s_add_u32 s6, s6, 0xb0080
	v_lshl_add_u64 v[220:221], v[222:223], 0, s[52:53]
	s_addc_u32 s7, s7, 0
	s_add_i32 s8, s19, s14
	global_load_lds_dwordx4 v[220:221], off
	v_lshl_add_u64 v[220:221], s[6:7], 0, v[138:139]
	s_mov_b32 m0, s8
	s_nop 0
	global_load_lds_dwordx4 v[220:221], off
	v_lshl_add_u64 v[220:221], s[6:7], 0, v[142:143]
	s_add_i32 m0, s8, 0x2000
	s_nop 0
	global_load_lds_dwordx4 v[220:221], off
	v_lshl_add_u64 v[220:221], v[224:225], 0, s[52:53]
	s_mov_b32 m0, s35
	s_nop 0
	global_load_lds_dwordx4 v[220:221], off
	v_lshl_add_u64 v[220:221], v[226:227], 0, s[52:53]
	s_mov_b32 m0, s62
	s_nop 0
	global_load_lds_dwordx4 v[220:221], off
	s_waitcnt vmcnt(8)
	s_waitcnt lgkmcnt(0)
	s_barrier
	s_setprio 1
	s_waitcnt lgkmcnt(0)
	v_mfma_f32_16x16x32_bf16 v[60:63], v[128:131], v[176:179], v[60:63]
	v_mfma_f32_16x16x32_bf16 v[56:59], v[152:155], v[176:179], v[56:59]
	v_mfma_f32_16x16x32_bf16 v[44:47], v[128:131], v[184:187], v[44:47]
	v_mfma_f32_16x16x32_bf16 v[40:43], v[152:155], v[184:187], v[40:43]
	v_mfma_f32_16x16x32_bf16 v[28:31], v[128:131], v[192:195], v[28:31]
	v_mfma_f32_16x16x32_bf16 v[24:27], v[152:155], v[192:195], v[24:27]
	v_mfma_f32_16x16x32_bf16 v[12:15], v[128:131], v[212:215], v[12:15]
	v_mfma_f32_16x16x32_bf16 v[8:11], v[152:155], v[212:215], v[8:11]
	v_mfma_f32_16x16x32_bf16 v[60:63], v[132:135], v[180:183], v[60:63]
	v_mfma_f32_16x16x32_bf16 v[56:59], v[156:159], v[180:183], v[56:59]
	v_mfma_f32_16x16x32_bf16 v[44:47], v[132:135], v[188:191], v[44:47]
	v_mfma_f32_16x16x32_bf16 v[40:43], v[156:159], v[188:191], v[40:43]
	v_mfma_f32_16x16x32_bf16 v[28:31], v[132:135], v[208:211], v[28:31]
	v_mfma_f32_16x16x32_bf16 v[24:27], v[156:159], v[208:211], v[24:27]
	v_mfma_f32_16x16x32_bf16 v[12:15], v[132:135], v[216:219], v[12:15]
	v_mfma_f32_16x16x32_bf16 v[8:11], v[156:159], v[216:219], v[8:11]
	v_mfma_f32_16x16x32_bf16 v[52:55], v[160:163], v[176:179], v[52:55]
	v_mfma_f32_16x16x32_bf16 v[48:51], v[168:171], v[176:179], v[48:51]
	v_mfma_f32_16x16x32_bf16 v[36:39], v[160:163], v[184:187], v[36:39]
	v_mfma_f32_16x16x32_bf16 v[32:35], v[168:171], v[184:187], v[32:35]
	v_mfma_f32_16x16x32_bf16 v[20:23], v[160:163], v[192:195], v[20:23]
	v_mfma_f32_16x16x32_bf16 v[16:19], v[168:171], v[192:195], v[16:19]
	v_mfma_f32_16x16x32_bf16 v[4:7], v[160:163], v[212:215], v[4:7]
	v_mfma_f32_16x16x32_bf16 v[0:3], v[168:171], v[212:215], v[0:3]
	v_mfma_f32_16x16x32_bf16 v[52:55], v[164:167], v[180:183], v[52:55]
	v_mfma_f32_16x16x32_bf16 v[48:51], v[172:175], v[180:183], v[48:51]
	v_mfma_f32_16x16x32_bf16 v[36:39], v[164:167], v[188:191], v[36:39]
	v_mfma_f32_16x16x32_bf16 v[32:35], v[172:175], v[188:191], v[32:35]
	v_mfma_f32_16x16x32_bf16 v[20:23], v[164:167], v[208:211], v[20:23]
	v_mfma_f32_16x16x32_bf16 v[16:19], v[172:175], v[208:211], v[16:19]
	v_mfma_f32_16x16x32_bf16 v[4:7], v[164:167], v[216:219], v[4:7]
	v_mfma_f32_16x16x32_bf16 v[0:3], v[172:175], v[216:219], v[0:3]
	s_setprio 0
	s_barrier
	s_add_i32 s16, s16, 2
	s_add_u32 s0, s0, 0x100
	s_addc_u32 s1, s1, 0
	s_add_u32 s12, s12, 0x100
	s_addc_u32 s13, s13, 0
	s_cmp_gt_u32 s16, 41
	s_cbranch_scc0 .LBB0_683
